# in-proj GEMM epilogue: each wave owns 64 contiguous output columns (LDS B-fragment read remap) and lane pairs exchange pieces so every P store writes 8 whole 128-B lines instead of 16 half lines
# speedup vs baseline: 1.0240x; 1.0074x over previous
.LBB0_315:
	s_add_u32 s56, s70, 0x9100000
	s_addc_u32 s57, s71, 0
	s_add_u32 s72, s70, 0x31500000
	s_addc_u32 s73, s71, 0
	s_and_b32 s63, s2, 3
	s_add_i32 m0, s53, 0x18000
	v_lshl_add_u64 v[6:7], v[6:7], 0, s[30:31]
	s_lshl_b32 s2, s3, 13
	s_lshl_b32 s8, s63, 13
	s_waitcnt vmcnt(2)
	s_barrier
	global_load_lds_dwordx4 v[6:7], off
	v_lshl_add_u64 v[4:5], v[4:5], 0, s[30:31]
	s_add_i32 m0, s53, 0x1a000
	s_add_i32 s59, s53, 0x8000
	s_add_i32 s58, s53, 0xa000
	global_load_lds_dwordx4 v[4:5], off
	v_lshl_add_u64 v[0:1], v[0:1], 0, s[30:31]
	s_mov_b32 m0, s59
	s_add_u32 s4, s18, 0x80080
	global_load_lds_dwordx4 v[0:1], off
	v_lshl_add_u64 v[0:1], v[2:3], 0, s[30:31]
	s_mov_b32 m0, s58
	s_addc_u32 s5, s19, 0
	global_load_lds_dwordx4 v[0:1], off
	s_add_i32 m0, s53, 0x1c000
	v_lshl_add_u64 v[0:1], s[4:5], 0, v[132:133]
	global_load_lds_dwordx4 v[0:1], off
	v_lshl_add_u64 v[0:1], s[4:5], 0, v[136:137]
	s_add_i32 m0, s53, 0x1e000
	s_cmpk_lt_u32 s0, 0x100
	global_load_lds_dwordx4 v[0:1], off
	v_bfe_u32 v1, v190, 4, 2
	v_and_b32_e32 v0, 15, v190
	v_lshlrev_b32_e32 v3, 4, v1
	v_lshl_or_b32 v164, s3, 6, v0
	v_and_b32_e32 v164, -2, v164
	v_lshl_or_b32 v0, v0, 6, v3
	v_lshlrev_b32_e32 v3, 2, v190
	v_and_b32_e32 v3, 32, v3
	v_lshlrev_b32_e32 v64, 5, v1
	v_lshlrev_b32_e32 v2, 3, v1
	v_bitop3_b32 v4, v0, s2, v3 bitop3:0xde
	v_bitop3_b32 v165, s8, v0, v3 bitop3:0xf6
	v_cmp_eq_u32_e64 s[76:77], 0, v1
	v_lshl_add_u64 v[0:1], s[70:71], 0, v[64:65]
	s_mov_b64 s[2:3], 0x31300000
	v_lshl_add_u64 v[138:139], v[0:1], 0, s[2:3]
	v_and_b32_e32 v1, 64, v185
	v_xor_b32_e32 v0, 16, v185
	v_add_u32_e32 v1, 64, v1
	v_cmp_lt_i32_e32 vcc, v0, v1
	s_waitcnt vmcnt(6)
	s_cselect_b64 s[74:75], -1, 0
	s_cmp_eq_u32 s63, 0
	v_cndmask_b32_e32 v0, v185, v0, vcc
	v_lshlrev_b32_e32 v166, 2, v0
	v_xor_b32_e32 v0, 32, v185
	v_cmp_lt_i32_e32 vcc, v0, v1
	v_and_b32_e32 v1, 1, v8
	s_mov_b32 s22, 0
	v_cndmask_b32_e32 v0, v185, v0, vcc
	v_lshlrev_b32_e32 v167, 2, v0
	v_lshlrev_b32_e32 v0, 15, v8
	v_and_b32_e32 v0, 0xffff0000, v0
	v_lshl_add_u32 v0, v9, 12, v0
	v_lshl_or_b32 v0, v1, 6, v0
	v_lshl_add_u32 v140, v10, 1, v0
	v_lshlrev_b32_e32 v0, 15, v11
	v_and_b32_e32 v0, 0xffff0000, v0
	v_lshl_add_u32 v0, v12, 12, v0
	v_and_b32_e32 v1, 1, v11
	v_lshl_or_b32 v0, v1, 6, v0
	s_cselect_b64 s[78:79], -1, 0
	s_ashr_i32 s23, s42, 31
	s_ashr_i32 s62, s34, 31
	v_lshl_or_b32 v168, s63, 6, v2
	v_and_b32_e32 v244, 1, v190
	v_lshl_or_b32 v168, v244, 5, v168
	v_mov_b32_e32 v141, v65
	v_lshl_add_u32 v142, v13, 1, v0
	v_mov_b32_e32 v143, v65
	v_add_u32_e32 v169, 0, v4
	s_mov_b32 s98, 0xaaaaaaaa
	s_mov_b32 s99, 0xaaaaaaaa
	s_mov_b32 s100, 0xa080
	s_mov_b32 s101, 0
	s_barrier
	s_branch .LBB0_326

.LBB0_329:
	s_add_u32 s18, s16, 0xfff80080
	s_addc_u32 s19, s17, -1
	s_add_i32 s27, 0, 0x10000
	s_cmp_eq_u32 s26, 28
	s_cselect_b32 s21, s0, s19
	s_cselect_b32 s20, s2, s18
	v_add_u32_e32 v64, s27, v165
	s_cselect_b32 s19, s3, s11
	s_cselect_b32 s18, s5, s9
	s_add_i32 s47, 0, 0x14000
	ds_read_b128 v[144:147], v64
	ds_read_b128 v[154:157], v64 offset:1024
	ds_read_b128 v[158:161], v64 offset:2048
	ds_read_b128 v[170:173], v64 offset:3072
	v_add_u32_e32 v64, s27, v165
	ds_read_b128 v[174:177], v64 offset:4096
	ds_read_b128 v[178:181], v64 offset:5120
	ds_read_b128 v[192:195], v64 offset:6144
	ds_read_b128 v[196:199], v64 offset:7168
	v_lshl_add_u64 v[162:163], s[16:17], 0, v[140:141]
	s_add_i32 m0, s53, 0xc000
	ds_read_b128 v[200:203], v169
	ds_read_b128 v[204:207], v169 offset:1024
	ds_read_b128 v[208:211], v169 offset:2048
	ds_read_b128 v[212:215], v169 offset:3072
	ds_read_b128 v[216:219], v169 offset:4096
	ds_read_b128 v[220:223], v169 offset:5120
	ds_read_b128 v[224:227], v169 offset:6144
	ds_read_b128 v[228:231], v169 offset:7168
	global_load_lds_dwordx4 v[162:163], off
	v_lshl_add_u64 v[162:163], s[16:17], 0, v[142:143]
	s_add_i32 m0, s53, 0xe000
	s_nop 0
	global_load_lds_dwordx4 v[162:163], off
	s_waitcnt vmcnt(8)
	s_waitcnt lgkmcnt(0)
	s_barrier
	s_setprio 1
	s_waitcnt lgkmcnt(0)
	v_mfma_f32_16x16x32_bf16 v[60:63], v[144:147], v[200:203], v[60:63]
	v_mfma_f32_16x16x32_bf16 v[56:59], v[158:161], v[200:203], v[56:59]
	v_mfma_f32_16x16x32_bf16 v[52:55], v[144:147], v[208:211], v[52:55]
	v_mfma_f32_16x16x32_bf16 v[48:51], v[158:161], v[208:211], v[48:51]
	v_mfma_f32_16x16x32_bf16 v[44:47], v[144:147], v[216:219], v[44:47]
	v_mfma_f32_16x16x32_bf16 v[40:43], v[158:161], v[216:219], v[40:43]
	v_mfma_f32_16x16x32_bf16 v[36:39], v[144:147], v[224:227], v[36:39]
	v_mfma_f32_16x16x32_bf16 v[32:35], v[158:161], v[224:227], v[32:35]
	v_mfma_f32_16x16x32_bf16 v[60:63], v[154:157], v[204:207], v[60:63]
	v_mfma_f32_16x16x32_bf16 v[56:59], v[170:173], v[204:207], v[56:59]
	v_mfma_f32_16x16x32_bf16 v[52:55], v[154:157], v[212:215], v[52:55]
	v_mfma_f32_16x16x32_bf16 v[48:51], v[170:173], v[212:215], v[48:51]
	v_mfma_f32_16x16x32_bf16 v[44:47], v[154:157], v[220:223], v[44:47]
	v_mfma_f32_16x16x32_bf16 v[40:43], v[170:173], v[220:223], v[40:43]
	v_mfma_f32_16x16x32_bf16 v[36:39], v[154:157], v[228:231], v[36:39]
	v_mfma_f32_16x16x32_bf16 v[32:35], v[170:173], v[228:231], v[32:35]
	s_setprio 0
	s_setprio 1
	v_mfma_f32_16x16x32_bf16 v[126:129], v[174:177], v[200:203], v[126:129]
	v_mfma_f32_16x16x32_bf16 v[122:125], v[192:195], v[200:203], v[122:125]
	v_mfma_f32_16x16x32_bf16 v[118:121], v[174:177], v[208:211], v[118:121]
	v_mfma_f32_16x16x32_bf16 v[114:117], v[192:195], v[208:211], v[114:117]
	v_mfma_f32_16x16x32_bf16 v[110:113], v[174:177], v[216:219], v[110:113]
	v_mfma_f32_16x16x32_bf16 v[106:109], v[192:195], v[216:219], v[106:109]
	v_mfma_f32_16x16x32_bf16 v[102:105], v[174:177], v[224:227], v[102:105]
	v_mfma_f32_16x16x32_bf16 v[98:101], v[192:195], v[224:227], v[98:101]
	v_mfma_f32_16x16x32_bf16 v[126:129], v[178:181], v[204:207], v[126:129]
	v_mfma_f32_16x16x32_bf16 v[122:125], v[196:199], v[204:207], v[122:125]
	v_mfma_f32_16x16x32_bf16 v[118:121], v[178:181], v[212:215], v[118:121]
	v_mfma_f32_16x16x32_bf16 v[114:117], v[196:199], v[212:215], v[114:117]
	v_mfma_f32_16x16x32_bf16 v[110:113], v[178:181], v[220:223], v[110:113]
	v_mfma_f32_16x16x32_bf16 v[106:109], v[196:199], v[220:223], v[106:109]
	v_mfma_f32_16x16x32_bf16 v[102:105], v[178:181], v[228:231], v[102:105]
	v_mfma_f32_16x16x32_bf16 v[98:101], v[196:199], v[228:231], v[98:101]
	s_setprio 0
	s_barrier
	s_add_i32 s27, s27, s54
	v_lshl_add_u64 v[162:163], s[18:19], 0, v[132:133]
	s_mov_b32 m0, s27
	ds_read_b128 v[200:203], v169 offset:16384
	ds_read_b128 v[204:207], v169 offset:17408
	ds_read_b128 v[208:211], v169 offset:18432
	ds_read_b128 v[212:215], v169 offset:19456
	ds_read_b128 v[216:219], v169 offset:20480
	ds_read_b128 v[220:223], v169 offset:21504
	ds_read_b128 v[224:227], v169 offset:22528
	ds_read_b128 v[228:231], v169 offset:23552
	global_load_lds_dwordx4 v[162:163], off
	s_add_i32 m0, s27, 0x2000
	s_add_u32 s28, s18, 0x80000
	v_lshl_add_u64 v[232:233], s[18:19], 0, v[136:137]
	s_addc_u32 s29, s19, 0
	s_add_i32 s27, s47, s54
	global_load_lds_dwordx4 v[232:233], off
	v_lshl_add_u64 v[234:235], s[28:29], 0, v[132:133]
	s_mov_b32 m0, s27
	v_lshl_add_u64 v[236:237], s[20:21], 0, v[134:135]
	global_load_lds_dwordx4 v[234:235], off
	v_lshl_add_u64 v[234:235], s[28:29], 0, v[136:137]
	s_add_i32 m0, s27, 0x2000
	s_nop 0
	global_load_lds_dwordx4 v[234:235], off
	v_lshl_add_u64 v[234:235], s[20:21], 0, v[130:131]
	s_mov_b32 m0, s53
	s_nop 0
	global_load_lds_dwordx4 v[234:235], off
	s_mov_b32 m0, s55
	s_nop 0
	global_load_lds_dwordx4 v[236:237], off
	s_waitcnt vmcnt(8)
	s_waitcnt lgkmcnt(0)
	s_barrier
	s_setprio 1
	s_waitcnt lgkmcnt(0)
	v_mfma_f32_16x16x32_bf16 v[28:31], v[144:147], v[200:203], v[28:31]
	v_mfma_f32_16x16x32_bf16 v[24:27], v[158:161], v[200:203], v[24:27]
	v_mfma_f32_16x16x32_bf16 v[20:23], v[144:147], v[208:211], v[20:23]
	v_mfma_f32_16x16x32_bf16 v[16:19], v[158:161], v[208:211], v[16:19]
	v_mfma_f32_16x16x32_bf16 v[12:15], v[144:147], v[216:219], v[12:15]
	v_mfma_f32_16x16x32_bf16 v[8:11], v[158:161], v[216:219], v[8:11]
	v_mfma_f32_16x16x32_bf16 v[4:7], v[144:147], v[224:227], v[4:7]
	v_mfma_f32_16x16x32_bf16 v[0:3], v[158:161], v[224:227], v[0:3]
	v_mfma_f32_16x16x32_bf16 v[28:31], v[154:157], v[204:207], v[28:31]
	v_mfma_f32_16x16x32_bf16 v[24:27], v[170:173], v[204:207], v[24:27]
	v_mfma_f32_16x16x32_bf16 v[20:23], v[154:157], v[212:215], v[20:23]
	v_mfma_f32_16x16x32_bf16 v[16:19], v[170:173], v[212:215], v[16:19]
	v_mfma_f32_16x16x32_bf16 v[12:15], v[154:157], v[220:223], v[12:15]
	v_mfma_f32_16x16x32_bf16 v[8:11], v[170:173], v[220:223], v[8:11]
	v_mfma_f32_16x16x32_bf16 v[4:7], v[154:157], v[228:231], v[4:7]
	v_mfma_f32_16x16x32_bf16 v[0:3], v[170:173], v[228:231], v[0:3]
	s_setprio 0
	s_setprio 1
	v_mfma_f32_16x16x32_bf16 v[94:97], v[174:177], v[200:203], v[94:97]
	v_mfma_f32_16x16x32_bf16 v[90:93], v[192:195], v[200:203], v[90:93]
	v_mfma_f32_16x16x32_bf16 v[86:89], v[174:177], v[208:211], v[86:89]
	v_mfma_f32_16x16x32_bf16 v[82:85], v[192:195], v[208:211], v[82:85]
	v_mfma_f32_16x16x32_bf16 v[78:81], v[174:177], v[216:219], v[78:81]
	v_mfma_f32_16x16x32_bf16 v[74:77], v[192:195], v[216:219], v[74:77]
	v_mfma_f32_16x16x32_bf16 v[70:73], v[174:177], v[224:227], v[70:73]
	v_mfma_f32_16x16x32_bf16 v[66:69], v[192:195], v[224:227], v[66:69]
	v_mfma_f32_16x16x32_bf16 v[94:97], v[178:181], v[204:207], v[94:97]
	v_mfma_f32_16x16x32_bf16 v[90:93], v[196:199], v[204:207], v[90:93]
	v_mfma_f32_16x16x32_bf16 v[86:89], v[178:181], v[212:215], v[86:89]
	v_mfma_f32_16x16x32_bf16 v[82:85], v[196:199], v[212:215], v[82:85]
	v_mfma_f32_16x16x32_bf16 v[78:81], v[178:181], v[220:223], v[78:81]
	v_mfma_f32_16x16x32_bf16 v[74:77], v[196:199], v[220:223], v[74:77]
	v_mfma_f32_16x16x32_bf16 v[70:73], v[178:181], v[228:231], v[70:73]
	v_mfma_f32_16x16x32_bf16 v[66:69], v[196:199], v[228:231], v[66:69]
	s_setprio 0
	s_barrier
	s_add_i32 s27, 0, 0x18000
	v_add_u32_e32 v64, s27, v165
	s_add_i32 s28, 0, 0x1c000
	ds_read_b128 v[144:147], v64
	ds_read_b128 v[154:157], v64 offset:1024
	ds_read_b128 v[158:161], v64 offset:2048
	ds_read_b128 v[170:173], v64 offset:3072
	v_add_u32_e32 v64, s27, v165
	ds_read_b128 v[174:177], v64 offset:4096
	ds_read_b128 v[178:181], v64 offset:5120
	ds_read_b128 v[192:195], v64 offset:6144
	ds_read_b128 v[196:199], v64 offset:7168
	s_add_u32 s20, s20, 0x80000
	s_addc_u32 s21, s21, 0
	s_mov_b32 m0, s6
	v_lshl_add_u64 v[238:239], s[20:21], 0, v[130:131]
	ds_read_b128 v[200:203], v169 offset:32768
	ds_read_b128 v[204:207], v169 offset:33792
	ds_read_b128 v[208:211], v169 offset:34816
	ds_read_b128 v[212:215], v169 offset:35840
	ds_read_b128 v[216:219], v169 offset:36864
	ds_read_b128 v[220:223], v169 offset:37888
	ds_read_b128 v[224:227], v169 offset:38912
	ds_read_b128 v[228:231], v169 offset:39936
	global_load_lds_dwordx4 v[238:239], off
	v_lshl_add_u64 v[238:239], s[20:21], 0, v[134:135]
	s_mov_b32 m0, s7
	s_nop 0
	global_load_lds_dwordx4 v[238:239], off
	s_waitcnt vmcnt(8)
	s_waitcnt lgkmcnt(0)
	s_barrier
	s_setprio 1
	s_waitcnt lgkmcnt(0)
	v_mfma_f32_16x16x32_bf16 v[60:63], v[144:147], v[200:203], v[60:63]
	v_mfma_f32_16x16x32_bf16 v[56:59], v[158:161], v[200:203], v[56:59]
	v_mfma_f32_16x16x32_bf16 v[52:55], v[144:147], v[208:211], v[52:55]
	v_mfma_f32_16x16x32_bf16 v[48:51], v[158:161], v[208:211], v[48:51]
	v_mfma_f32_16x16x32_bf16 v[44:47], v[144:147], v[216:219], v[44:47]
	v_mfma_f32_16x16x32_bf16 v[40:43], v[158:161], v[216:219], v[40:43]
	v_mfma_f32_16x16x32_bf16 v[36:39], v[144:147], v[224:227], v[36:39]
	v_mfma_f32_16x16x32_bf16 v[32:35], v[158:161], v[224:227], v[32:35]
	v_mfma_f32_16x16x32_bf16 v[60:63], v[154:157], v[204:207], v[60:63]
	v_mfma_f32_16x16x32_bf16 v[56:59], v[170:173], v[204:207], v[56:59]
	v_mfma_f32_16x16x32_bf16 v[52:55], v[154:157], v[212:215], v[52:55]
	v_mfma_f32_16x16x32_bf16 v[48:51], v[170:173], v[212:215], v[48:51]
	v_mfma_f32_16x16x32_bf16 v[44:47], v[154:157], v[220:223], v[44:47]
	v_mfma_f32_16x16x32_bf16 v[40:43], v[170:173], v[220:223], v[40:43]
	v_mfma_f32_16x16x32_bf16 v[36:39], v[154:157], v[228:231], v[36:39]
	v_mfma_f32_16x16x32_bf16 v[32:35], v[170:173], v[228:231], v[32:35]
	s_setprio 0
	s_setprio 1
	v_mfma_f32_16x16x32_bf16 v[126:129], v[174:177], v[200:203], v[126:129]
	v_mfma_f32_16x16x32_bf16 v[122:125], v[192:195], v[200:203], v[122:125]
	v_mfma_f32_16x16x32_bf16 v[118:121], v[174:177], v[208:211], v[118:121]
	v_mfma_f32_16x16x32_bf16 v[114:117], v[192:195], v[208:211], v[114:117]
	v_mfma_f32_16x16x32_bf16 v[110:113], v[174:177], v[216:219], v[110:113]
	v_mfma_f32_16x16x32_bf16 v[106:109], v[192:195], v[216:219], v[106:109]
	v_mfma_f32_16x16x32_bf16 v[102:105], v[174:177], v[224:227], v[102:105]
	v_mfma_f32_16x16x32_bf16 v[98:101], v[192:195], v[224:227], v[98:101]
	v_mfma_f32_16x16x32_bf16 v[126:129], v[178:181], v[204:207], v[126:129]
	v_mfma_f32_16x16x32_bf16 v[122:125], v[196:199], v[204:207], v[122:125]
	v_mfma_f32_16x16x32_bf16 v[118:121], v[178:181], v[212:215], v[118:121]
	v_mfma_f32_16x16x32_bf16 v[114:117], v[196:199], v[212:215], v[114:117]
	v_mfma_f32_16x16x32_bf16 v[110:113], v[178:181], v[220:223], v[110:113]
	v_mfma_f32_16x16x32_bf16 v[106:109], v[196:199], v[220:223], v[106:109]
	v_mfma_f32_16x16x32_bf16 v[102:105], v[178:181], v[228:231], v[102:105]
	v_mfma_f32_16x16x32_bf16 v[98:101], v[196:199], v[228:231], v[98:101]
	s_setprio 0
	s_barrier
	s_add_i32 s20, s27, s54
	v_lshl_add_u64 v[162:163], v[162:163], 0, s[30:31]
	s_mov_b32 m0, s20
	ds_read_b128 v[200:203], v169 offset:49152
	ds_read_b128 v[204:207], v169 offset:50176
	ds_read_b128 v[208:211], v169 offset:51200
	ds_read_b128 v[212:215], v169 offset:52224
	ds_read_b128 v[216:219], v169 offset:53248
	ds_read_b128 v[220:223], v169 offset:54272
	ds_read_b128 v[224:227], v169 offset:55296
	ds_read_b128 v[228:231], v169 offset:56320
	global_load_lds_dwordx4 v[162:163], off
	s_add_i32 m0, s20, 0x2000
	s_add_u32 s18, s18, 0x80080
	v_lshl_add_u64 v[162:163], v[232:233], 0, s[30:31]
	s_addc_u32 s19, s19, 0
	s_add_i32 s20, s28, s54
	global_load_lds_dwordx4 v[162:163], off
	v_lshl_add_u64 v[162:163], s[18:19], 0, v[132:133]
	s_mov_b32 m0, s20
	s_nop 0
	global_load_lds_dwordx4 v[162:163], off
	v_lshl_add_u64 v[162:163], s[18:19], 0, v[136:137]
	s_add_i32 m0, s20, 0x2000
	s_nop 0
	global_load_lds_dwordx4 v[162:163], off
	v_lshl_add_u64 v[162:163], v[234:235], 0, s[30:31]
	s_mov_b32 m0, s59
	s_nop 0
	global_load_lds_dwordx4 v[162:163], off
	v_lshl_add_u64 v[162:163], v[236:237], 0, s[30:31]
	s_mov_b32 m0, s58
	s_nop 0
	global_load_lds_dwordx4 v[162:163], off
	s_waitcnt vmcnt(8)
	s_waitcnt lgkmcnt(0)
	s_barrier
	s_setprio 1
	s_waitcnt lgkmcnt(0)
	v_mfma_f32_16x16x32_bf16 v[28:31], v[144:147], v[200:203], v[28:31]
	v_mfma_f32_16x16x32_bf16 v[24:27], v[158:161], v[200:203], v[24:27]
	v_mfma_f32_16x16x32_bf16 v[20:23], v[144:147], v[208:211], v[20:23]
	v_mfma_f32_16x16x32_bf16 v[16:19], v[158:161], v[208:211], v[16:19]
	v_mfma_f32_16x16x32_bf16 v[12:15], v[144:147], v[216:219], v[12:15]
	v_mfma_f32_16x16x32_bf16 v[8:11], v[158:161], v[216:219], v[8:11]
	v_mfma_f32_16x16x32_bf16 v[4:7], v[144:147], v[224:227], v[4:7]
	v_mfma_f32_16x16x32_bf16 v[0:3], v[158:161], v[224:227], v[0:3]
	v_mfma_f32_16x16x32_bf16 v[28:31], v[154:157], v[204:207], v[28:31]
	v_mfma_f32_16x16x32_bf16 v[24:27], v[170:173], v[204:207], v[24:27]
	v_mfma_f32_16x16x32_bf16 v[20:23], v[154:157], v[212:215], v[20:23]
	v_mfma_f32_16x16x32_bf16 v[16:19], v[170:173], v[212:215], v[16:19]
	v_mfma_f32_16x16x32_bf16 v[12:15], v[154:157], v[220:223], v[12:15]
	v_mfma_f32_16x16x32_bf16 v[8:11], v[170:173], v[220:223], v[8:11]
	v_mfma_f32_16x16x32_bf16 v[4:7], v[154:157], v[228:231], v[4:7]
	v_mfma_f32_16x16x32_bf16 v[0:3], v[170:173], v[228:231], v[0:3]
	s_setprio 0
	s_setprio 1
	v_mfma_f32_16x16x32_bf16 v[94:97], v[174:177], v[200:203], v[94:97]
	v_mfma_f32_16x16x32_bf16 v[90:93], v[192:195], v[200:203], v[90:93]
	v_mfma_f32_16x16x32_bf16 v[86:89], v[174:177], v[208:211], v[86:89]
	v_mfma_f32_16x16x32_bf16 v[82:85], v[192:195], v[208:211], v[82:85]
	v_mfma_f32_16x16x32_bf16 v[78:81], v[174:177], v[216:219], v[78:81]
	v_mfma_f32_16x16x32_bf16 v[74:77], v[192:195], v[216:219], v[74:77]
	v_mfma_f32_16x16x32_bf16 v[70:73], v[174:177], v[224:227], v[70:73]
	v_mfma_f32_16x16x32_bf16 v[66:69], v[192:195], v[224:227], v[66:69]
	v_mfma_f32_16x16x32_bf16 v[94:97], v[178:181], v[204:207], v[94:97]
	v_mfma_f32_16x16x32_bf16 v[90:93], v[196:199], v[204:207], v[90:93]
	v_mfma_f32_16x16x32_bf16 v[86:89], v[178:181], v[212:215], v[86:89]
	v_mfma_f32_16x16x32_bf16 v[82:85], v[196:199], v[212:215], v[82:85]
	v_mfma_f32_16x16x32_bf16 v[78:81], v[178:181], v[220:223], v[78:81]
	v_mfma_f32_16x16x32_bf16 v[74:77], v[196:199], v[220:223], v[74:77]
	v_mfma_f32_16x16x32_bf16 v[70:73], v[178:181], v[228:231], v[70:73]
	v_mfma_f32_16x16x32_bf16 v[66:69], v[196:199], v[228:231], v[66:69]
	s_setprio 0
	s_barrier
	s_add_i32 s26, s26, 2
	s_add_u32 s16, s16, 0x100
	s_addc_u32 s17, s17, 0
	s_add_u32 s9, s9, 0x100
	s_addc_u32 s11, s11, 0
	s_cmp_gt_u32 s26, 29
	s_cbranch_scc0 .LBB0_329
	s_and_b64 vcc, exec, s[74:75]
	s_cbranch_vccnz .LBB0_333
	s_cmpk_lg_i32 s52, 0x50
	s_mov_b64 s[16:17], -1
	s_movk_i32 s28, 0x101
	s_cbranch_scc1 .LBB0_334

.LBB0_334:
	s_cmp_gt_i32 s52, 15
	s_cbranch_scc0 .LBB0_345
	s_cmp_lt_u32 s52, 24
	s_cselect_b64 s[16:17], -1, 0
	s_and_b64 vcc, exec, s[16:17]
	s_cbranch_vccnz .LBB0_342
	s_and_b32 s0, s52, 0x7ffffff8
	s_cmp_lg_u32 s0, 40
	s_cselect_b64 s[2:3], -1, 0
	s_cmpk_lt_u32 s52, 0x48
	s_cselect_b64 s[16:17], -1, 0
	s_and_b64 s[2:3], s[16:17], s[2:3]
	s_mov_b64 s[16:17], -1
	s_and_b64 vcc, exec, s[2:3]
	s_cbranch_vccz .LBB0_342
	v_lshl_add_u32 v146, s10, 8, v164
	v_lshl_or_b32 v64, s52, 8, v168
	v_mov_b64_e32 v[144:145], s[56:57]
	v_mad_i64_i32 v[144:145], s[2:3], v146, s69, v[144:145]
	v_lshlrev_b32_e32 v64, 1, v64
	s_cmp_gt_u32 s52, 27
	v_lshl_add_u64 v[144:145], v[144:145], 0, v[64:65]
	v_or_b32_e32 v158, 16, v146
	v_or_b32_e32 v157, 32, v146
	v_or_b32_e32 v156, 48, v146
	v_add_u32_e32 v155, 0x80, v146
	v_add_u32_e32 v154, 0x90, v146
	v_add_u32_e32 v147, 0xa0, v146
	v_add_u32_e32 v146, 0xb0, v146
	s_cbranch_scc0 .LBB0_339
	v_cvt_pk_bf16_f32 v160, v60, v61
	v_cvt_pk_bf16_f32 v161, v62, v63
	v_cvt_pk_bf16_f32 v162, v56, v57
	v_cvt_pk_bf16_f32 v163, v58, v59
	v_mov_b32_e32 v240, v160
	v_mov_b32_e32 v241, v161
	v_mov_b32_e32 v242, v162
	v_mov_b32_e32 v243, v163
	v_mov_b64_e32 v[170:171], s[56:57]
	s_mov_b64 s[16:17], 0
	v_cvt_pk_bf16_f32 v160, v126, v127
	v_cvt_pk_bf16_f32 v161, v128, v129
	v_cvt_pk_bf16_f32 v162, v122, v123
	v_cvt_pk_bf16_f32 v163, v124, v125
	s_nop 1
	v_mov_b32_dpp v244, v160 quad_perm:[1,0,3,2] row_mask:0xf bank_mask:0xf
	v_mov_b32_dpp v245, v240 quad_perm:[1,0,3,2] row_mask:0xf bank_mask:0xf
	v_cndmask_b32_e64 v240, v240, v244, s[98:99]
	v_cndmask_b32_e64 v160, v245, v160, s[98:99]
	v_mov_b32_dpp v244, v161 quad_perm:[1,0,3,2] row_mask:0xf bank_mask:0xf
	v_mov_b32_dpp v245, v241 quad_perm:[1,0,3,2] row_mask:0xf bank_mask:0xf
	v_cndmask_b32_e64 v241, v241, v244, s[98:99]
	v_cndmask_b32_e64 v161, v245, v161, s[98:99]
	v_mov_b32_dpp v244, v162 quad_perm:[1,0,3,2] row_mask:0xf bank_mask:0xf
	v_mov_b32_dpp v245, v242 quad_perm:[1,0,3,2] row_mask:0xf bank_mask:0xf
	v_cndmask_b32_e64 v242, v242, v244, s[98:99]
	v_cndmask_b32_e64 v162, v245, v162, s[98:99]
	v_mov_b32_dpp v244, v163 quad_perm:[1,0,3,2] row_mask:0xf bank_mask:0xf
	v_mov_b32_dpp v245, v243 quad_perm:[1,0,3,2] row_mask:0xf bank_mask:0xf
	v_cndmask_b32_e64 v243, v243, v244, s[98:99]
	v_cndmask_b32_e64 v163, v245, v163, s[98:99]
	v_lshl_add_u64 v[246:247], v[144:145], 0, s[100:101]
	global_store_dwordx4 v[144:145], v[240:243], off nt
	global_store_dwordx4 v[246:247], v[160:163], off nt
	s_nop 1
	v_mad_i64_i32 v[160:161], s[2:3], v158, s69, v[170:171]
	v_lshl_add_u64 v[172:173], v[160:161], 0, v[64:65]
	v_cvt_pk_bf16_f32 v160, v52, v53
	v_cvt_pk_bf16_f32 v161, v54, v55
	v_cvt_pk_bf16_f32 v162, v48, v49
	v_cvt_pk_bf16_f32 v163, v50, v51
	v_mov_b32_e32 v240, v160
	v_mov_b32_e32 v241, v161
	v_mov_b32_e32 v242, v162
	v_mov_b32_e32 v243, v163
	s_nop 1
	v_cvt_pk_bf16_f32 v160, v118, v119
	v_cvt_pk_bf16_f32 v161, v120, v121
	v_cvt_pk_bf16_f32 v162, v114, v115
	v_cvt_pk_bf16_f32 v163, v116, v117
	s_nop 1
	v_mov_b32_dpp v244, v160 quad_perm:[1,0,3,2] row_mask:0xf bank_mask:0xf
	v_mov_b32_dpp v245, v240 quad_perm:[1,0,3,2] row_mask:0xf bank_mask:0xf
	v_cndmask_b32_e64 v240, v240, v244, s[98:99]
	v_cndmask_b32_e64 v160, v245, v160, s[98:99]
	v_mov_b32_dpp v244, v161 quad_perm:[1,0,3,2] row_mask:0xf bank_mask:0xf
	v_mov_b32_dpp v245, v241 quad_perm:[1,0,3,2] row_mask:0xf bank_mask:0xf
	v_cndmask_b32_e64 v241, v241, v244, s[98:99]
	v_cndmask_b32_e64 v161, v245, v161, s[98:99]
	v_mov_b32_dpp v244, v162 quad_perm:[1,0,3,2] row_mask:0xf bank_mask:0xf
	v_mov_b32_dpp v245, v242 quad_perm:[1,0,3,2] row_mask:0xf bank_mask:0xf
	v_cndmask_b32_e64 v242, v242, v244, s[98:99]
	v_cndmask_b32_e64 v162, v245, v162, s[98:99]
	v_mov_b32_dpp v244, v163 quad_perm:[1,0,3,2] row_mask:0xf bank_mask:0xf
	v_mov_b32_dpp v245, v243 quad_perm:[1,0,3,2] row_mask:0xf bank_mask:0xf
	v_cndmask_b32_e64 v243, v243, v244, s[98:99]
	v_cndmask_b32_e64 v163, v245, v163, s[98:99]
	v_lshl_add_u64 v[246:247], v[172:173], 0, s[100:101]
	global_store_dwordx4 v[172:173], v[240:243], off nt
	global_store_dwordx4 v[246:247], v[160:163], off nt
	s_nop 1
	v_mad_i64_i32 v[160:161], s[2:3], v157, s69, v[170:171]
	v_lshl_add_u64 v[172:173], v[160:161], 0, v[64:65]
	v_cvt_pk_bf16_f32 v160, v44, v45
	v_cvt_pk_bf16_f32 v161, v46, v47
	v_cvt_pk_bf16_f32 v162, v40, v41
	v_cvt_pk_bf16_f32 v163, v42, v43
	v_mov_b32_e32 v240, v160
	v_mov_b32_e32 v241, v161
	v_mov_b32_e32 v242, v162
	v_mov_b32_e32 v243, v163
	s_nop 1
	v_cvt_pk_bf16_f32 v160, v110, v111
	v_cvt_pk_bf16_f32 v161, v112, v113
	v_cvt_pk_bf16_f32 v162, v106, v107
	v_cvt_pk_bf16_f32 v163, v108, v109
	s_nop 1
	v_mov_b32_dpp v244, v160 quad_perm:[1,0,3,2] row_mask:0xf bank_mask:0xf
	v_mov_b32_dpp v245, v240 quad_perm:[1,0,3,2] row_mask:0xf bank_mask:0xf
	v_cndmask_b32_e64 v240, v240, v244, s[98:99]
	v_cndmask_b32_e64 v160, v245, v160, s[98:99]
	v_mov_b32_dpp v244, v161 quad_perm:[1,0,3,2] row_mask:0xf bank_mask:0xf
	v_mov_b32_dpp v245, v241 quad_perm:[1,0,3,2] row_mask:0xf bank_mask:0xf
	v_cndmask_b32_e64 v241, v241, v244, s[98:99]
	v_cndmask_b32_e64 v161, v245, v161, s[98:99]
	v_mov_b32_dpp v244, v162 quad_perm:[1,0,3,2] row_mask:0xf bank_mask:0xf
	v_mov_b32_dpp v245, v242 quad_perm:[1,0,3,2] row_mask:0xf bank_mask:0xf
	v_cndmask_b32_e64 v242, v242, v244, s[98:99]
	v_cndmask_b32_e64 v162, v245, v162, s[98:99]
	v_mov_b32_dpp v244, v163 quad_perm:[1,0,3,2] row_mask:0xf bank_mask:0xf
	v_mov_b32_dpp v245, v243 quad_perm:[1,0,3,2] row_mask:0xf bank_mask:0xf
	v_cndmask_b32_e64 v243, v243, v244, s[98:99]
	v_cndmask_b32_e64 v163, v245, v163, s[98:99]
	v_lshl_add_u64 v[246:247], v[172:173], 0, s[100:101]
	global_store_dwordx4 v[172:173], v[240:243], off nt
	global_store_dwordx4 v[246:247], v[160:163], off nt
	s_nop 1
	v_mad_i64_i32 v[160:161], s[2:3], v156, s69, v[170:171]
	v_lshl_add_u64 v[172:173], v[160:161], 0, v[64:65]
	v_cvt_pk_bf16_f32 v160, v36, v37
	v_cvt_pk_bf16_f32 v161, v38, v39
	v_cvt_pk_bf16_f32 v162, v32, v33
	v_cvt_pk_bf16_f32 v163, v34, v35
	v_mov_b32_e32 v240, v160
	v_mov_b32_e32 v241, v161
	v_mov_b32_e32 v242, v162
	v_mov_b32_e32 v243, v163
	s_nop 1
	v_cvt_pk_bf16_f32 v160, v102, v103
	v_cvt_pk_bf16_f32 v161, v104, v105
	v_cvt_pk_bf16_f32 v162, v98, v99
	v_cvt_pk_bf16_f32 v163, v100, v101
	s_nop 1
	v_mov_b32_dpp v244, v160 quad_perm:[1,0,3,2] row_mask:0xf bank_mask:0xf
	v_mov_b32_dpp v245, v240 quad_perm:[1,0,3,2] row_mask:0xf bank_mask:0xf
	v_cndmask_b32_e64 v240, v240, v244, s[98:99]
	v_cndmask_b32_e64 v160, v245, v160, s[98:99]
	v_mov_b32_dpp v244, v161 quad_perm:[1,0,3,2] row_mask:0xf bank_mask:0xf
	v_mov_b32_dpp v245, v241 quad_perm:[1,0,3,2] row_mask:0xf bank_mask:0xf
	v_cndmask_b32_e64 v241, v241, v244, s[98:99]
	v_cndmask_b32_e64 v161, v245, v161, s[98:99]
	v_mov_b32_dpp v244, v162 quad_perm:[1,0,3,2] row_mask:0xf bank_mask:0xf
	v_mov_b32_dpp v245, v242 quad_perm:[1,0,3,2] row_mask:0xf bank_mask:0xf
	v_cndmask_b32_e64 v242, v242, v244, s[98:99]
	v_cndmask_b32_e64 v162, v245, v162, s[98:99]
	v_mov_b32_dpp v244, v163 quad_perm:[1,0,3,2] row_mask:0xf bank_mask:0xf
	v_mov_b32_dpp v245, v243 quad_perm:[1,0,3,2] row_mask:0xf bank_mask:0xf
	v_cndmask_b32_e64 v243, v243, v244, s[98:99]
	v_cndmask_b32_e64 v163, v245, v163, s[98:99]
	v_lshl_add_u64 v[246:247], v[172:173], 0, s[100:101]
	global_store_dwordx4 v[172:173], v[240:243], off nt
	global_store_dwordx4 v[246:247], v[160:163], off nt
	s_nop 1
	v_mad_i64_i32 v[160:161], s[2:3], v155, s69, v[170:171]
	v_lshl_add_u64 v[172:173], v[160:161], 0, v[64:65]
	v_cvt_pk_bf16_f32 v160, v28, v29
	v_cvt_pk_bf16_f32 v161, v30, v31
	v_cvt_pk_bf16_f32 v162, v24, v25
	v_cvt_pk_bf16_f32 v163, v26, v27
	v_mov_b32_e32 v240, v160
	v_mov_b32_e32 v241, v161
	v_mov_b32_e32 v242, v162
	v_mov_b32_e32 v243, v163
	s_nop 1
	v_cvt_pk_bf16_f32 v160, v94, v95
	v_cvt_pk_bf16_f32 v161, v96, v97
	v_cvt_pk_bf16_f32 v162, v90, v91
	v_cvt_pk_bf16_f32 v163, v92, v93
	s_nop 1
	v_mov_b32_dpp v244, v160 quad_perm:[1,0,3,2] row_mask:0xf bank_mask:0xf
	v_mov_b32_dpp v245, v240 quad_perm:[1,0,3,2] row_mask:0xf bank_mask:0xf
	v_cndmask_b32_e64 v240, v240, v244, s[98:99]
	v_cndmask_b32_e64 v160, v245, v160, s[98:99]
	v_mov_b32_dpp v244, v161 quad_perm:[1,0,3,2] row_mask:0xf bank_mask:0xf
	v_mov_b32_dpp v245, v241 quad_perm:[1,0,3,2] row_mask:0xf bank_mask:0xf
	v_cndmask_b32_e64 v241, v241, v244, s[98:99]
	v_cndmask_b32_e64 v161, v245, v161, s[98:99]
	v_mov_b32_dpp v244, v162 quad_perm:[1,0,3,2] row_mask:0xf bank_mask:0xf
	v_mov_b32_dpp v245, v242 quad_perm:[1,0,3,2] row_mask:0xf bank_mask:0xf
	v_cndmask_b32_e64 v242, v242, v244, s[98:99]
	v_cndmask_b32_e64 v162, v245, v162, s[98:99]
	v_mov_b32_dpp v244, v163 quad_perm:[1,0,3,2] row_mask:0xf bank_mask:0xf
	v_mov_b32_dpp v245, v243 quad_perm:[1,0,3,2] row_mask:0xf bank_mask:0xf
	v_cndmask_b32_e64 v243, v243, v244, s[98:99]
	v_cndmask_b32_e64 v163, v245, v163, s[98:99]
	v_lshl_add_u64 v[246:247], v[172:173], 0, s[100:101]
	global_store_dwordx4 v[172:173], v[240:243], off nt
	global_store_dwordx4 v[246:247], v[160:163], off nt
	s_nop 1
	v_mad_i64_i32 v[160:161], s[2:3], v154, s69, v[170:171]
	v_lshl_add_u64 v[172:173], v[160:161], 0, v[64:65]
	v_cvt_pk_bf16_f32 v160, v20, v21
	v_cvt_pk_bf16_f32 v161, v22, v23
	v_cvt_pk_bf16_f32 v162, v16, v17
	v_cvt_pk_bf16_f32 v163, v18, v19
	v_mov_b32_e32 v240, v160
	v_mov_b32_e32 v241, v161
	v_mov_b32_e32 v242, v162
	v_mov_b32_e32 v243, v163
	s_nop 1
	v_cvt_pk_bf16_f32 v160, v86, v87
	v_cvt_pk_bf16_f32 v161, v88, v89
	v_cvt_pk_bf16_f32 v162, v82, v83
	v_cvt_pk_bf16_f32 v163, v84, v85
	s_nop 1
	v_mov_b32_dpp v244, v160 quad_perm:[1,0,3,2] row_mask:0xf bank_mask:0xf
	v_mov_b32_dpp v245, v240 quad_perm:[1,0,3,2] row_mask:0xf bank_mask:0xf
	v_cndmask_b32_e64 v240, v240, v244, s[98:99]
	v_cndmask_b32_e64 v160, v245, v160, s[98:99]
	v_mov_b32_dpp v244, v161 quad_perm:[1,0,3,2] row_mask:0xf bank_mask:0xf
	v_mov_b32_dpp v245, v241 quad_perm:[1,0,3,2] row_mask:0xf bank_mask:0xf
	v_cndmask_b32_e64 v241, v241, v244, s[98:99]
	v_cndmask_b32_e64 v161, v245, v161, s[98:99]
	v_mov_b32_dpp v244, v162 quad_perm:[1,0,3,2] row_mask:0xf bank_mask:0xf
	v_mov_b32_dpp v245, v242 quad_perm:[1,0,3,2] row_mask:0xf bank_mask:0xf
	v_cndmask_b32_e64 v242, v242, v244, s[98:99]
	v_cndmask_b32_e64 v162, v245, v162, s[98:99]
	v_mov_b32_dpp v244, v163 quad_perm:[1,0,3,2] row_mask:0xf bank_mask:0xf
	v_mov_b32_dpp v245, v243 quad_perm:[1,0,3,2] row_mask:0xf bank_mask:0xf
	v_cndmask_b32_e64 v243, v243, v244, s[98:99]
	v_cndmask_b32_e64 v163, v245, v163, s[98:99]
	v_lshl_add_u64 v[246:247], v[172:173], 0, s[100:101]
	global_store_dwordx4 v[172:173], v[240:243], off nt
	global_store_dwordx4 v[246:247], v[160:163], off nt
	s_nop 1
	v_mad_i64_i32 v[160:161], s[2:3], v147, s69, v[170:171]
	v_lshl_add_u64 v[172:173], v[160:161], 0, v[64:65]
	v_cvt_pk_bf16_f32 v160, v12, v13
	v_cvt_pk_bf16_f32 v161, v14, v15
	v_cvt_pk_bf16_f32 v162, v8, v9
	v_cvt_pk_bf16_f32 v163, v10, v11
	v_mov_b32_e32 v240, v160
	v_mov_b32_e32 v241, v161
	v_mov_b32_e32 v242, v162
	v_mov_b32_e32 v243, v163
	s_nop 1
	v_cvt_pk_bf16_f32 v160, v78, v79
	v_cvt_pk_bf16_f32 v161, v80, v81
	v_cvt_pk_bf16_f32 v162, v74, v75
	v_cvt_pk_bf16_f32 v163, v76, v77
	s_nop 1
	v_mov_b32_dpp v244, v160 quad_perm:[1,0,3,2] row_mask:0xf bank_mask:0xf
	v_mov_b32_dpp v245, v240 quad_perm:[1,0,3,2] row_mask:0xf bank_mask:0xf
	v_cndmask_b32_e64 v240, v240, v244, s[98:99]
	v_cndmask_b32_e64 v160, v245, v160, s[98:99]
	v_mov_b32_dpp v244, v161 quad_perm:[1,0,3,2] row_mask:0xf bank_mask:0xf
	v_mov_b32_dpp v245, v241 quad_perm:[1,0,3,2] row_mask:0xf bank_mask:0xf
	v_cndmask_b32_e64 v241, v241, v244, s[98:99]
	v_cndmask_b32_e64 v161, v245, v161, s[98:99]
	v_mov_b32_dpp v244, v162 quad_perm:[1,0,3,2] row_mask:0xf bank_mask:0xf
	v_mov_b32_dpp v245, v242 quad_perm:[1,0,3,2] row_mask:0xf bank_mask:0xf
	v_cndmask_b32_e64 v242, v242, v244, s[98:99]
	v_cndmask_b32_e64 v162, v245, v162, s[98:99]
	v_mov_b32_dpp v244, v163 quad_perm:[1,0,3,2] row_mask:0xf bank_mask:0xf
	v_mov_b32_dpp v245, v243 quad_perm:[1,0,3,2] row_mask:0xf bank_mask:0xf
	v_cndmask_b32_e64 v243, v243, v244, s[98:99]
	v_cndmask_b32_e64 v163, v245, v163, s[98:99]
	v_lshl_add_u64 v[246:247], v[172:173], 0, s[100:101]
	global_store_dwordx4 v[172:173], v[240:243], off nt
	global_store_dwordx4 v[246:247], v[160:163], off nt
	s_nop 1
	v_mad_i64_i32 v[160:161], s[2:3], v146, s69, v[170:171]
	v_lshl_add_u64 v[170:171], v[160:161], 0, v[64:65]
	v_cvt_pk_bf16_f32 v160, v4, v5
	v_cvt_pk_bf16_f32 v161, v6, v7
	v_cvt_pk_bf16_f32 v162, v0, v1
	v_cvt_pk_bf16_f32 v163, v2, v3
	v_mov_b32_e32 v240, v160
	v_mov_b32_e32 v241, v161
	v_mov_b32_e32 v242, v162
	v_mov_b32_e32 v243, v163
	s_nop 1
	v_cvt_pk_bf16_f32 v160, v70, v71
	v_cvt_pk_bf16_f32 v161, v72, v73
	v_cvt_pk_bf16_f32 v162, v66, v67
	v_cvt_pk_bf16_f32 v163, v68, v69
	s_nop 1
	v_mov_b32_dpp v244, v160 quad_perm:[1,0,3,2] row_mask:0xf bank_mask:0xf
	v_mov_b32_dpp v245, v240 quad_perm:[1,0,3,2] row_mask:0xf bank_mask:0xf
	v_cndmask_b32_e64 v240, v240, v244, s[98:99]
	v_cndmask_b32_e64 v160, v245, v160, s[98:99]
	v_mov_b32_dpp v244, v161 quad_perm:[1,0,3,2] row_mask:0xf bank_mask:0xf
	v_mov_b32_dpp v245, v241 quad_perm:[1,0,3,2] row_mask:0xf bank_mask:0xf
	v_cndmask_b32_e64 v241, v241, v244, s[98:99]
	v_cndmask_b32_e64 v161, v245, v161, s[98:99]
	v_mov_b32_dpp v244, v162 quad_perm:[1,0,3,2] row_mask:0xf bank_mask:0xf
	v_mov_b32_dpp v245, v242 quad_perm:[1,0,3,2] row_mask:0xf bank_mask:0xf
	v_cndmask_b32_e64 v242, v242, v244, s[98:99]
	v_cndmask_b32_e64 v162, v245, v162, s[98:99]
	v_mov_b32_dpp v244, v163 quad_perm:[1,0,3,2] row_mask:0xf bank_mask:0xf
	v_mov_b32_dpp v245, v243 quad_perm:[1,0,3,2] row_mask:0xf bank_mask:0xf
	v_cndmask_b32_e64 v243, v243, v244, s[98:99]
	v_cndmask_b32_e64 v163, v245, v163, s[98:99]
	v_lshl_add_u64 v[246:247], v[170:171], 0, s[100:101]
	global_store_dwordx4 v[170:171], v[240:243], off nt
	global_store_dwordx4 v[246:247], v[160:163], off nt
.LBB0_339:
	s_andn2_b64 vcc, exec, s[16:17]
	s_cbranch_vccnz .LBB0_341
	s_mov_b32 s0, 0x3d800000
	v_pk_mul_f32 v[160:161], v[60:61], s[0:1] op_sel_hi:[1,0]
	v_pk_mul_f32 v[162:163], v[62:63], s[0:1] op_sel_hi:[1,0]
	v_pk_mul_f32 v[170:171], v[56:57], s[0:1] op_sel_hi:[1,0]
	v_pk_mul_f32 v[172:173], v[58:59], s[0:1] op_sel_hi:[1,0]
	v_cvt_pk_bf16_f32 v160, v160, v161
	v_cvt_pk_bf16_f32 v161, v162, v163
	v_cvt_pk_bf16_f32 v162, v170, v171
	v_cvt_pk_bf16_f32 v163, v172, v173
	v_mov_b32_e32 v240, v160
	v_mov_b32_e32 v241, v161
	v_mov_b32_e32 v242, v162
	v_mov_b32_e32 v243, v163
	v_pk_mul_f32 v[170:171], v[122:123], s[0:1] op_sel_hi:[1,0]
	v_pk_mul_f32 v[172:173], v[124:125], s[0:1] op_sel_hi:[1,0]
	v_pk_mul_f32 v[160:161], v[126:127], s[0:1] op_sel_hi:[1,0]
	v_pk_mul_f32 v[162:163], v[128:129], s[0:1] op_sel_hi:[1,0]
	v_cvt_pk_bf16_f32 v160, v160, v161
	v_cvt_pk_bf16_f32 v161, v162, v163
	v_cvt_pk_bf16_f32 v162, v170, v171
	v_cvt_pk_bf16_f32 v163, v172, v173
	s_nop 1
	v_mov_b32_dpp v244, v160 quad_perm:[1,0,3,2] row_mask:0xf bank_mask:0xf
	v_mov_b32_dpp v245, v240 quad_perm:[1,0,3,2] row_mask:0xf bank_mask:0xf
	v_cndmask_b32_e64 v240, v240, v244, s[98:99]
	v_cndmask_b32_e64 v160, v245, v160, s[98:99]
	v_mov_b32_dpp v244, v161 quad_perm:[1,0,3,2] row_mask:0xf bank_mask:0xf
	v_mov_b32_dpp v245, v241 quad_perm:[1,0,3,2] row_mask:0xf bank_mask:0xf
	v_cndmask_b32_e64 v241, v241, v244, s[98:99]
	v_cndmask_b32_e64 v161, v245, v161, s[98:99]
	v_mov_b32_dpp v244, v162 quad_perm:[1,0,3,2] row_mask:0xf bank_mask:0xf
	v_mov_b32_dpp v245, v242 quad_perm:[1,0,3,2] row_mask:0xf bank_mask:0xf
	v_cndmask_b32_e64 v242, v242, v244, s[98:99]
	v_cndmask_b32_e64 v162, v245, v162, s[98:99]
	v_mov_b32_dpp v244, v163 quad_perm:[1,0,3,2] row_mask:0xf bank_mask:0xf
	v_mov_b32_dpp v245, v243 quad_perm:[1,0,3,2] row_mask:0xf bank_mask:0xf
	v_cndmask_b32_e64 v243, v243, v244, s[98:99]
	v_cndmask_b32_e64 v163, v245, v163, s[98:99]
	v_lshl_add_u64 v[246:247], v[144:145], 0, s[100:101]
	global_store_dwordx4 v[144:145], v[240:243], off nt
	global_store_dwordx4 v[246:247], v[160:163], off nt
	v_mov_b64_e32 v[144:145], s[56:57]
	v_mad_i64_i32 v[158:159], s[2:3], v158, s69, v[144:145]
	v_lshl_add_u64 v[162:163], v[158:159], 0, v[64:65]
	v_pk_mul_f32 v[158:159], v[52:53], s[0:1] op_sel_hi:[1,0]
	v_pk_mul_f32 v[160:161], v[54:55], s[0:1] op_sel_hi:[1,0]
	v_pk_mul_f32 v[170:171], v[48:49], s[0:1] op_sel_hi:[1,0]
	v_pk_mul_f32 v[172:173], v[50:51], s[0:1] op_sel_hi:[1,0]
	v_cvt_pk_bf16_f32 v158, v158, v159
	v_cvt_pk_bf16_f32 v159, v160, v161
	v_cvt_pk_bf16_f32 v160, v170, v171
	v_cvt_pk_bf16_f32 v161, v172, v173
	v_mov_b32_e32 v240, v158
	v_mov_b32_e32 v241, v159
	v_mov_b32_e32 v242, v160
	v_mov_b32_e32 v243, v161
	v_pk_mul_f32 v[170:171], v[114:115], s[0:1] op_sel_hi:[1,0]
	v_pk_mul_f32 v[172:173], v[116:117], s[0:1] op_sel_hi:[1,0]
	v_pk_mul_f32 v[158:159], v[118:119], s[0:1] op_sel_hi:[1,0]
	v_pk_mul_f32 v[160:161], v[120:121], s[0:1] op_sel_hi:[1,0]
	v_cvt_pk_bf16_f32 v158, v158, v159
	v_cvt_pk_bf16_f32 v159, v160, v161
	v_cvt_pk_bf16_f32 v160, v170, v171
	v_cvt_pk_bf16_f32 v161, v172, v173
	s_nop 1
	v_mov_b32_dpp v244, v158 quad_perm:[1,0,3,2] row_mask:0xf bank_mask:0xf
	v_mov_b32_dpp v245, v240 quad_perm:[1,0,3,2] row_mask:0xf bank_mask:0xf
	v_cndmask_b32_e64 v240, v240, v244, s[98:99]
	v_cndmask_b32_e64 v158, v245, v158, s[98:99]
	v_mov_b32_dpp v244, v159 quad_perm:[1,0,3,2] row_mask:0xf bank_mask:0xf
	v_mov_b32_dpp v245, v241 quad_perm:[1,0,3,2] row_mask:0xf bank_mask:0xf
	v_cndmask_b32_e64 v241, v241, v244, s[98:99]
	v_cndmask_b32_e64 v159, v245, v159, s[98:99]
	v_mov_b32_dpp v244, v160 quad_perm:[1,0,3,2] row_mask:0xf bank_mask:0xf
	v_mov_b32_dpp v245, v242 quad_perm:[1,0,3,2] row_mask:0xf bank_mask:0xf
	v_cndmask_b32_e64 v242, v242, v244, s[98:99]
	v_cndmask_b32_e64 v160, v245, v160, s[98:99]
	v_mov_b32_dpp v244, v161 quad_perm:[1,0,3,2] row_mask:0xf bank_mask:0xf
	v_mov_b32_dpp v245, v243 quad_perm:[1,0,3,2] row_mask:0xf bank_mask:0xf
	v_cndmask_b32_e64 v243, v243, v244, s[98:99]
	v_cndmask_b32_e64 v161, v245, v161, s[98:99]
	v_lshl_add_u64 v[246:247], v[162:163], 0, s[100:101]
	global_store_dwordx4 v[162:163], v[240:243], off nt
	global_store_dwordx4 v[246:247], v[158:161], off nt
	v_pk_mul_f32 v[170:171], v[40:41], s[0:1] op_sel_hi:[1,0]
	v_pk_mul_f32 v[172:173], v[42:43], s[0:1] op_sel_hi:[1,0]
	v_mad_i64_i32 v[158:159], s[2:3], v157, s69, v[144:145]
	v_lshl_add_u64 v[162:163], v[158:159], 0, v[64:65]
	v_pk_mul_f32 v[158:159], v[44:45], s[0:1] op_sel_hi:[1,0]
	v_pk_mul_f32 v[160:161], v[46:47], s[0:1] op_sel_hi:[1,0]
	v_cvt_pk_bf16_f32 v158, v158, v159
	v_cvt_pk_bf16_f32 v159, v160, v161
	v_cvt_pk_bf16_f32 v160, v170, v171
	v_cvt_pk_bf16_f32 v161, v172, v173
	v_mov_b32_e32 v240, v158
	v_mov_b32_e32 v241, v159
	v_mov_b32_e32 v242, v160
	v_mov_b32_e32 v243, v161
	v_pk_mul_f32 v[170:171], v[106:107], s[0:1] op_sel_hi:[1,0]
	v_pk_mul_f32 v[172:173], v[108:109], s[0:1] op_sel_hi:[1,0]
	v_pk_mul_f32 v[158:159], v[110:111], s[0:1] op_sel_hi:[1,0]
	v_pk_mul_f32 v[160:161], v[112:113], s[0:1] op_sel_hi:[1,0]
	v_cvt_pk_bf16_f32 v158, v158, v159
	v_cvt_pk_bf16_f32 v159, v160, v161
	v_cvt_pk_bf16_f32 v160, v170, v171
	v_cvt_pk_bf16_f32 v161, v172, v173
	v_mad_i64_i32 v[156:157], s[2:3], v156, s69, v[144:145]
	s_nop 1
	v_mov_b32_dpp v244, v158 quad_perm:[1,0,3,2] row_mask:0xf bank_mask:0xf
	v_mov_b32_dpp v245, v240 quad_perm:[1,0,3,2] row_mask:0xf bank_mask:0xf
	v_cndmask_b32_e64 v240, v240, v244, s[98:99]
	v_cndmask_b32_e64 v158, v245, v158, s[98:99]
	v_mov_b32_dpp v244, v159 quad_perm:[1,0,3,2] row_mask:0xf bank_mask:0xf
	v_mov_b32_dpp v245, v241 quad_perm:[1,0,3,2] row_mask:0xf bank_mask:0xf
	v_cndmask_b32_e64 v241, v241, v244, s[98:99]
	v_cndmask_b32_e64 v159, v245, v159, s[98:99]
	v_mov_b32_dpp v244, v160 quad_perm:[1,0,3,2] row_mask:0xf bank_mask:0xf
	v_mov_b32_dpp v245, v242 quad_perm:[1,0,3,2] row_mask:0xf bank_mask:0xf
	v_cndmask_b32_e64 v242, v242, v244, s[98:99]
	v_cndmask_b32_e64 v160, v245, v160, s[98:99]
	v_mov_b32_dpp v244, v161 quad_perm:[1,0,3,2] row_mask:0xf bank_mask:0xf
	v_mov_b32_dpp v245, v243 quad_perm:[1,0,3,2] row_mask:0xf bank_mask:0xf
	v_cndmask_b32_e64 v243, v243, v244, s[98:99]
	v_cndmask_b32_e64 v161, v245, v161, s[98:99]
	v_lshl_add_u64 v[246:247], v[162:163], 0, s[100:101]
	global_store_dwordx4 v[162:163], v[240:243], off nt
	global_store_dwordx4 v[246:247], v[158:161], off nt
	v_pk_mul_f32 v[162:163], v[32:33], s[0:1] op_sel_hi:[1,0]
	v_pk_mul_f32 v[170:171], v[34:35], s[0:1] op_sel_hi:[1,0]
	v_lshl_add_u64 v[160:161], v[156:157], 0, v[64:65]
	v_pk_mul_f32 v[156:157], v[36:37], s[0:1] op_sel_hi:[1,0]
	v_pk_mul_f32 v[158:159], v[38:39], s[0:1] op_sel_hi:[1,0]
	v_cvt_pk_bf16_f32 v156, v156, v157
	v_cvt_pk_bf16_f32 v157, v158, v159
	v_cvt_pk_bf16_f32 v158, v162, v163
	v_cvt_pk_bf16_f32 v159, v170, v171
	v_mov_b32_e32 v240, v156
	v_mov_b32_e32 v241, v157
	v_mov_b32_e32 v242, v158
	v_mov_b32_e32 v243, v159
	v_pk_mul_f32 v[162:163], v[98:99], s[0:1] op_sel_hi:[1,0]
	v_pk_mul_f32 v[170:171], v[100:101], s[0:1] op_sel_hi:[1,0]
	v_pk_mul_f32 v[156:157], v[102:103], s[0:1] op_sel_hi:[1,0]
	v_pk_mul_f32 v[158:159], v[104:105], s[0:1] op_sel_hi:[1,0]
	v_cvt_pk_bf16_f32 v156, v156, v157
	v_cvt_pk_bf16_f32 v157, v158, v159
	v_cvt_pk_bf16_f32 v158, v162, v163
	v_cvt_pk_bf16_f32 v159, v170, v171
	s_nop 1
	v_mov_b32_dpp v244, v156 quad_perm:[1,0,3,2] row_mask:0xf bank_mask:0xf
	v_mov_b32_dpp v245, v240 quad_perm:[1,0,3,2] row_mask:0xf bank_mask:0xf
	v_cndmask_b32_e64 v240, v240, v244, s[98:99]
	v_cndmask_b32_e64 v156, v245, v156, s[98:99]
	v_mov_b32_dpp v244, v157 quad_perm:[1,0,3,2] row_mask:0xf bank_mask:0xf
	v_mov_b32_dpp v245, v241 quad_perm:[1,0,3,2] row_mask:0xf bank_mask:0xf
	v_cndmask_b32_e64 v241, v241, v244, s[98:99]
	v_cndmask_b32_e64 v157, v245, v157, s[98:99]
	v_mov_b32_dpp v244, v158 quad_perm:[1,0,3,2] row_mask:0xf bank_mask:0xf
	v_mov_b32_dpp v245, v242 quad_perm:[1,0,3,2] row_mask:0xf bank_mask:0xf
	v_cndmask_b32_e64 v242, v242, v244, s[98:99]
	v_cndmask_b32_e64 v158, v245, v158, s[98:99]
	v_mov_b32_dpp v244, v159 quad_perm:[1,0,3,2] row_mask:0xf bank_mask:0xf
	v_mov_b32_dpp v245, v243 quad_perm:[1,0,3,2] row_mask:0xf bank_mask:0xf
	v_cndmask_b32_e64 v243, v243, v244, s[98:99]
	v_cndmask_b32_e64 v159, v245, v159, s[98:99]
	v_lshl_add_u64 v[246:247], v[160:161], 0, s[100:101]
	global_store_dwordx4 v[160:161], v[240:243], off nt
	global_store_dwordx4 v[246:247], v[156:159], off nt
	v_pk_mul_f32 v[162:163], v[24:25], s[0:1] op_sel_hi:[1,0]
	v_pk_mul_f32 v[170:171], v[26:27], s[0:1] op_sel_hi:[1,0]
	v_mad_i64_i32 v[156:157], s[2:3], v155, s69, v[144:145]
	v_lshl_add_u64 v[160:161], v[156:157], 0, v[64:65]
	v_pk_mul_f32 v[156:157], v[28:29], s[0:1] op_sel_hi:[1,0]
	v_pk_mul_f32 v[158:159], v[30:31], s[0:1] op_sel_hi:[1,0]
	v_cvt_pk_bf16_f32 v156, v156, v157
	v_cvt_pk_bf16_f32 v157, v158, v159
	v_cvt_pk_bf16_f32 v158, v162, v163
	v_cvt_pk_bf16_f32 v159, v170, v171
	v_mov_b32_e32 v240, v156
	v_mov_b32_e32 v241, v157
	v_mov_b32_e32 v242, v158
	v_mov_b32_e32 v243, v159
	v_pk_mul_f32 v[162:163], v[90:91], s[0:1] op_sel_hi:[1,0]
	v_pk_mul_f32 v[170:171], v[92:93], s[0:1] op_sel_hi:[1,0]
	v_pk_mul_f32 v[156:157], v[94:95], s[0:1] op_sel_hi:[1,0]
	v_pk_mul_f32 v[158:159], v[96:97], s[0:1] op_sel_hi:[1,0]
	v_cvt_pk_bf16_f32 v156, v156, v157
	v_cvt_pk_bf16_f32 v157, v158, v159
	v_cvt_pk_bf16_f32 v158, v162, v163
	v_cvt_pk_bf16_f32 v159, v170, v171
	v_mad_i64_i32 v[154:155], s[2:3], v154, s69, v[144:145]
	s_nop 1
	v_mov_b32_dpp v244, v156 quad_perm:[1,0,3,2] row_mask:0xf bank_mask:0xf
	v_mov_b32_dpp v245, v240 quad_perm:[1,0,3,2] row_mask:0xf bank_mask:0xf
	v_cndmask_b32_e64 v240, v240, v244, s[98:99]
	v_cndmask_b32_e64 v156, v245, v156, s[98:99]
	v_mov_b32_dpp v244, v157 quad_perm:[1,0,3,2] row_mask:0xf bank_mask:0xf
	v_mov_b32_dpp v245, v241 quad_perm:[1,0,3,2] row_mask:0xf bank_mask:0xf
	v_cndmask_b32_e64 v241, v241, v244, s[98:99]
	v_cndmask_b32_e64 v157, v245, v157, s[98:99]
	v_mov_b32_dpp v244, v158 quad_perm:[1,0,3,2] row_mask:0xf bank_mask:0xf
	v_mov_b32_dpp v245, v242 quad_perm:[1,0,3,2] row_mask:0xf bank_mask:0xf
	v_cndmask_b32_e64 v242, v242, v244, s[98:99]
	v_cndmask_b32_e64 v158, v245, v158, s[98:99]
	v_mov_b32_dpp v244, v159 quad_perm:[1,0,3,2] row_mask:0xf bank_mask:0xf
	v_mov_b32_dpp v245, v243 quad_perm:[1,0,3,2] row_mask:0xf bank_mask:0xf
	v_cndmask_b32_e64 v243, v243, v244, s[98:99]
	v_cndmask_b32_e64 v159, v245, v159, s[98:99]
	v_lshl_add_u64 v[246:247], v[160:161], 0, s[100:101]
	global_store_dwordx4 v[160:161], v[240:243], off nt
	global_store_dwordx4 v[246:247], v[156:159], off nt
	v_pk_mul_f32 v[160:161], v[16:17], s[0:1] op_sel_hi:[1,0]
	v_pk_mul_f32 v[162:163], v[18:19], s[0:1] op_sel_hi:[1,0]
	v_lshl_add_u64 v[158:159], v[154:155], 0, v[64:65]
	v_pk_mul_f32 v[154:155], v[20:21], s[0:1] op_sel_hi:[1,0]
	v_pk_mul_f32 v[156:157], v[22:23], s[0:1] op_sel_hi:[1,0]
	v_cvt_pk_bf16_f32 v154, v154, v155
	v_cvt_pk_bf16_f32 v155, v156, v157
	v_cvt_pk_bf16_f32 v156, v160, v161
	v_cvt_pk_bf16_f32 v157, v162, v163
	v_mov_b32_e32 v240, v154
	v_mov_b32_e32 v241, v155
	v_mov_b32_e32 v242, v156
	v_mov_b32_e32 v243, v157
	v_pk_mul_f32 v[160:161], v[82:83], s[0:1] op_sel_hi:[1,0]
	v_pk_mul_f32 v[162:163], v[84:85], s[0:1] op_sel_hi:[1,0]
	v_pk_mul_f32 v[154:155], v[86:87], s[0:1] op_sel_hi:[1,0]
	v_pk_mul_f32 v[156:157], v[88:89], s[0:1] op_sel_hi:[1,0]
	v_cvt_pk_bf16_f32 v154, v154, v155
	v_cvt_pk_bf16_f32 v155, v156, v157
	v_cvt_pk_bf16_f32 v156, v160, v161
	v_cvt_pk_bf16_f32 v157, v162, v163
	s_nop 1
	v_mov_b32_dpp v244, v154 quad_perm:[1,0,3,2] row_mask:0xf bank_mask:0xf
	v_mov_b32_dpp v245, v240 quad_perm:[1,0,3,2] row_mask:0xf bank_mask:0xf
	v_cndmask_b32_e64 v240, v240, v244, s[98:99]
	v_cndmask_b32_e64 v154, v245, v154, s[98:99]
	v_mov_b32_dpp v244, v155 quad_perm:[1,0,3,2] row_mask:0xf bank_mask:0xf
	v_mov_b32_dpp v245, v241 quad_perm:[1,0,3,2] row_mask:0xf bank_mask:0xf
	v_cndmask_b32_e64 v241, v241, v244, s[98:99]
	v_cndmask_b32_e64 v155, v245, v155, s[98:99]
	v_mov_b32_dpp v244, v156 quad_perm:[1,0,3,2] row_mask:0xf bank_mask:0xf
	v_mov_b32_dpp v245, v242 quad_perm:[1,0,3,2] row_mask:0xf bank_mask:0xf
	v_cndmask_b32_e64 v242, v242, v244, s[98:99]
	v_cndmask_b32_e64 v156, v245, v156, s[98:99]
	v_mov_b32_dpp v244, v157 quad_perm:[1,0,3,2] row_mask:0xf bank_mask:0xf
	v_mov_b32_dpp v245, v243 quad_perm:[1,0,3,2] row_mask:0xf bank_mask:0xf
	v_cndmask_b32_e64 v243, v243, v244, s[98:99]
	v_cndmask_b32_e64 v157, v245, v157, s[98:99]
	v_lshl_add_u64 v[246:247], v[158:159], 0, s[100:101]
	global_store_dwordx4 v[158:159], v[240:243], off nt
	global_store_dwordx4 v[246:247], v[154:157], off nt
	v_pk_mul_f32 v[160:161], v[8:9], s[0:1] op_sel_hi:[1,0]
	v_pk_mul_f32 v[162:163], v[10:11], s[0:1] op_sel_hi:[1,0]
	v_mad_i64_i32 v[154:155], s[2:3], v147, s69, v[144:145]
	v_lshl_add_u64 v[158:159], v[154:155], 0, v[64:65]
	v_pk_mul_f32 v[154:155], v[12:13], s[0:1] op_sel_hi:[1,0]
	v_pk_mul_f32 v[156:157], v[14:15], s[0:1] op_sel_hi:[1,0]
	v_cvt_pk_bf16_f32 v154, v154, v155
	v_cvt_pk_bf16_f32 v155, v156, v157
	v_cvt_pk_bf16_f32 v156, v160, v161
	v_cvt_pk_bf16_f32 v157, v162, v163
	v_mov_b32_e32 v240, v154
	v_mov_b32_e32 v241, v155
	v_mov_b32_e32 v242, v156
	v_mov_b32_e32 v243, v157
	v_pk_mul_f32 v[160:161], v[74:75], s[0:1] op_sel_hi:[1,0]
	v_pk_mul_f32 v[162:163], v[76:77], s[0:1] op_sel_hi:[1,0]
	v_pk_mul_f32 v[154:155], v[78:79], s[0:1] op_sel_hi:[1,0]
	v_pk_mul_f32 v[156:157], v[80:81], s[0:1] op_sel_hi:[1,0]
	v_cvt_pk_bf16_f32 v154, v154, v155
	v_cvt_pk_bf16_f32 v155, v156, v157
	v_cvt_pk_bf16_f32 v156, v160, v161
	v_cvt_pk_bf16_f32 v157, v162, v163
	v_mad_i64_i32 v[144:145], s[2:3], v146, s69, v[144:145]
	s_nop 1
	v_mov_b32_dpp v244, v154 quad_perm:[1,0,3,2] row_mask:0xf bank_mask:0xf
	v_mov_b32_dpp v245, v240 quad_perm:[1,0,3,2] row_mask:0xf bank_mask:0xf
	v_cndmask_b32_e64 v240, v240, v244, s[98:99]
	v_cndmask_b32_e64 v154, v245, v154, s[98:99]
	v_mov_b32_dpp v244, v155 quad_perm:[1,0,3,2] row_mask:0xf bank_mask:0xf
	v_mov_b32_dpp v245, v241 quad_perm:[1,0,3,2] row_mask:0xf bank_mask:0xf
	v_cndmask_b32_e64 v241, v241, v244, s[98:99]
	v_cndmask_b32_e64 v155, v245, v155, s[98:99]
	v_mov_b32_dpp v244, v156 quad_perm:[1,0,3,2] row_mask:0xf bank_mask:0xf
	v_mov_b32_dpp v245, v242 quad_perm:[1,0,3,2] row_mask:0xf bank_mask:0xf
	v_cndmask_b32_e64 v242, v242, v244, s[98:99]
	v_cndmask_b32_e64 v156, v245, v156, s[98:99]
	v_mov_b32_dpp v244, v157 quad_perm:[1,0,3,2] row_mask:0xf bank_mask:0xf
	v_mov_b32_dpp v245, v243 quad_perm:[1,0,3,2] row_mask:0xf bank_mask:0xf
	v_cndmask_b32_e64 v243, v243, v244, s[98:99]
	v_cndmask_b32_e64 v157, v245, v157, s[98:99]
	v_lshl_add_u64 v[246:247], v[158:159], 0, s[100:101]
	global_store_dwordx4 v[158:159], v[240:243], off nt
	global_store_dwordx4 v[246:247], v[154:157], off nt
	v_pk_mul_f32 v[146:147], v[6:7], s[0:1] op_sel_hi:[1,0]
	v_pk_mul_f32 v[158:159], v[2:3], s[0:1] op_sel_hi:[1,0]
	v_lshl_add_u64 v[154:155], v[144:145], 0, v[64:65]
	v_pk_mul_f32 v[144:145], v[4:5], s[0:1] op_sel_hi:[1,0]
	v_pk_mul_f32 v[156:157], v[0:1], s[0:1] op_sel_hi:[1,0]
	v_cvt_pk_bf16_f32 v144, v144, v145
	v_cvt_pk_bf16_f32 v145, v146, v147
	v_cvt_pk_bf16_f32 v146, v156, v157
	v_cvt_pk_bf16_f32 v147, v158, v159
	v_mov_b32_e32 v240, v144
	v_mov_b32_e32 v241, v145
	v_mov_b32_e32 v242, v146
	v_mov_b32_e32 v243, v147
	v_pk_mul_f32 v[156:157], v[66:67], s[0:1] op_sel_hi:[1,0]
	v_pk_mul_f32 v[158:159], v[68:69], s[0:1] op_sel_hi:[1,0]
	v_pk_mul_f32 v[144:145], v[70:71], s[0:1] op_sel_hi:[1,0]
	v_pk_mul_f32 v[146:147], v[72:73], s[0:1] op_sel_hi:[1,0]
	v_cvt_pk_bf16_f32 v144, v144, v145
	v_cvt_pk_bf16_f32 v145, v146, v147
	v_cvt_pk_bf16_f32 v146, v156, v157
	v_cvt_pk_bf16_f32 v147, v158, v159
	s_nop 1
	v_mov_b32_dpp v244, v144 quad_perm:[1,0,3,2] row_mask:0xf bank_mask:0xf
	v_mov_b32_dpp v245, v240 quad_perm:[1,0,3,2] row_mask:0xf bank_mask:0xf
	v_cndmask_b32_e64 v240, v240, v244, s[98:99]
	v_cndmask_b32_e64 v144, v245, v144, s[98:99]
	v_mov_b32_dpp v244, v145 quad_perm:[1,0,3,2] row_mask:0xf bank_mask:0xf
	v_mov_b32_dpp v245, v241 quad_perm:[1,0,3,2] row_mask:0xf bank_mask:0xf
	v_cndmask_b32_e64 v241, v241, v244, s[98:99]
	v_cndmask_b32_e64 v145, v245, v145, s[98:99]
	v_mov_b32_dpp v244, v146 quad_perm:[1,0,3,2] row_mask:0xf bank_mask:0xf
	v_mov_b32_dpp v245, v242 quad_perm:[1,0,3,2] row_mask:0xf bank_mask:0xf
	v_cndmask_b32_e64 v242, v242, v244, s[98:99]
	v_cndmask_b32_e64 v146, v245, v146, s[98:99]
	v_mov_b32_dpp v244, v147 quad_perm:[1,0,3,2] row_mask:0xf bank_mask:0xf
	v_mov_b32_dpp v245, v243 quad_perm:[1,0,3,2] row_mask:0xf bank_mask:0xf
	v_cndmask_b32_e64 v243, v243, v244, s[98:99]
	v_cndmask_b32_e64 v147, v245, v147, s[98:99]
	v_lshl_add_u64 v[246:247], v[154:155], 0, s[100:101]
	global_store_dwordx4 v[154:155], v[240:243], off nt
	global_store_dwordx4 v[246:247], v[144:147], off nt

.LBB0_342:
	s_and_b64 vcc, exec, s[16:17]
	s_cbranch_vccz .LBB0_344
	v_mul_f32_e32 v147, 0xbfb8aa3b, v60
	v_exp_f32_e32 v147, v147
	v_mul_f32_e32 v152, 0xbfb8aa3b, v61
	v_exp_f32_e32 v152, v152
	v_lshl_add_u32 v146, s10, 8, v164
	v_mov_b64_e32 v[144:145], s[56:57]
	v_lshlrev_b32_e32 v64, 1, v168
	v_mad_i64_i32 v[154:155], s[2:3], v146, s69, v[144:145]
	v_lshl_or_b32 v64, s52, 9, v64
	v_add_f32_e32 v147, 1.0, v147
	v_lshl_add_u64 v[158:159], v[154:155], 0, v[64:65]
	v_rcp_f32_e32 v154, v147
	v_add_f32_e32 v147, 1.0, v152
	v_mul_f32_e32 v152, 0xbfb8aa3b, v62
	v_exp_f32_e32 v152, v152
	v_mul_f32_e32 v153, 0xbfb8aa3b, v63
	v_exp_f32_e32 v153, v153
	v_rcp_f32_e32 v155, v147
	v_add_f32_e32 v147, 1.0, v152
	v_mul_f32_e32 v152, 0xbfb8aa3b, v56
	v_rcp_f32_e32 v156, v147
	v_add_f32_e32 v147, 1.0, v153
	v_exp_f32_e32 v152, v152
	v_mul_f32_e32 v153, 0xbfb8aa3b, v57
	v_exp_f32_e32 v153, v153
	v_rcp_f32_e32 v157, v147
	v_add_f32_e32 v147, 1.0, v152
	v_mul_f32_e32 v152, 0xbfb8aa3b, v58
	v_rcp_f32_e32 v160, v147
	v_add_f32_e32 v147, 1.0, v153
	v_exp_f32_e32 v152, v152
	v_mul_f32_e32 v153, 0xbfb8aa3b, v59
	v_exp_f32_e32 v153, v153
	v_rcp_f32_e32 v161, v147
	v_add_f32_e32 v147, 1.0, v152
	v_rcp_f32_e32 v162, v147
	v_add_f32_e32 v147, 1.0, v153
	v_rcp_f32_e32 v163, v147
	v_mul_f32_e32 v147, 0xbfb8aa3b, v126
	v_exp_f32_e32 v147, v147
	v_mul_f32_e32 v152, 0xbfb8aa3b, v127
	v_exp_f32_e32 v152, v152
	v_pk_mul_f32 v[154:155], v[60:61], v[154:155]
	v_pk_mul_f32 v[156:157], v[62:63], v[156:157]
	v_pk_mul_f32 v[160:161], v[56:57], v[160:161]
	v_pk_mul_f32 v[162:163], v[58:59], v[162:163]
	v_cvt_pk_bf16_f32 v154, v154, v155
	v_cvt_pk_bf16_f32 v155, v156, v157
	v_cvt_pk_bf16_f32 v156, v160, v161
	v_cvt_pk_bf16_f32 v157, v162, v163
	v_add_f32_e32 v147, 1.0, v147
	v_mov_b32_e32 v240, v154
	v_mov_b32_e32 v241, v155
	v_mov_b32_e32 v242, v156
	v_mov_b32_e32 v243, v157
	v_mul_f32_e32 v153, 0xbfb8aa3b, v129
	v_exp_f32_e32 v153, v153
	v_rcp_f32_e32 v154, v147
	v_add_f32_e32 v147, 1.0, v152
	v_mul_f32_e32 v152, 0xbfb8aa3b, v128
	v_exp_f32_e32 v152, v152
	v_rcp_f32_e32 v155, v147
	v_add_f32_e32 v147, 1.0, v152
	v_mul_f32_e32 v152, 0xbfb8aa3b, v122
	v_rcp_f32_e32 v156, v147
	v_add_f32_e32 v147, 1.0, v153
	v_exp_f32_e32 v152, v152
	v_mul_f32_e32 v153, 0xbfb8aa3b, v123
	v_exp_f32_e32 v153, v153
	v_rcp_f32_e32 v157, v147
	v_add_f32_e32 v147, 1.0, v152
	v_mul_f32_e32 v152, 0xbfb8aa3b, v124
	v_rcp_f32_e32 v160, v147
	v_add_f32_e32 v147, 1.0, v153
	v_exp_f32_e32 v152, v152
	v_mul_f32_e32 v153, 0xbfb8aa3b, v125
	v_exp_f32_e32 v153, v153
	v_rcp_f32_e32 v161, v147
	v_add_f32_e32 v147, 1.0, v152
	v_rcp_f32_e32 v162, v147
	v_add_f32_e32 v147, 1.0, v153
	v_rcp_f32_e32 v163, v147
	v_pk_mul_f32 v[154:155], v[126:127], v[154:155]
	v_pk_mul_f32 v[156:157], v[128:129], v[156:157]
	v_pk_mul_f32 v[160:161], v[122:123], v[160:161]
	v_pk_mul_f32 v[162:163], v[124:125], v[162:163]
	v_cvt_pk_bf16_f32 v154, v154, v155
	v_cvt_pk_bf16_f32 v155, v156, v157
	v_cvt_pk_bf16_f32 v156, v160, v161
	v_cvt_pk_bf16_f32 v157, v162, v163
	v_or_b32_e32 v147, 16, v146
	s_nop 1
	v_mov_b32_dpp v244, v154 quad_perm:[1,0,3,2] row_mask:0xf bank_mask:0xf
	v_mov_b32_dpp v245, v240 quad_perm:[1,0,3,2] row_mask:0xf bank_mask:0xf
	v_cndmask_b32_e64 v240, v240, v244, s[98:99]
	v_cndmask_b32_e64 v154, v245, v154, s[98:99]
	v_mov_b32_dpp v244, v155 quad_perm:[1,0,3,2] row_mask:0xf bank_mask:0xf
	v_mov_b32_dpp v245, v241 quad_perm:[1,0,3,2] row_mask:0xf bank_mask:0xf
	v_cndmask_b32_e64 v241, v241, v244, s[98:99]
	v_cndmask_b32_e64 v155, v245, v155, s[98:99]
	v_mov_b32_dpp v244, v156 quad_perm:[1,0,3,2] row_mask:0xf bank_mask:0xf
	v_mov_b32_dpp v245, v242 quad_perm:[1,0,3,2] row_mask:0xf bank_mask:0xf
	v_cndmask_b32_e64 v242, v242, v244, s[98:99]
	v_cndmask_b32_e64 v156, v245, v156, s[98:99]
	v_mov_b32_dpp v244, v157 quad_perm:[1,0,3,2] row_mask:0xf bank_mask:0xf
	v_mov_b32_dpp v245, v243 quad_perm:[1,0,3,2] row_mask:0xf bank_mask:0xf
	v_cndmask_b32_e64 v243, v243, v244, s[98:99]
	v_cndmask_b32_e64 v157, v245, v157, s[98:99]
	v_lshl_add_u64 v[246:247], v[158:159], 0, s[100:101]
	global_store_dwordx4 v[158:159], v[240:243], off nt
	global_store_dwordx4 v[246:247], v[154:157], off nt
	v_mul_f32_e32 v152, 0xbfb8aa3b, v53
	v_exp_f32_e32 v152, v152
	v_mad_i64_i32 v[154:155], s[2:3], v147, s69, v[144:145]
	v_mul_f32_e32 v147, 0xbfb8aa3b, v52
	v_exp_f32_e32 v147, v147
	v_lshl_add_u64 v[158:159], v[154:155], 0, v[64:65]
	v_mul_f32_e32 v153, 0xbfb8aa3b, v55
	v_exp_f32_e32 v153, v153
	v_add_f32_e32 v147, 1.0, v147
	v_rcp_f32_e32 v154, v147
	v_add_f32_e32 v147, 1.0, v152
	v_mul_f32_e32 v152, 0xbfb8aa3b, v54
	v_exp_f32_e32 v152, v152
	v_rcp_f32_e32 v155, v147
	v_add_f32_e32 v147, 1.0, v152
	v_mul_f32_e32 v152, 0xbfb8aa3b, v48
	v_rcp_f32_e32 v156, v147
	v_add_f32_e32 v147, 1.0, v153
	v_exp_f32_e32 v152, v152
	v_mul_f32_e32 v153, 0xbfb8aa3b, v49
	v_exp_f32_e32 v153, v153
	v_rcp_f32_e32 v157, v147
	v_add_f32_e32 v147, 1.0, v152
	v_mul_f32_e32 v152, 0xbfb8aa3b, v50
	v_rcp_f32_e32 v160, v147
	v_add_f32_e32 v147, 1.0, v153
	v_exp_f32_e32 v152, v152
	v_mul_f32_e32 v153, 0xbfb8aa3b, v51
	v_exp_f32_e32 v153, v153
	v_rcp_f32_e32 v161, v147
	v_add_f32_e32 v147, 1.0, v152
	v_rcp_f32_e32 v162, v147
	v_add_f32_e32 v147, 1.0, v153
	v_rcp_f32_e32 v163, v147
	v_mul_f32_e32 v147, 0xbfb8aa3b, v118
	v_exp_f32_e32 v147, v147
	v_mul_f32_e32 v152, 0xbfb8aa3b, v119
	v_exp_f32_e32 v152, v152
	v_pk_mul_f32 v[154:155], v[52:53], v[154:155]
	v_pk_mul_f32 v[156:157], v[54:55], v[156:157]
	v_pk_mul_f32 v[160:161], v[48:49], v[160:161]
	v_pk_mul_f32 v[162:163], v[50:51], v[162:163]
	v_cvt_pk_bf16_f32 v154, v154, v155
	v_cvt_pk_bf16_f32 v155, v156, v157
	v_cvt_pk_bf16_f32 v156, v160, v161
	v_cvt_pk_bf16_f32 v157, v162, v163
	v_add_f32_e32 v147, 1.0, v147
	v_mov_b32_e32 v240, v154
	v_mov_b32_e32 v241, v155
	v_mov_b32_e32 v242, v156
	v_mov_b32_e32 v243, v157
	v_mul_f32_e32 v153, 0xbfb8aa3b, v121
	v_exp_f32_e32 v153, v153
	v_rcp_f32_e32 v154, v147
	v_add_f32_e32 v147, 1.0, v152
	v_mul_f32_e32 v152, 0xbfb8aa3b, v120
	v_exp_f32_e32 v152, v152
	v_rcp_f32_e32 v155, v147
	v_add_f32_e32 v147, 1.0, v152
	v_mul_f32_e32 v152, 0xbfb8aa3b, v114
	v_rcp_f32_e32 v156, v147
	v_add_f32_e32 v147, 1.0, v153
	v_exp_f32_e32 v152, v152
	v_mul_f32_e32 v153, 0xbfb8aa3b, v115
	v_exp_f32_e32 v153, v153
	v_rcp_f32_e32 v157, v147
	v_add_f32_e32 v147, 1.0, v152
	v_mul_f32_e32 v152, 0xbfb8aa3b, v116
	v_rcp_f32_e32 v160, v147
	v_add_f32_e32 v147, 1.0, v153
	v_exp_f32_e32 v152, v152
	v_mul_f32_e32 v153, 0xbfb8aa3b, v117
	v_exp_f32_e32 v153, v153
	v_rcp_f32_e32 v161, v147
	v_add_f32_e32 v147, 1.0, v152
	v_rcp_f32_e32 v162, v147
	v_add_f32_e32 v147, 1.0, v153
	v_rcp_f32_e32 v163, v147
	v_pk_mul_f32 v[154:155], v[118:119], v[154:155]
	v_pk_mul_f32 v[156:157], v[120:121], v[156:157]
	v_pk_mul_f32 v[160:161], v[114:115], v[160:161]
	v_pk_mul_f32 v[162:163], v[116:117], v[162:163]
	v_cvt_pk_bf16_f32 v154, v154, v155
	v_cvt_pk_bf16_f32 v155, v156, v157
	v_cvt_pk_bf16_f32 v156, v160, v161
	v_cvt_pk_bf16_f32 v157, v162, v163
	v_or_b32_e32 v147, 32, v146
	s_nop 1
	v_mov_b32_dpp v244, v154 quad_perm:[1,0,3,2] row_mask:0xf bank_mask:0xf
	v_mov_b32_dpp v245, v240 quad_perm:[1,0,3,2] row_mask:0xf bank_mask:0xf
	v_cndmask_b32_e64 v240, v240, v244, s[98:99]
	v_cndmask_b32_e64 v154, v245, v154, s[98:99]
	v_mov_b32_dpp v244, v155 quad_perm:[1,0,3,2] row_mask:0xf bank_mask:0xf
	v_mov_b32_dpp v245, v241 quad_perm:[1,0,3,2] row_mask:0xf bank_mask:0xf
	v_cndmask_b32_e64 v241, v241, v244, s[98:99]
	v_cndmask_b32_e64 v155, v245, v155, s[98:99]
	v_mov_b32_dpp v244, v156 quad_perm:[1,0,3,2] row_mask:0xf bank_mask:0xf
	v_mov_b32_dpp v245, v242 quad_perm:[1,0,3,2] row_mask:0xf bank_mask:0xf
	v_cndmask_b32_e64 v242, v242, v244, s[98:99]
	v_cndmask_b32_e64 v156, v245, v156, s[98:99]
	v_mov_b32_dpp v244, v157 quad_perm:[1,0,3,2] row_mask:0xf bank_mask:0xf
	v_mov_b32_dpp v245, v243 quad_perm:[1,0,3,2] row_mask:0xf bank_mask:0xf
	v_cndmask_b32_e64 v243, v243, v244, s[98:99]
	v_cndmask_b32_e64 v157, v245, v157, s[98:99]
	v_lshl_add_u64 v[246:247], v[158:159], 0, s[100:101]
	global_store_dwordx4 v[158:159], v[240:243], off nt
	global_store_dwordx4 v[246:247], v[154:157], off nt
	v_mul_f32_e32 v152, 0xbfb8aa3b, v45
	v_exp_f32_e32 v152, v152
	v_mad_i64_i32 v[154:155], s[2:3], v147, s69, v[144:145]
	v_mul_f32_e32 v147, 0xbfb8aa3b, v44
	v_exp_f32_e32 v147, v147
	v_lshl_add_u64 v[158:159], v[154:155], 0, v[64:65]
	v_mul_f32_e32 v153, 0xbfb8aa3b, v47
	v_exp_f32_e32 v153, v153
	v_add_f32_e32 v147, 1.0, v147
	v_rcp_f32_e32 v154, v147
	v_add_f32_e32 v147, 1.0, v152
	v_mul_f32_e32 v152, 0xbfb8aa3b, v46
	v_exp_f32_e32 v152, v152
	v_rcp_f32_e32 v155, v147
	v_add_f32_e32 v147, 1.0, v152
	v_mul_f32_e32 v152, 0xbfb8aa3b, v40
	v_rcp_f32_e32 v156, v147
	v_add_f32_e32 v147, 1.0, v153
	v_exp_f32_e32 v152, v152
	v_mul_f32_e32 v153, 0xbfb8aa3b, v41
	v_exp_f32_e32 v153, v153
	v_rcp_f32_e32 v157, v147
	v_add_f32_e32 v147, 1.0, v152
	v_mul_f32_e32 v152, 0xbfb8aa3b, v42
	v_rcp_f32_e32 v160, v147
	v_add_f32_e32 v147, 1.0, v153
	v_exp_f32_e32 v152, v152
	v_mul_f32_e32 v153, 0xbfb8aa3b, v43
	v_exp_f32_e32 v153, v153
	v_rcp_f32_e32 v161, v147
	v_add_f32_e32 v147, 1.0, v152
	v_rcp_f32_e32 v162, v147
	v_add_f32_e32 v147, 1.0, v153
	v_rcp_f32_e32 v163, v147
	v_mul_f32_e32 v147, 0xbfb8aa3b, v110
	v_exp_f32_e32 v147, v147
	v_mul_f32_e32 v152, 0xbfb8aa3b, v111
	v_exp_f32_e32 v152, v152
	v_pk_mul_f32 v[154:155], v[44:45], v[154:155]
	v_pk_mul_f32 v[156:157], v[46:47], v[156:157]
	v_pk_mul_f32 v[160:161], v[40:41], v[160:161]
	v_pk_mul_f32 v[162:163], v[42:43], v[162:163]
	v_cvt_pk_bf16_f32 v154, v154, v155
	v_cvt_pk_bf16_f32 v155, v156, v157
	v_cvt_pk_bf16_f32 v156, v160, v161
	v_cvt_pk_bf16_f32 v157, v162, v163
	v_add_f32_e32 v147, 1.0, v147
	v_mov_b32_e32 v240, v154
	v_mov_b32_e32 v241, v155
	v_mov_b32_e32 v242, v156
	v_mov_b32_e32 v243, v157
	v_mul_f32_e32 v153, 0xbfb8aa3b, v113
	v_exp_f32_e32 v153, v153
	v_rcp_f32_e32 v154, v147
	v_add_f32_e32 v147, 1.0, v152
	v_mul_f32_e32 v152, 0xbfb8aa3b, v112
	v_exp_f32_e32 v152, v152
	v_rcp_f32_e32 v155, v147
	v_add_f32_e32 v147, 1.0, v152
	v_mul_f32_e32 v152, 0xbfb8aa3b, v106
	v_rcp_f32_e32 v156, v147
	v_add_f32_e32 v147, 1.0, v153
	v_exp_f32_e32 v152, v152
	v_mul_f32_e32 v153, 0xbfb8aa3b, v107
	v_exp_f32_e32 v153, v153
	v_rcp_f32_e32 v157, v147
	v_add_f32_e32 v147, 1.0, v152
	v_mul_f32_e32 v152, 0xbfb8aa3b, v108
	v_rcp_f32_e32 v160, v147
	v_add_f32_e32 v147, 1.0, v153
	v_exp_f32_e32 v152, v152
	v_mul_f32_e32 v153, 0xbfb8aa3b, v109
	v_exp_f32_e32 v153, v153
	v_rcp_f32_e32 v161, v147
	v_add_f32_e32 v147, 1.0, v152
	v_rcp_f32_e32 v162, v147
	v_add_f32_e32 v147, 1.0, v153
	v_rcp_f32_e32 v163, v147
	v_pk_mul_f32 v[154:155], v[110:111], v[154:155]
	v_pk_mul_f32 v[156:157], v[112:113], v[156:157]
	v_pk_mul_f32 v[160:161], v[106:107], v[160:161]
	v_pk_mul_f32 v[162:163], v[108:109], v[162:163]
	v_cvt_pk_bf16_f32 v154, v154, v155
	v_cvt_pk_bf16_f32 v155, v156, v157
	v_cvt_pk_bf16_f32 v156, v160, v161
	v_cvt_pk_bf16_f32 v157, v162, v163
	v_or_b32_e32 v147, 48, v146
	s_nop 1
	v_mov_b32_dpp v244, v154 quad_perm:[1,0,3,2] row_mask:0xf bank_mask:0xf
	v_mov_b32_dpp v245, v240 quad_perm:[1,0,3,2] row_mask:0xf bank_mask:0xf
	v_cndmask_b32_e64 v240, v240, v244, s[98:99]
	v_cndmask_b32_e64 v154, v245, v154, s[98:99]
	v_mov_b32_dpp v244, v155 quad_perm:[1,0,3,2] row_mask:0xf bank_mask:0xf
	v_mov_b32_dpp v245, v241 quad_perm:[1,0,3,2] row_mask:0xf bank_mask:0xf
	v_cndmask_b32_e64 v241, v241, v244, s[98:99]
	v_cndmask_b32_e64 v155, v245, v155, s[98:99]
	v_mov_b32_dpp v244, v156 quad_perm:[1,0,3,2] row_mask:0xf bank_mask:0xf
	v_mov_b32_dpp v245, v242 quad_perm:[1,0,3,2] row_mask:0xf bank_mask:0xf
	v_cndmask_b32_e64 v242, v242, v244, s[98:99]
	v_cndmask_b32_e64 v156, v245, v156, s[98:99]
	v_mov_b32_dpp v244, v157 quad_perm:[1,0,3,2] row_mask:0xf bank_mask:0xf
	v_mov_b32_dpp v245, v243 quad_perm:[1,0,3,2] row_mask:0xf bank_mask:0xf
	v_cndmask_b32_e64 v243, v243, v244, s[98:99]
	v_cndmask_b32_e64 v157, v245, v157, s[98:99]
	v_lshl_add_u64 v[246:247], v[158:159], 0, s[100:101]
	global_store_dwordx4 v[158:159], v[240:243], off nt
	global_store_dwordx4 v[246:247], v[154:157], off nt
	v_mul_f32_e32 v152, 0xbfb8aa3b, v37
	v_exp_f32_e32 v152, v152
	v_mad_i64_i32 v[154:155], s[2:3], v147, s69, v[144:145]
	v_mul_f32_e32 v147, 0xbfb8aa3b, v36
	v_exp_f32_e32 v147, v147
	v_lshl_add_u64 v[158:159], v[154:155], 0, v[64:65]
	v_mul_f32_e32 v153, 0xbfb8aa3b, v39
	v_exp_f32_e32 v153, v153
	v_add_f32_e32 v147, 1.0, v147
	v_rcp_f32_e32 v154, v147
	v_add_f32_e32 v147, 1.0, v152
	v_mul_f32_e32 v152, 0xbfb8aa3b, v38
	v_exp_f32_e32 v152, v152
	v_rcp_f32_e32 v155, v147
	v_add_f32_e32 v147, 1.0, v152
	v_mul_f32_e32 v152, 0xbfb8aa3b, v32
	v_rcp_f32_e32 v156, v147
	v_add_f32_e32 v147, 1.0, v153
	v_exp_f32_e32 v152, v152
	v_mul_f32_e32 v153, 0xbfb8aa3b, v33
	v_exp_f32_e32 v153, v153
	v_rcp_f32_e32 v157, v147
	v_add_f32_e32 v147, 1.0, v152
	v_mul_f32_e32 v152, 0xbfb8aa3b, v34
	v_rcp_f32_e32 v160, v147
	v_add_f32_e32 v147, 1.0, v153
	v_exp_f32_e32 v152, v152
	v_mul_f32_e32 v153, 0xbfb8aa3b, v35
	v_exp_f32_e32 v153, v153
	v_rcp_f32_e32 v161, v147
	v_add_f32_e32 v147, 1.0, v152
	v_rcp_f32_e32 v162, v147
	v_add_f32_e32 v147, 1.0, v153
	v_rcp_f32_e32 v163, v147
	v_mul_f32_e32 v147, 0xbfb8aa3b, v102
	v_exp_f32_e32 v147, v147
	v_mul_f32_e32 v152, 0xbfb8aa3b, v103
	v_exp_f32_e32 v152, v152
	v_pk_mul_f32 v[154:155], v[36:37], v[154:155]
	v_pk_mul_f32 v[156:157], v[38:39], v[156:157]
	v_pk_mul_f32 v[160:161], v[32:33], v[160:161]
	v_pk_mul_f32 v[162:163], v[34:35], v[162:163]
	v_cvt_pk_bf16_f32 v154, v154, v155
	v_cvt_pk_bf16_f32 v155, v156, v157
	v_cvt_pk_bf16_f32 v156, v160, v161
	v_cvt_pk_bf16_f32 v157, v162, v163
	v_add_f32_e32 v147, 1.0, v147
	v_mov_b32_e32 v240, v154
	v_mov_b32_e32 v241, v155
	v_mov_b32_e32 v242, v156
	v_mov_b32_e32 v243, v157
	v_mul_f32_e32 v153, 0xbfb8aa3b, v105
	v_exp_f32_e32 v153, v153
	v_rcp_f32_e32 v154, v147
	v_add_f32_e32 v147, 1.0, v152
	v_mul_f32_e32 v152, 0xbfb8aa3b, v104
	v_exp_f32_e32 v152, v152
	v_rcp_f32_e32 v155, v147
	v_add_f32_e32 v147, 1.0, v152
	v_mul_f32_e32 v152, 0xbfb8aa3b, v98
	v_rcp_f32_e32 v156, v147
	v_add_f32_e32 v147, 1.0, v153
	v_exp_f32_e32 v152, v152
	v_mul_f32_e32 v153, 0xbfb8aa3b, v99
	v_exp_f32_e32 v153, v153
	v_rcp_f32_e32 v157, v147
	v_add_f32_e32 v147, 1.0, v152
	v_mul_f32_e32 v152, 0xbfb8aa3b, v100
	v_rcp_f32_e32 v160, v147
	v_add_f32_e32 v147, 1.0, v153
	v_exp_f32_e32 v152, v152
	v_mul_f32_e32 v153, 0xbfb8aa3b, v101
	v_exp_f32_e32 v153, v153
	v_rcp_f32_e32 v161, v147
	v_add_f32_e32 v147, 1.0, v152
	v_rcp_f32_e32 v162, v147
	v_add_f32_e32 v147, 1.0, v153
	v_rcp_f32_e32 v163, v147
	v_pk_mul_f32 v[154:155], v[102:103], v[154:155]
	v_pk_mul_f32 v[156:157], v[104:105], v[156:157]
	v_pk_mul_f32 v[160:161], v[98:99], v[160:161]
	v_pk_mul_f32 v[162:163], v[100:101], v[162:163]
	v_cvt_pk_bf16_f32 v154, v154, v155
	v_cvt_pk_bf16_f32 v155, v156, v157
	v_cvt_pk_bf16_f32 v156, v160, v161
	v_cvt_pk_bf16_f32 v157, v162, v163
	v_add_u32_e32 v147, 0x80, v146
	s_nop 1
	v_mov_b32_dpp v244, v154 quad_perm:[1,0,3,2] row_mask:0xf bank_mask:0xf
	v_mov_b32_dpp v245, v240 quad_perm:[1,0,3,2] row_mask:0xf bank_mask:0xf
	v_cndmask_b32_e64 v240, v240, v244, s[98:99]
	v_cndmask_b32_e64 v154, v245, v154, s[98:99]
	v_mov_b32_dpp v244, v155 quad_perm:[1,0,3,2] row_mask:0xf bank_mask:0xf
	v_mov_b32_dpp v245, v241 quad_perm:[1,0,3,2] row_mask:0xf bank_mask:0xf
	v_cndmask_b32_e64 v241, v241, v244, s[98:99]
	v_cndmask_b32_e64 v155, v245, v155, s[98:99]
	v_mov_b32_dpp v244, v156 quad_perm:[1,0,3,2] row_mask:0xf bank_mask:0xf
	v_mov_b32_dpp v245, v242 quad_perm:[1,0,3,2] row_mask:0xf bank_mask:0xf
	v_cndmask_b32_e64 v242, v242, v244, s[98:99]
	v_cndmask_b32_e64 v156, v245, v156, s[98:99]
	v_mov_b32_dpp v244, v157 quad_perm:[1,0,3,2] row_mask:0xf bank_mask:0xf
	v_mov_b32_dpp v245, v243 quad_perm:[1,0,3,2] row_mask:0xf bank_mask:0xf
	v_cndmask_b32_e64 v243, v243, v244, s[98:99]
	v_cndmask_b32_e64 v157, v245, v157, s[98:99]
	v_lshl_add_u64 v[246:247], v[158:159], 0, s[100:101]
	global_store_dwordx4 v[158:159], v[240:243], off nt
	global_store_dwordx4 v[246:247], v[154:157], off nt
	v_mul_f32_e32 v152, 0xbfb8aa3b, v29
	v_exp_f32_e32 v152, v152
	v_mad_i64_i32 v[154:155], s[2:3], v147, s69, v[144:145]
	v_mul_f32_e32 v147, 0xbfb8aa3b, v28
	v_exp_f32_e32 v147, v147
	v_lshl_add_u64 v[158:159], v[154:155], 0, v[64:65]
	v_mul_f32_e32 v153, 0xbfb8aa3b, v31
	v_exp_f32_e32 v153, v153
	v_add_f32_e32 v147, 1.0, v147
	v_rcp_f32_e32 v154, v147
	v_add_f32_e32 v147, 1.0, v152
	v_mul_f32_e32 v152, 0xbfb8aa3b, v30
	v_exp_f32_e32 v152, v152
	v_rcp_f32_e32 v155, v147
	v_add_f32_e32 v147, 1.0, v152
	v_mul_f32_e32 v152, 0xbfb8aa3b, v24
	v_rcp_f32_e32 v156, v147
	v_add_f32_e32 v147, 1.0, v153
	v_exp_f32_e32 v152, v152
	v_mul_f32_e32 v153, 0xbfb8aa3b, v25
	v_exp_f32_e32 v153, v153
	v_rcp_f32_e32 v157, v147
	v_add_f32_e32 v147, 1.0, v152
	v_mul_f32_e32 v152, 0xbfb8aa3b, v26
	v_rcp_f32_e32 v160, v147
	v_add_f32_e32 v147, 1.0, v153
	v_exp_f32_e32 v152, v152
	v_mul_f32_e32 v153, 0xbfb8aa3b, v27
	v_exp_f32_e32 v153, v153
	v_rcp_f32_e32 v161, v147
	v_add_f32_e32 v147, 1.0, v152
	v_rcp_f32_e32 v162, v147
	v_add_f32_e32 v147, 1.0, v153
	v_rcp_f32_e32 v163, v147
	v_mul_f32_e32 v147, 0xbfb8aa3b, v94
	v_exp_f32_e32 v147, v147
	v_mul_f32_e32 v152, 0xbfb8aa3b, v95
	v_exp_f32_e32 v152, v152
	v_pk_mul_f32 v[154:155], v[28:29], v[154:155]
	v_pk_mul_f32 v[156:157], v[30:31], v[156:157]
	v_pk_mul_f32 v[160:161], v[24:25], v[160:161]
	v_pk_mul_f32 v[162:163], v[26:27], v[162:163]
	v_cvt_pk_bf16_f32 v154, v154, v155
	v_cvt_pk_bf16_f32 v155, v156, v157
	v_cvt_pk_bf16_f32 v156, v160, v161
	v_cvt_pk_bf16_f32 v157, v162, v163
	v_add_f32_e32 v147, 1.0, v147
	v_mov_b32_e32 v240, v154
	v_mov_b32_e32 v241, v155
	v_mov_b32_e32 v242, v156
	v_mov_b32_e32 v243, v157
	v_mul_f32_e32 v153, 0xbfb8aa3b, v97
	v_exp_f32_e32 v153, v153
	v_rcp_f32_e32 v154, v147
	v_add_f32_e32 v147, 1.0, v152
	v_mul_f32_e32 v152, 0xbfb8aa3b, v96
	v_exp_f32_e32 v152, v152
	v_rcp_f32_e32 v155, v147
	v_add_f32_e32 v147, 1.0, v152
	v_mul_f32_e32 v152, 0xbfb8aa3b, v90
	v_rcp_f32_e32 v156, v147
	v_add_f32_e32 v147, 1.0, v153
	v_exp_f32_e32 v152, v152
	v_mul_f32_e32 v153, 0xbfb8aa3b, v91
	v_exp_f32_e32 v153, v153
	v_rcp_f32_e32 v157, v147
	v_add_f32_e32 v147, 1.0, v152
	v_mul_f32_e32 v152, 0xbfb8aa3b, v92
	v_rcp_f32_e32 v160, v147
	v_add_f32_e32 v147, 1.0, v153
	v_exp_f32_e32 v152, v152
	v_mul_f32_e32 v153, 0xbfb8aa3b, v93
	v_exp_f32_e32 v153, v153
	v_rcp_f32_e32 v161, v147
	v_add_f32_e32 v147, 1.0, v152
	v_rcp_f32_e32 v162, v147
	v_add_f32_e32 v147, 1.0, v153
	v_rcp_f32_e32 v163, v147
	v_pk_mul_f32 v[154:155], v[94:95], v[154:155]
	v_pk_mul_f32 v[156:157], v[96:97], v[156:157]
	v_pk_mul_f32 v[160:161], v[90:91], v[160:161]
	v_pk_mul_f32 v[162:163], v[92:93], v[162:163]
	v_cvt_pk_bf16_f32 v154, v154, v155
	v_cvt_pk_bf16_f32 v155, v156, v157
	v_cvt_pk_bf16_f32 v156, v160, v161
	v_cvt_pk_bf16_f32 v157, v162, v163
	v_add_u32_e32 v147, 0x90, v146
	s_nop 1
	v_mov_b32_dpp v244, v154 quad_perm:[1,0,3,2] row_mask:0xf bank_mask:0xf
	v_mov_b32_dpp v245, v240 quad_perm:[1,0,3,2] row_mask:0xf bank_mask:0xf
	v_cndmask_b32_e64 v240, v240, v244, s[98:99]
	v_cndmask_b32_e64 v154, v245, v154, s[98:99]
	v_mov_b32_dpp v244, v155 quad_perm:[1,0,3,2] row_mask:0xf bank_mask:0xf
	v_mov_b32_dpp v245, v241 quad_perm:[1,0,3,2] row_mask:0xf bank_mask:0xf
	v_cndmask_b32_e64 v241, v241, v244, s[98:99]
	v_cndmask_b32_e64 v155, v245, v155, s[98:99]
	v_mov_b32_dpp v244, v156 quad_perm:[1,0,3,2] row_mask:0xf bank_mask:0xf
	v_mov_b32_dpp v245, v242 quad_perm:[1,0,3,2] row_mask:0xf bank_mask:0xf
	v_cndmask_b32_e64 v242, v242, v244, s[98:99]
	v_cndmask_b32_e64 v156, v245, v156, s[98:99]
	v_mov_b32_dpp v244, v157 quad_perm:[1,0,3,2] row_mask:0xf bank_mask:0xf
	v_mov_b32_dpp v245, v243 quad_perm:[1,0,3,2] row_mask:0xf bank_mask:0xf
	v_cndmask_b32_e64 v243, v243, v244, s[98:99]
	v_cndmask_b32_e64 v157, v245, v157, s[98:99]
	v_lshl_add_u64 v[246:247], v[158:159], 0, s[100:101]
	global_store_dwordx4 v[158:159], v[240:243], off nt
	global_store_dwordx4 v[246:247], v[154:157], off nt
	v_mul_f32_e32 v152, 0xbfb8aa3b, v21
	v_exp_f32_e32 v152, v152
	v_mad_i64_i32 v[154:155], s[2:3], v147, s69, v[144:145]
	v_mul_f32_e32 v147, 0xbfb8aa3b, v20
	v_exp_f32_e32 v147, v147
	v_lshl_add_u64 v[158:159], v[154:155], 0, v[64:65]
	v_mul_f32_e32 v153, 0xbfb8aa3b, v23
	v_exp_f32_e32 v153, v153
	v_add_f32_e32 v147, 1.0, v147
	v_rcp_f32_e32 v154, v147
	v_add_f32_e32 v147, 1.0, v152
	v_mul_f32_e32 v152, 0xbfb8aa3b, v22
	v_exp_f32_e32 v152, v152
	v_rcp_f32_e32 v155, v147
	v_add_f32_e32 v147, 1.0, v152
	v_mul_f32_e32 v152, 0xbfb8aa3b, v16
	v_rcp_f32_e32 v156, v147
	v_add_f32_e32 v147, 1.0, v153
	v_exp_f32_e32 v152, v152
	v_mul_f32_e32 v153, 0xbfb8aa3b, v17
	v_exp_f32_e32 v153, v153
	v_rcp_f32_e32 v157, v147
	v_add_f32_e32 v147, 1.0, v152
	v_mul_f32_e32 v152, 0xbfb8aa3b, v18
	v_rcp_f32_e32 v160, v147
	v_add_f32_e32 v147, 1.0, v153
	v_exp_f32_e32 v152, v152
	v_mul_f32_e32 v153, 0xbfb8aa3b, v19
	v_exp_f32_e32 v153, v153
	v_rcp_f32_e32 v161, v147
	v_add_f32_e32 v147, 1.0, v152
	v_rcp_f32_e32 v162, v147
	v_add_f32_e32 v147, 1.0, v153
	v_rcp_f32_e32 v163, v147
	v_mul_f32_e32 v147, 0xbfb8aa3b, v86
	v_exp_f32_e32 v147, v147
	v_mul_f32_e32 v152, 0xbfb8aa3b, v87
	v_exp_f32_e32 v152, v152
	v_pk_mul_f32 v[154:155], v[20:21], v[154:155]
	v_pk_mul_f32 v[156:157], v[22:23], v[156:157]
	v_pk_mul_f32 v[160:161], v[16:17], v[160:161]
	v_pk_mul_f32 v[162:163], v[18:19], v[162:163]
	v_cvt_pk_bf16_f32 v154, v154, v155
	v_cvt_pk_bf16_f32 v155, v156, v157
	v_cvt_pk_bf16_f32 v156, v160, v161
	v_cvt_pk_bf16_f32 v157, v162, v163
	v_add_f32_e32 v147, 1.0, v147
	v_mov_b32_e32 v240, v154
	v_mov_b32_e32 v241, v155
	v_mov_b32_e32 v242, v156
	v_mov_b32_e32 v243, v157
	v_mul_f32_e32 v153, 0xbfb8aa3b, v89
	v_exp_f32_e32 v153, v153
	v_rcp_f32_e32 v154, v147
	v_add_f32_e32 v147, 1.0, v152
	v_mul_f32_e32 v152, 0xbfb8aa3b, v88
	v_exp_f32_e32 v152, v152
	v_rcp_f32_e32 v155, v147
	v_add_f32_e32 v147, 1.0, v152
	v_mul_f32_e32 v152, 0xbfb8aa3b, v82
	v_rcp_f32_e32 v156, v147
	v_add_f32_e32 v147, 1.0, v153
	v_exp_f32_e32 v152, v152
	v_mul_f32_e32 v153, 0xbfb8aa3b, v83
	v_exp_f32_e32 v153, v153
	v_rcp_f32_e32 v157, v147
	v_add_f32_e32 v147, 1.0, v152
	v_mul_f32_e32 v152, 0xbfb8aa3b, v84
	v_rcp_f32_e32 v160, v147
	v_add_f32_e32 v147, 1.0, v153
	v_exp_f32_e32 v152, v152
	v_mul_f32_e32 v153, 0xbfb8aa3b, v85
	v_exp_f32_e32 v153, v153
	v_rcp_f32_e32 v161, v147
	v_add_f32_e32 v147, 1.0, v152
	v_rcp_f32_e32 v162, v147
	v_add_f32_e32 v147, 1.0, v153
	v_rcp_f32_e32 v163, v147
	v_pk_mul_f32 v[154:155], v[86:87], v[154:155]
	v_pk_mul_f32 v[156:157], v[88:89], v[156:157]
	v_pk_mul_f32 v[160:161], v[82:83], v[160:161]
	v_pk_mul_f32 v[162:163], v[84:85], v[162:163]
	v_cvt_pk_bf16_f32 v154, v154, v155
	v_cvt_pk_bf16_f32 v155, v156, v157
	v_cvt_pk_bf16_f32 v156, v160, v161
	v_cvt_pk_bf16_f32 v157, v162, v163
	v_add_u32_e32 v147, 0xa0, v146
	s_nop 1
	v_mov_b32_dpp v244, v154 quad_perm:[1,0,3,2] row_mask:0xf bank_mask:0xf
	v_mov_b32_dpp v245, v240 quad_perm:[1,0,3,2] row_mask:0xf bank_mask:0xf
	v_cndmask_b32_e64 v240, v240, v244, s[98:99]
	v_cndmask_b32_e64 v154, v245, v154, s[98:99]
	v_mov_b32_dpp v244, v155 quad_perm:[1,0,3,2] row_mask:0xf bank_mask:0xf
	v_mov_b32_dpp v245, v241 quad_perm:[1,0,3,2] row_mask:0xf bank_mask:0xf
	v_cndmask_b32_e64 v241, v241, v244, s[98:99]
	v_cndmask_b32_e64 v155, v245, v155, s[98:99]
	v_mov_b32_dpp v244, v156 quad_perm:[1,0,3,2] row_mask:0xf bank_mask:0xf
	v_mov_b32_dpp v245, v242 quad_perm:[1,0,3,2] row_mask:0xf bank_mask:0xf
	v_cndmask_b32_e64 v242, v242, v244, s[98:99]
	v_cndmask_b32_e64 v156, v245, v156, s[98:99]
	v_mov_b32_dpp v244, v157 quad_perm:[1,0,3,2] row_mask:0xf bank_mask:0xf
	v_mov_b32_dpp v245, v243 quad_perm:[1,0,3,2] row_mask:0xf bank_mask:0xf
	v_cndmask_b32_e64 v243, v243, v244, s[98:99]
	v_cndmask_b32_e64 v157, v245, v157, s[98:99]
	v_lshl_add_u64 v[246:247], v[158:159], 0, s[100:101]
	global_store_dwordx4 v[158:159], v[240:243], off nt
	global_store_dwordx4 v[246:247], v[154:157], off nt
	v_mul_f32_e32 v152, 0xbfb8aa3b, v13
	v_exp_f32_e32 v152, v152
	v_mad_i64_i32 v[154:155], s[2:3], v147, s69, v[144:145]
	v_mul_f32_e32 v147, 0xbfb8aa3b, v12
	v_exp_f32_e32 v147, v147
	v_lshl_add_u64 v[158:159], v[154:155], 0, v[64:65]
	v_mul_f32_e32 v153, 0xbfb8aa3b, v15
	v_exp_f32_e32 v153, v153
	v_add_f32_e32 v147, 1.0, v147
	v_rcp_f32_e32 v154, v147
	v_add_f32_e32 v147, 1.0, v152
	v_mul_f32_e32 v152, 0xbfb8aa3b, v14
	v_exp_f32_e32 v152, v152
	v_rcp_f32_e32 v155, v147
	v_add_u32_e32 v146, 0xb0, v146
	v_mad_i64_i32 v[144:145], s[2:3], v146, s69, v[144:145]
	v_add_f32_e32 v147, 1.0, v152
	v_mul_f32_e32 v152, 0xbfb8aa3b, v8
	v_rcp_f32_e32 v156, v147
	v_add_f32_e32 v147, 1.0, v153
	v_exp_f32_e32 v152, v152
	v_mul_f32_e32 v153, 0xbfb8aa3b, v9
	v_exp_f32_e32 v153, v153
	v_rcp_f32_e32 v157, v147
	v_add_f32_e32 v147, 1.0, v152
	v_mul_f32_e32 v152, 0xbfb8aa3b, v10
	v_rcp_f32_e32 v160, v147
	v_add_f32_e32 v147, 1.0, v153
	v_exp_f32_e32 v152, v152
	v_mul_f32_e32 v153, 0xbfb8aa3b, v11
	v_exp_f32_e32 v153, v153
	v_rcp_f32_e32 v161, v147
	v_add_f32_e32 v147, 1.0, v152
	v_rcp_f32_e32 v162, v147
	v_add_f32_e32 v147, 1.0, v153
	v_rcp_f32_e32 v163, v147
	v_mul_f32_e32 v147, 0xbfb8aa3b, v78
	v_exp_f32_e32 v147, v147
	v_mul_f32_e32 v152, 0xbfb8aa3b, v79
	v_exp_f32_e32 v152, v152
	v_pk_mul_f32 v[154:155], v[12:13], v[154:155]
	v_pk_mul_f32 v[156:157], v[14:15], v[156:157]
	v_pk_mul_f32 v[160:161], v[8:9], v[160:161]
	v_pk_mul_f32 v[162:163], v[10:11], v[162:163]
	v_cvt_pk_bf16_f32 v154, v154, v155
	v_cvt_pk_bf16_f32 v155, v156, v157
	v_cvt_pk_bf16_f32 v156, v160, v161
	v_cvt_pk_bf16_f32 v157, v162, v163
	v_add_f32_e32 v147, 1.0, v147
	v_mov_b32_e32 v240, v154
	v_mov_b32_e32 v241, v155
	v_mov_b32_e32 v242, v156
	v_mov_b32_e32 v243, v157
	v_mul_f32_e32 v153, 0xbfb8aa3b, v81
	v_exp_f32_e32 v153, v153
	v_rcp_f32_e32 v154, v147
	v_add_f32_e32 v147, 1.0, v152
	v_mul_f32_e32 v152, 0xbfb8aa3b, v80
	v_exp_f32_e32 v152, v152
	v_rcp_f32_e32 v155, v147
	v_mul_f32_e32 v146, 0xbfb8aa3b, v4
	v_exp_f32_e32 v146, v146
	v_add_f32_e32 v147, 1.0, v152
	v_mul_f32_e32 v152, 0xbfb8aa3b, v74
	v_rcp_f32_e32 v156, v147
	v_add_f32_e32 v147, 1.0, v153
	v_exp_f32_e32 v152, v152
	v_mul_f32_e32 v153, 0xbfb8aa3b, v75
	v_exp_f32_e32 v153, v153
	v_rcp_f32_e32 v157, v147
	v_add_f32_e32 v147, 1.0, v152
	v_mul_f32_e32 v152, 0xbfb8aa3b, v76
	v_rcp_f32_e32 v160, v147
	v_add_f32_e32 v147, 1.0, v153
	v_exp_f32_e32 v152, v152
	v_mul_f32_e32 v153, 0xbfb8aa3b, v77
	v_exp_f32_e32 v153, v153
	v_rcp_f32_e32 v161, v147
	v_add_f32_e32 v147, 1.0, v152
	v_rcp_f32_e32 v162, v147
	v_add_f32_e32 v147, 1.0, v153
	v_rcp_f32_e32 v163, v147
	v_mul_f32_e32 v147, 0xbfb8aa3b, v5
	v_pk_mul_f32 v[154:155], v[78:79], v[154:155]
	v_pk_mul_f32 v[156:157], v[80:81], v[156:157]
	v_pk_mul_f32 v[160:161], v[74:75], v[160:161]
	v_pk_mul_f32 v[162:163], v[76:77], v[162:163]
	v_exp_f32_e32 v147, v147
	v_cvt_pk_bf16_f32 v154, v154, v155
	v_cvt_pk_bf16_f32 v155, v156, v157
	v_cvt_pk_bf16_f32 v156, v160, v161
	v_cvt_pk_bf16_f32 v157, v162, v163
	s_nop 1
	v_mov_b32_dpp v244, v154 quad_perm:[1,0,3,2] row_mask:0xf bank_mask:0xf
	v_mov_b32_dpp v245, v240 quad_perm:[1,0,3,2] row_mask:0xf bank_mask:0xf
	v_cndmask_b32_e64 v240, v240, v244, s[98:99]
	v_cndmask_b32_e64 v154, v245, v154, s[98:99]
	v_mov_b32_dpp v244, v155 quad_perm:[1,0,3,2] row_mask:0xf bank_mask:0xf
	v_mov_b32_dpp v245, v241 quad_perm:[1,0,3,2] row_mask:0xf bank_mask:0xf
	v_cndmask_b32_e64 v241, v241, v244, s[98:99]
	v_cndmask_b32_e64 v155, v245, v155, s[98:99]
	v_mov_b32_dpp v244, v156 quad_perm:[1,0,3,2] row_mask:0xf bank_mask:0xf
	v_mov_b32_dpp v245, v242 quad_perm:[1,0,3,2] row_mask:0xf bank_mask:0xf
	v_cndmask_b32_e64 v242, v242, v244, s[98:99]
	v_cndmask_b32_e64 v156, v245, v156, s[98:99]
	v_mov_b32_dpp v244, v157 quad_perm:[1,0,3,2] row_mask:0xf bank_mask:0xf
	v_mov_b32_dpp v245, v243 quad_perm:[1,0,3,2] row_mask:0xf bank_mask:0xf
	v_cndmask_b32_e64 v243, v243, v244, s[98:99]
	v_cndmask_b32_e64 v157, v245, v157, s[98:99]
	v_lshl_add_u64 v[246:247], v[158:159], 0, s[100:101]
	global_store_dwordx4 v[158:159], v[240:243], off nt
	global_store_dwordx4 v[246:247], v[154:157], off nt
	s_nop 1
	v_lshl_add_u64 v[154:155], v[144:145], 0, v[64:65]
	v_mul_f32_e32 v145, 0xbfb8aa3b, v6
	v_add_f32_e32 v64, 1.0, v146
	v_exp_f32_e32 v146, v145
	v_mul_f32_e32 v145, 0xbfb8aa3b, v7
	v_rcp_f32_e32 v144, v64
	v_add_f32_e32 v64, 1.0, v147
	v_exp_f32_e32 v147, v145
	v_rcp_f32_e32 v145, v64
	v_add_f32_e32 v64, 1.0, v146
	v_rcp_f32_e32 v146, v64
	v_add_f32_e32 v64, 1.0, v147
	v_mul_f32_e32 v147, 0xbfb8aa3b, v0
	v_exp_f32_e32 v152, v147
	v_mul_f32_e32 v147, 0xbfb8aa3b, v1
	v_exp_f32_e32 v153, v147
	v_rcp_f32_e32 v147, v64
	v_add_f32_e32 v64, 1.0, v152
	v_mul_f32_e32 v152, 0xbfb8aa3b, v2
	v_rcp_f32_e32 v156, v64
	v_add_f32_e32 v64, 1.0, v153
	v_exp_f32_e32 v152, v152
	v_mul_f32_e32 v153, 0xbfb8aa3b, v3
	v_exp_f32_e32 v153, v153
	v_rcp_f32_e32 v157, v64
	v_add_f32_e32 v64, 1.0, v152
	v_rcp_f32_e32 v158, v64
	v_add_f32_e32 v64, 1.0, v153
	v_rcp_f32_e32 v159, v64
	v_pk_mul_f32 v[144:145], v[4:5], v[144:145]
	v_pk_mul_f32 v[146:147], v[6:7], v[146:147]
	v_pk_mul_f32 v[156:157], v[0:1], v[156:157]
	v_pk_mul_f32 v[158:159], v[2:3], v[158:159]
	v_mul_f32_e32 v64, 0xbfb8aa3b, v70
	v_cvt_pk_bf16_f32 v144, v144, v145
	v_cvt_pk_bf16_f32 v145, v146, v147
	v_cvt_pk_bf16_f32 v146, v156, v157
	v_cvt_pk_bf16_f32 v147, v158, v159
	v_exp_f32_e32 v64, v64
	v_mul_f32_e32 v152, 0xbfb8aa3b, v71
	v_exp_f32_e32 v152, v152
	v_mov_b32_e32 v240, v144
	v_mov_b32_e32 v241, v145
	v_mov_b32_e32 v242, v146
	v_mov_b32_e32 v243, v147
	v_add_f32_e32 v64, 1.0, v64
	s_nop 0
	v_mul_f32_e32 v145, 0xbfb8aa3b, v72
	v_exp_f32_e32 v146, v145
	v_mul_f32_e32 v145, 0xbfb8aa3b, v73
	v_exp_f32_e32 v147, v145
	v_rcp_f32_e32 v144, v64
	v_add_f32_e32 v64, 1.0, v152
	v_rcp_f32_e32 v145, v64
	v_add_f32_e32 v64, 1.0, v146
	v_rcp_f32_e32 v146, v64
	v_add_f32_e32 v64, 1.0, v147
	v_mul_f32_e32 v147, 0xbfb8aa3b, v66
	v_exp_f32_e32 v152, v147
	v_mul_f32_e32 v147, 0xbfb8aa3b, v67
	v_exp_f32_e32 v153, v147
	v_rcp_f32_e32 v147, v64
	v_add_f32_e32 v64, 1.0, v152
	v_mul_f32_e32 v152, 0xbfb8aa3b, v68
	v_rcp_f32_e32 v156, v64
	v_add_f32_e32 v64, 1.0, v153
	v_exp_f32_e32 v152, v152
	v_mul_f32_e32 v153, 0xbfb8aa3b, v69
	v_exp_f32_e32 v153, v153
	v_rcp_f32_e32 v157, v64
	v_add_f32_e32 v64, 1.0, v152
	v_rcp_f32_e32 v158, v64
	v_add_f32_e32 v64, 1.0, v153
	v_rcp_f32_e32 v159, v64
	v_pk_mul_f32 v[144:145], v[70:71], v[144:145]
	v_pk_mul_f32 v[146:147], v[72:73], v[146:147]
	v_pk_mul_f32 v[156:157], v[66:67], v[156:157]
	v_pk_mul_f32 v[158:159], v[68:69], v[158:159]
	v_cvt_pk_bf16_f32 v144, v144, v145
	v_cvt_pk_bf16_f32 v145, v146, v147
	v_cvt_pk_bf16_f32 v146, v156, v157
	v_cvt_pk_bf16_f32 v147, v158, v159
	s_nop 1
	v_mov_b32_dpp v244, v144 quad_perm:[1,0,3,2] row_mask:0xf bank_mask:0xf
	v_mov_b32_dpp v245, v240 quad_perm:[1,0,3,2] row_mask:0xf bank_mask:0xf
	v_cndmask_b32_e64 v240, v240, v244, s[98:99]
	v_cndmask_b32_e64 v144, v245, v144, s[98:99]
	v_mov_b32_dpp v244, v145 quad_perm:[1,0,3,2] row_mask:0xf bank_mask:0xf
	v_mov_b32_dpp v245, v241 quad_perm:[1,0,3,2] row_mask:0xf bank_mask:0xf
	v_cndmask_b32_e64 v241, v241, v244, s[98:99]
	v_cndmask_b32_e64 v145, v245, v145, s[98:99]
	v_mov_b32_dpp v244, v146 quad_perm:[1,0,3,2] row_mask:0xf bank_mask:0xf
	v_mov_b32_dpp v245, v242 quad_perm:[1,0,3,2] row_mask:0xf bank_mask:0xf
	v_cndmask_b32_e64 v242, v242, v244, s[98:99]
	v_cndmask_b32_e64 v146, v245, v146, s[98:99]
	v_mov_b32_dpp v244, v147 quad_perm:[1,0,3,2] row_mask:0xf bank_mask:0xf
	v_mov_b32_dpp v245, v243 quad_perm:[1,0,3,2] row_mask:0xf bank_mask:0xf
	v_cndmask_b32_e64 v243, v243, v244, s[98:99]
	v_cndmask_b32_e64 v147, v245, v147, s[98:99]
	v_lshl_add_u64 v[246:247], v[154:155], 0, s[100:101]
	global_store_dwordx4 v[154:155], v[240:243], off nt
	global_store_dwordx4 v[246:247], v[144:147], off nt

.LBB0_345:
	s_andn2_b64 vcc, exec, s[16:17]
	s_cbranch_vccnz .LBB0_378
	v_mul_f32_e32 v64, 0x3d372713, v60
	v_mul_f32_e32 v64, v60, v64
	v_fma_f32 v64, v60, v64, v60
	v_mul_f32_e32 v64, 0x3fcc422a, v64
	v_mul_f32_e32 v64, 0xbfb8aa3b, v64
	v_exp_f32_e32 v64, v64
	v_lshl_or_b32 v144, s52, 8, v168
	v_lshl_add_u32 v146, s10, 8, v164
	v_mov_b64_e32 v[154:155], s[56:57]
	v_add_f32_e32 v64, 1.0, v64
	v_rcp_f32_e32 v156, v64
	v_mul_f32_e32 v64, 0x3d372713, v61
	v_mul_f32_e32 v64, v61, v64
	v_fma_f32 v64, v61, v64, v61
	v_mul_f32_e32 v64, 0x3fcc422a, v64
	v_mul_f32_e32 v64, 0xbfb8aa3b, v64
	v_exp_f32_e32 v64, v64
	v_ashrrev_i32_e32 v145, 31, v144
	v_mad_i64_i32 v[154:155], s[2:3], v146, s69, v[154:155]
	v_add_f32_e32 v64, 1.0, v64
	v_rcp_f32_e32 v157, v64
	v_mul_f32_e32 v64, 0x3d372713, v62
	v_mul_f32_e32 v64, v62, v64
	v_fma_f32 v64, v62, v64, v62
	v_mul_f32_e32 v64, 0x3fcc422a, v64
	v_mul_f32_e32 v64, 0xbfb8aa3b, v64
	v_exp_f32_e32 v64, v64
	v_pk_mul_f32 v[156:157], v[60:61], v[156:157]
	v_lshl_add_u64 v[154:155], v[144:145], 1, v[154:155]
	v_cvt_pk_bf16_f32 v170, v156, v157
	v_add_f32_e32 v64, 1.0, v64
	v_rcp_f32_e32 v158, v64
	v_mul_f32_e32 v64, 0x3d372713, v63
	v_mul_f32_e32 v64, v63, v64
	v_fma_f32 v64, v63, v64, v63
	v_mul_f32_e32 v64, 0x3fcc422a, v64
	v_mul_f32_e32 v64, 0xbfb8aa3b, v64
	v_exp_f32_e32 v64, v64
	s_cmp_gt_i32 s52, 7
	s_cselect_b64 s[16:17], -1, 0
	s_cmp_lt_i32 s52, 8
	v_add_f32_e32 v64, 1.0, v64
	v_rcp_f32_e32 v159, v64
	v_mul_f32_e32 v64, 0x3d372713, v56
	v_mul_f32_e32 v64, v56, v64
	v_fma_f32 v64, v56, v64, v56
	v_mul_f32_e32 v64, 0x3fcc422a, v64
	v_mul_f32_e32 v64, 0xbfb8aa3b, v64
	v_exp_f32_e32 v64, v64
	v_pk_mul_f32 v[158:159], v[62:63], v[158:159]
	v_ashrrev_i32_e32 v147, 31, v146
	v_cvt_pk_bf16_f32 v171, v158, v159
	v_add_f32_e32 v64, 1.0, v64
	v_rcp_f32_e32 v160, v64
	v_mul_f32_e32 v64, 0x3d372713, v57
	v_mul_f32_e32 v64, v57, v64
	v_fma_f32 v64, v57, v64, v57
	v_mul_f32_e32 v64, 0x3fcc422a, v64
	v_mul_f32_e32 v64, 0xbfb8aa3b, v64
	v_exp_f32_e32 v64, v64
	s_nop 0
	v_add_f32_e32 v64, 1.0, v64
	v_rcp_f32_e32 v161, v64
	v_mul_f32_e32 v64, 0x3d372713, v58
	v_mul_f32_e32 v64, v58, v64
	v_fma_f32 v64, v58, v64, v58
	v_mul_f32_e32 v64, 0x3fcc422a, v64
	v_mul_f32_e32 v64, 0xbfb8aa3b, v64
	v_exp_f32_e32 v64, v64
	v_pk_mul_f32 v[160:161], v[56:57], v[160:161]
	v_add_f32_e32 v64, 1.0, v64
	v_rcp_f32_e32 v162, v64
	v_mul_f32_e32 v64, 0x3d372713, v59
	v_mul_f32_e32 v64, v59, v64
	v_fma_f32 v64, v59, v64, v59
	v_mul_f32_e32 v64, 0x3fcc422a, v64
	v_mul_f32_e32 v64, 0xbfb8aa3b, v64
	v_exp_f32_e32 v64, v64
	v_cvt_pk_bf16_f32 v172, v160, v161
	v_add_f32_e32 v64, 1.0, v64
	v_rcp_f32_e32 v163, v64
	v_mul_f32_e32 v64, 0x3d372713, v126
	v_mul_f32_e32 v64, v126, v64
	v_fma_f32 v64, v126, v64, v126
	v_mul_f32_e32 v64, 0x3fcc422a, v64
	v_mul_f32_e32 v64, 0xbfb8aa3b, v64
	v_exp_f32_e32 v64, v64
	v_pk_mul_f32 v[162:163], v[58:59], v[162:163]
	v_add_f32_e32 v64, 1.0, v64
	v_cvt_pk_bf16_f32 v173, v162, v163
	v_mov_b32_e32 v240, v170
	v_mov_b32_e32 v241, v171
	v_mov_b32_e32 v242, v172
	v_mov_b32_e32 v243, v173
	s_nop 1
	v_rcp_f32_e32 v170, v64
	v_mul_f32_e32 v64, 0x3d372713, v127
	v_mul_f32_e32 v64, v127, v64
	v_fma_f32 v64, v127, v64, v127
	v_mul_f32_e32 v64, 0x3fcc422a, v64
	v_mul_f32_e32 v64, 0xbfb8aa3b, v64
	v_exp_f32_e32 v64, v64
	s_nop 0
	v_add_f32_e32 v64, 1.0, v64
	v_rcp_f32_e32 v171, v64
	v_mul_f32_e32 v64, 0x3d372713, v128
	v_mul_f32_e32 v64, v128, v64
	v_fma_f32 v64, v128, v64, v128
	v_mul_f32_e32 v64, 0x3fcc422a, v64
	v_mul_f32_e32 v64, 0xbfb8aa3b, v64
	v_exp_f32_e32 v64, v64
	v_pk_mul_f32 v[126:127], v[126:127], v[170:171]
	v_add_f32_e32 v64, 1.0, v64
	v_rcp_f32_e32 v170, v64
	v_mul_f32_e32 v64, 0x3d372713, v129
	v_mul_f32_e32 v64, v129, v64
	v_fma_f32 v64, v129, v64, v129
	v_mul_f32_e32 v64, 0x3fcc422a, v64
	v_mul_f32_e32 v64, 0xbfb8aa3b, v64
	v_exp_f32_e32 v64, v64
	s_nop 0
	v_add_f32_e32 v64, 1.0, v64
	v_rcp_f32_e32 v171, v64
	v_mul_f32_e32 v64, 0x3d372713, v122
	v_mul_f32_e32 v64, v122, v64
	v_fma_f32 v64, v122, v64, v122
	v_mul_f32_e32 v64, 0x3fcc422a, v64
	v_mul_f32_e32 v64, 0xbfb8aa3b, v64
	v_exp_f32_e32 v64, v64
	v_pk_mul_f32 v[128:129], v[128:129], v[170:171]
	v_add_f32_e32 v64, 1.0, v64
	v_rcp_f32_e32 v170, v64
	v_mul_f32_e32 v64, 0x3d372713, v123
	v_mul_f32_e32 v64, v123, v64
	v_fma_f32 v64, v123, v64, v123
	v_mul_f32_e32 v64, 0x3fcc422a, v64
	v_mul_f32_e32 v64, 0xbfb8aa3b, v64
	v_exp_f32_e32 v64, v64
	s_nop 0
	v_add_f32_e32 v64, 1.0, v64
	v_rcp_f32_e32 v171, v64
	v_mul_f32_e32 v64, 0x3d372713, v124
	v_mul_f32_e32 v64, v124, v64
	v_fma_f32 v64, v124, v64, v124
	v_mul_f32_e32 v64, 0x3fcc422a, v64
	v_mul_f32_e32 v64, 0xbfb8aa3b, v64
	v_exp_f32_e32 v64, v64
	v_pk_mul_f32 v[122:123], v[122:123], v[170:171]
	v_add_f32_e32 v64, 1.0, v64
	v_rcp_f32_e32 v170, v64
	v_mul_f32_e32 v64, 0x3d372713, v125
	v_mul_f32_e32 v64, v125, v64
	v_fma_f32 v64, v125, v64, v125
	v_mul_f32_e32 v64, 0x3fcc422a, v64
	v_mul_f32_e32 v64, 0xbfb8aa3b, v64
	v_exp_f32_e32 v64, v64
	v_cvt_pk_bf16_f32 v172, v122, v123
	v_add_f32_e32 v64, 1.0, v64
	v_rcp_f32_e32 v171, v64
	s_nop 0
	v_pk_mul_f32 v[124:125], v[124:125], v[170:171]
	v_cvt_pk_bf16_f32 v170, v126, v127
	v_cvt_pk_bf16_f32 v171, v128, v129
	v_cvt_pk_bf16_f32 v173, v124, v125
	s_nop 1
	v_mov_b32_dpp v244, v170 quad_perm:[1,0,3,2] row_mask:0xf bank_mask:0xf
	v_mov_b32_dpp v245, v240 quad_perm:[1,0,3,2] row_mask:0xf bank_mask:0xf
	v_cndmask_b32_e64 v240, v240, v244, s[98:99]
	v_cndmask_b32_e64 v170, v245, v170, s[98:99]
	v_mov_b32_dpp v244, v171 quad_perm:[1,0,3,2] row_mask:0xf bank_mask:0xf
	v_mov_b32_dpp v245, v241 quad_perm:[1,0,3,2] row_mask:0xf bank_mask:0xf
	v_cndmask_b32_e64 v241, v241, v244, s[98:99]
	v_cndmask_b32_e64 v171, v245, v171, s[98:99]
	v_mov_b32_dpp v244, v172 quad_perm:[1,0,3,2] row_mask:0xf bank_mask:0xf
	v_mov_b32_dpp v245, v242 quad_perm:[1,0,3,2] row_mask:0xf bank_mask:0xf
	v_cndmask_b32_e64 v242, v242, v244, s[98:99]
	v_cndmask_b32_e64 v172, v245, v172, s[98:99]
	v_mov_b32_dpp v244, v173 quad_perm:[1,0,3,2] row_mask:0xf bank_mask:0xf
	v_mov_b32_dpp v245, v243 quad_perm:[1,0,3,2] row_mask:0xf bank_mask:0xf
	v_cndmask_b32_e64 v243, v243, v244, s[98:99]
	v_cndmask_b32_e64 v173, v245, v173, s[98:99]
	v_lshl_add_u64 v[246:247], v[154:155], 0, s[100:101]
	global_store_dwordx4 v[154:155], v[240:243], off nt
	global_store_dwordx4 v[246:247], v[170:173], off nt
	s_cbranch_scc1 .LBB0_350
	s_nop 0
	v_mov_b32_e32 v170, v65
	v_mov_b32_e32 v171, v157
	v_pk_mul_f32 v[154:155], v[156:157], v[156:157]
	v_pk_add_f32 v[170:171], v[156:157], v[170:171]
	v_pk_mul_f32 v[172:173], v[158:159], v[158:159]
	v_mov_b32_e32 v171, v155
	v_pk_mov_b32 v[154:155], v[156:157], v[154:155] op_sel:[1,0]
	v_mov_b32_e32 v156, v158
	v_pk_add_f32 v[154:155], v[154:155], v[170:171]
	v_mov_b32_e32 v157, v172
	v_pk_mul_f32 v[174:175], v[160:161], v[160:161]
	v_pk_add_f32 v[154:155], v[156:157], v[154:155]
	v_mov_b32_e32 v172, v159
	v_pk_add_f32 v[154:155], v[172:173], v[154:155]
	v_mov_b32_e32 v156, v160
	v_mov_b32_e32 v157, v174
	v_pk_mul_f32 v[176:177], v[162:163], v[162:163]
	v_pk_add_f32 v[154:155], v[156:157], v[154:155]
	v_mov_b32_e32 v174, v161
	v_pk_add_f32 v[154:155], v[174:175], v[154:155]
	v_mov_b32_e32 v156, v162
	v_mov_b32_e32 v157, v176
	v_pk_mul_f32 v[178:179], v[126:127], v[126:127]
	v_pk_add_f32 v[154:155], v[156:157], v[154:155]
	v_mov_b32_e32 v176, v163
	v_pk_add_f32 v[154:155], v[176:177], v[154:155]
	v_mov_b32_e32 v156, v126
	v_mov_b32_e32 v157, v178
	v_pk_mul_f32 v[180:181], v[128:129], v[128:129]
	v_pk_add_f32 v[154:155], v[154:155], v[156:157]
	v_mov_b32_e32 v178, v127
	v_pk_add_f32 v[126:127], v[178:179], v[154:155]
	v_mov_b32_e32 v154, v128
	v_mov_b32_e32 v155, v180
	v_pk_mul_f32 v[192:193], v[122:123], v[122:123]
	v_pk_add_f32 v[126:127], v[154:155], v[126:127]
	v_mov_b32_e32 v180, v129
	v_pk_add_f32 v[126:127], v[180:181], v[126:127]
	v_mov_b32_e32 v128, v122
	v_mov_b32_e32 v129, v192
	v_pk_mul_f32 v[194:195], v[124:125], v[124:125]
	v_pk_add_f32 v[126:127], v[128:129], v[126:127]
	v_mov_b32_e32 v192, v123
	v_pk_add_f32 v[122:123], v[192:193], v[126:127]
	v_mov_b32_e32 v126, v124
	v_mov_b32_e32 v127, v194
	v_pk_add_f32 v[122:123], v[126:127], v[122:123]
	v_mov_b32_e32 v194, v125
	v_pk_add_f32 v[122:123], v[194:195], v[122:123]
	ds_bpermute_b32 v124, v166, v122
	ds_bpermute_b32 v125, v166, v123
	s_waitcnt lgkmcnt(0)
	v_pk_add_f32 v[122:123], v[122:123], v[124:125]
	ds_bpermute_b32 v124, v167, v122
	ds_bpermute_b32 v125, v167, v123
	s_and_saveexec_b64 s[18:19], s[76:77]
	s_cbranch_execz .LBB0_349
	s_lshl_b32 s0, s52, 2
	s_waitcnt lgkmcnt(0)
	v_pk_add_f32 v[122:123], v[122:123], v[124:125]
	v_lshlrev_b64 v[124:125], 5, v[146:147]
	v_and_b32_e32 v248, 1, v190
	v_lshl_or_b32 v124, v248, 5, v124
	s_sub_i32 s0, s0, 32
	v_lshl_add_u64 v[124:125], v[124:125], 0, s[0:1]
	v_or_b32_e32 v124, s63, v124
	v_lshl_add_u64 v[124:125], v[124:125], 3, s[72:73]
	global_store_dwordx2 v[124:125], v[122:123], off

.LBB0_350:
	v_mul_f32_e32 v64, 0x3d372713, v52
	v_mul_f32_e32 v64, v52, v64
	v_fma_f32 v64, v52, v64, v52
	v_mul_f32_e32 v64, 0x3fcc422a, v64
	v_mul_f32_e32 v64, 0xbfb8aa3b, v64
	v_exp_f32_e32 v64, v64
	v_or_b32_e32 v122, 16, v146
	s_waitcnt lgkmcnt(0)
	v_mov_b64_e32 v[124:125], s[56:57]
	v_mad_i64_i32 v[124:125], s[2:3], v122, s69, v[124:125]
	v_add_f32_e32 v64, 1.0, v64
	v_rcp_f32_e32 v126, v64
	v_mul_f32_e32 v64, 0x3d372713, v53
	v_mul_f32_e32 v64, v53, v64
	v_fma_f32 v64, v53, v64, v53
	v_mul_f32_e32 v64, 0x3fcc422a, v64
	v_mul_f32_e32 v64, 0xbfb8aa3b, v64
	v_exp_f32_e32 v64, v64
	v_lshl_add_u64 v[124:125], v[144:145], 1, v[124:125]
	s_andn2_b64 vcc, exec, s[16:17]
	v_add_f32_e32 v64, 1.0, v64
	v_rcp_f32_e32 v127, v64
	v_mul_f32_e32 v64, 0x3d372713, v54
	v_mul_f32_e32 v64, v54, v64
	v_fma_f32 v64, v54, v64, v54
	v_mul_f32_e32 v64, 0x3fcc422a, v64
	v_mul_f32_e32 v64, 0xbfb8aa3b, v64
	v_exp_f32_e32 v64, v64
	v_pk_mul_f32 v[126:127], v[52:53], v[126:127]
	v_add_f32_e32 v64, 1.0, v64
	v_rcp_f32_e32 v128, v64
	v_mul_f32_e32 v64, 0x3d372713, v55
	v_mul_f32_e32 v64, v55, v64
	v_fma_f32 v64, v55, v64, v55
	v_mul_f32_e32 v64, 0x3fcc422a, v64
	v_mul_f32_e32 v64, 0xbfb8aa3b, v64
	v_exp_f32_e32 v64, v64
	v_cvt_pk_bf16_f32 v158, v126, v127
	v_add_f32_e32 v64, 1.0, v64
	v_rcp_f32_e32 v129, v64
	v_mul_f32_e32 v64, 0x3d372713, v48
	v_mul_f32_e32 v64, v48, v64
	v_fma_f32 v64, v48, v64, v48
	v_mul_f32_e32 v64, 0x3fcc422a, v64
	v_mul_f32_e32 v64, 0xbfb8aa3b, v64
	v_exp_f32_e32 v64, v64
	v_pk_mul_f32 v[128:129], v[54:55], v[128:129]
	v_add_f32_e32 v64, 1.0, v64
	v_rcp_f32_e32 v154, v64
	v_mul_f32_e32 v64, 0x3d372713, v49
	v_mul_f32_e32 v64, v49, v64
	v_fma_f32 v64, v49, v64, v49
	v_mul_f32_e32 v64, 0x3fcc422a, v64
	v_mul_f32_e32 v64, 0xbfb8aa3b, v64
	v_exp_f32_e32 v64, v64
	v_cvt_pk_bf16_f32 v159, v128, v129
	v_add_f32_e32 v64, 1.0, v64
	v_rcp_f32_e32 v155, v64
	v_mul_f32_e32 v64, 0x3d372713, v50
	v_mul_f32_e32 v64, v50, v64
	v_fma_f32 v64, v50, v64, v50
	v_mul_f32_e32 v64, 0x3fcc422a, v64
	v_mul_f32_e32 v64, 0xbfb8aa3b, v64
	v_exp_f32_e32 v64, v64
	v_pk_mul_f32 v[154:155], v[48:49], v[154:155]
	v_add_f32_e32 v64, 1.0, v64
	v_rcp_f32_e32 v156, v64
	v_mul_f32_e32 v64, 0x3d372713, v51
	v_mul_f32_e32 v64, v51, v64
	v_fma_f32 v64, v51, v64, v51
	v_mul_f32_e32 v64, 0x3fcc422a, v64
	v_mul_f32_e32 v64, 0xbfb8aa3b, v64
	v_exp_f32_e32 v64, v64
	v_cvt_pk_bf16_f32 v160, v154, v155
	v_add_f32_e32 v64, 1.0, v64
	v_rcp_f32_e32 v157, v64
	v_mul_f32_e32 v64, 0x3d372713, v118
	v_mul_f32_e32 v64, v118, v64
	v_fma_f32 v64, v118, v64, v118
	v_mul_f32_e32 v64, 0x3fcc422a, v64
	v_mul_f32_e32 v64, 0xbfb8aa3b, v64
	v_exp_f32_e32 v64, v64
	v_pk_mul_f32 v[156:157], v[50:51], v[156:157]
	v_add_f32_e32 v64, 1.0, v64
	v_cvt_pk_bf16_f32 v161, v156, v157
	v_mov_b32_e32 v240, v158
	v_mov_b32_e32 v241, v159
	v_mov_b32_e32 v242, v160
	v_mov_b32_e32 v243, v161
	s_nop 1
	v_rcp_f32_e32 v158, v64
	v_mul_f32_e32 v64, 0x3d372713, v119
	v_mul_f32_e32 v64, v119, v64
	v_fma_f32 v64, v119, v64, v119
	v_mul_f32_e32 v64, 0x3fcc422a, v64
	v_mul_f32_e32 v64, 0xbfb8aa3b, v64
	v_exp_f32_e32 v64, v64
	s_nop 0
	v_add_f32_e32 v64, 1.0, v64
	v_rcp_f32_e32 v159, v64
	v_mul_f32_e32 v64, 0x3d372713, v120
	v_mul_f32_e32 v64, v120, v64
	v_fma_f32 v64, v120, v64, v120
	v_mul_f32_e32 v64, 0x3fcc422a, v64
	v_mul_f32_e32 v64, 0xbfb8aa3b, v64
	v_exp_f32_e32 v64, v64
	v_pk_mul_f32 v[118:119], v[118:119], v[158:159]
	v_add_f32_e32 v64, 1.0, v64
	v_rcp_f32_e32 v158, v64
	v_mul_f32_e32 v64, 0x3d372713, v121
	v_mul_f32_e32 v64, v121, v64
	v_fma_f32 v64, v121, v64, v121
	v_mul_f32_e32 v64, 0x3fcc422a, v64
	v_mul_f32_e32 v64, 0xbfb8aa3b, v64
	v_exp_f32_e32 v64, v64
	s_nop 0
	v_add_f32_e32 v64, 1.0, v64
	v_rcp_f32_e32 v159, v64
	v_mul_f32_e32 v64, 0x3d372713, v114
	v_mul_f32_e32 v64, v114, v64
	v_fma_f32 v64, v114, v64, v114
	v_mul_f32_e32 v64, 0x3fcc422a, v64
	v_mul_f32_e32 v64, 0xbfb8aa3b, v64
	v_exp_f32_e32 v64, v64
	v_pk_mul_f32 v[120:121], v[120:121], v[158:159]
	v_add_f32_e32 v64, 1.0, v64
	v_rcp_f32_e32 v158, v64
	v_mul_f32_e32 v64, 0x3d372713, v115
	v_mul_f32_e32 v64, v115, v64
	v_fma_f32 v64, v115, v64, v115
	v_mul_f32_e32 v64, 0x3fcc422a, v64
	v_mul_f32_e32 v64, 0xbfb8aa3b, v64
	v_exp_f32_e32 v64, v64
	s_nop 0
	v_add_f32_e32 v64, 1.0, v64
	v_rcp_f32_e32 v159, v64
	v_mul_f32_e32 v64, 0x3d372713, v116
	v_mul_f32_e32 v64, v116, v64
	v_fma_f32 v64, v116, v64, v116
	v_mul_f32_e32 v64, 0x3fcc422a, v64
	v_mul_f32_e32 v64, 0xbfb8aa3b, v64
	v_exp_f32_e32 v64, v64
	v_pk_mul_f32 v[114:115], v[114:115], v[158:159]
	v_add_f32_e32 v64, 1.0, v64
	v_rcp_f32_e32 v158, v64
	v_mul_f32_e32 v64, 0x3d372713, v117
	v_mul_f32_e32 v64, v117, v64
	v_fma_f32 v64, v117, v64, v117
	v_mul_f32_e32 v64, 0x3fcc422a, v64
	v_mul_f32_e32 v64, 0xbfb8aa3b, v64
	v_exp_f32_e32 v64, v64
	v_cvt_pk_bf16_f32 v160, v114, v115
	v_add_f32_e32 v64, 1.0, v64
	v_rcp_f32_e32 v159, v64
	v_cndmask_b32_e64 v64, 0, 1, s[16:17]
	v_cmp_ne_u32_e64 s[66:67], 1, v64
	v_pk_mul_f32 v[116:117], v[116:117], v[158:159]
	v_cvt_pk_bf16_f32 v158, v118, v119
	v_cvt_pk_bf16_f32 v159, v120, v121
	v_cvt_pk_bf16_f32 v161, v116, v117
	s_nop 1
	v_mov_b32_dpp v244, v158 quad_perm:[1,0,3,2] row_mask:0xf bank_mask:0xf
	v_mov_b32_dpp v245, v240 quad_perm:[1,0,3,2] row_mask:0xf bank_mask:0xf
	v_cndmask_b32_e64 v240, v240, v244, s[98:99]
	v_cndmask_b32_e64 v158, v245, v158, s[98:99]
	v_mov_b32_dpp v244, v159 quad_perm:[1,0,3,2] row_mask:0xf bank_mask:0xf
	v_mov_b32_dpp v245, v241 quad_perm:[1,0,3,2] row_mask:0xf bank_mask:0xf
	v_cndmask_b32_e64 v241, v241, v244, s[98:99]
	v_cndmask_b32_e64 v159, v245, v159, s[98:99]
	v_mov_b32_dpp v244, v160 quad_perm:[1,0,3,2] row_mask:0xf bank_mask:0xf
	v_mov_b32_dpp v245, v242 quad_perm:[1,0,3,2] row_mask:0xf bank_mask:0xf
	v_cndmask_b32_e64 v242, v242, v244, s[98:99]
	v_cndmask_b32_e64 v160, v245, v160, s[98:99]
	v_mov_b32_dpp v244, v161 quad_perm:[1,0,3,2] row_mask:0xf bank_mask:0xf
	v_mov_b32_dpp v245, v243 quad_perm:[1,0,3,2] row_mask:0xf bank_mask:0xf
	v_cndmask_b32_e64 v243, v243, v244, s[98:99]
	v_cndmask_b32_e64 v161, v245, v161, s[98:99]
	v_lshl_add_u64 v[246:247], v[124:125], 0, s[100:101]
	global_store_dwordx4 v[124:125], v[240:243], off nt
	global_store_dwordx4 v[246:247], v[158:161], off nt
	s_cbranch_vccnz .LBB0_354
	s_nop 0
	v_mov_b32_e32 v158, v65
	v_mov_b32_e32 v159, v127
	v_pk_mul_f32 v[124:125], v[126:127], v[126:127]
	v_pk_add_f32 v[158:159], v[126:127], v[158:159]
	v_pk_mul_f32 v[160:161], v[128:129], v[128:129]
	v_mov_b32_e32 v159, v125
	v_pk_mov_b32 v[124:125], v[126:127], v[124:125] op_sel:[1,0]
	v_mov_b32_e32 v126, v128
	v_pk_add_f32 v[124:125], v[124:125], v[158:159]
	v_mov_b32_e32 v127, v160
	v_pk_mul_f32 v[162:163], v[154:155], v[154:155]
	v_pk_add_f32 v[124:125], v[126:127], v[124:125]
	v_mov_b32_e32 v160, v129
	v_pk_add_f32 v[124:125], v[160:161], v[124:125]
	v_mov_b32_e32 v126, v154
	v_mov_b32_e32 v127, v162
	v_pk_mul_f32 v[170:171], v[156:157], v[156:157]
	v_pk_add_f32 v[124:125], v[126:127], v[124:125]
	v_mov_b32_e32 v162, v155
	v_pk_add_f32 v[124:125], v[162:163], v[124:125]
	v_mov_b32_e32 v126, v156
	v_mov_b32_e32 v127, v170
	v_pk_mul_f32 v[172:173], v[118:119], v[118:119]
	v_pk_add_f32 v[124:125], v[126:127], v[124:125]
	v_mov_b32_e32 v170, v157
	v_pk_add_f32 v[124:125], v[170:171], v[124:125]
	v_mov_b32_e32 v126, v118
	v_mov_b32_e32 v127, v172
	v_pk_mul_f32 v[174:175], v[120:121], v[120:121]
	v_pk_add_f32 v[124:125], v[124:125], v[126:127]
	v_mov_b32_e32 v172, v119
	v_pk_add_f32 v[118:119], v[172:173], v[124:125]
	v_mov_b32_e32 v124, v120
	v_mov_b32_e32 v125, v174
	v_pk_mul_f32 v[176:177], v[114:115], v[114:115]
	v_pk_add_f32 v[118:119], v[124:125], v[118:119]
	v_mov_b32_e32 v174, v121
	v_pk_add_f32 v[118:119], v[174:175], v[118:119]
	v_mov_b32_e32 v120, v114
	v_mov_b32_e32 v121, v176
	v_pk_mul_f32 v[178:179], v[116:117], v[116:117]
	v_pk_add_f32 v[118:119], v[120:121], v[118:119]
	v_mov_b32_e32 v176, v115
	v_pk_add_f32 v[114:115], v[176:177], v[118:119]
	v_mov_b32_e32 v118, v116
	v_mov_b32_e32 v119, v178
	v_pk_add_f32 v[114:115], v[118:119], v[114:115]
	v_mov_b32_e32 v178, v117
	v_pk_add_f32 v[114:115], v[178:179], v[114:115]
	ds_bpermute_b32 v116, v166, v114
	ds_bpermute_b32 v117, v166, v115
	s_waitcnt lgkmcnt(0)
	v_pk_add_f32 v[114:115], v[114:115], v[116:117]
	ds_bpermute_b32 v116, v167, v114
	ds_bpermute_b32 v117, v167, v115
	s_and_saveexec_b64 s[16:17], s[76:77]
	s_cbranch_execz .LBB0_353
	v_ashrrev_i32_e32 v123, 31, v122
	s_lshl_b32 s0, s52, 2
	s_waitcnt lgkmcnt(0)
	v_pk_add_f32 v[114:115], v[114:115], v[116:117]
	v_lshlrev_b64 v[116:117], 5, v[122:123]
	v_and_b32_e32 v248, 1, v190
	v_lshl_or_b32 v116, v248, 5, v116
	s_sub_i32 s0, s0, 32
	v_lshl_add_u64 v[116:117], v[116:117], 0, s[0:1]
	v_or_b32_e32 v116, s63, v116
	v_lshl_add_u64 v[116:117], v[116:117], 3, s[72:73]
	global_store_dwordx2 v[116:117], v[114:115], off

.LBB0_354:
	v_mul_f32_e32 v64, 0x3d372713, v44
	v_mul_f32_e32 v64, v44, v64
	v_fma_f32 v64, v44, v64, v44
	v_mul_f32_e32 v64, 0x3fcc422a, v64
	v_mul_f32_e32 v64, 0xbfb8aa3b, v64
	v_exp_f32_e32 v64, v64
	v_or_b32_e32 v114, 32, v146
	s_waitcnt lgkmcnt(0)
	v_mov_b64_e32 v[116:117], s[56:57]
	v_mad_i64_i32 v[116:117], s[2:3], v114, s69, v[116:117]
	v_add_f32_e32 v64, 1.0, v64
	v_rcp_f32_e32 v118, v64
	v_mul_f32_e32 v64, 0x3d372713, v45
	v_mul_f32_e32 v64, v45, v64
	v_fma_f32 v64, v45, v64, v45
	v_mul_f32_e32 v64, 0x3fcc422a, v64
	v_mul_f32_e32 v64, 0xbfb8aa3b, v64
	v_exp_f32_e32 v64, v64
	v_lshl_add_u64 v[116:117], v[144:145], 1, v[116:117]
	s_and_b64 vcc, exec, s[66:67]
	v_add_f32_e32 v64, 1.0, v64
	v_rcp_f32_e32 v119, v64
	v_mul_f32_e32 v64, 0x3d372713, v46
	v_mul_f32_e32 v64, v46, v64
	v_fma_f32 v64, v46, v64, v46
	v_mul_f32_e32 v64, 0x3fcc422a, v64
	v_mul_f32_e32 v64, 0xbfb8aa3b, v64
	v_exp_f32_e32 v64, v64
	v_pk_mul_f32 v[118:119], v[44:45], v[118:119]
	v_add_f32_e32 v64, 1.0, v64
	v_rcp_f32_e32 v120, v64
	v_mul_f32_e32 v64, 0x3d372713, v47
	v_mul_f32_e32 v64, v47, v64
	v_fma_f32 v64, v47, v64, v47
	v_mul_f32_e32 v64, 0x3fcc422a, v64
	v_mul_f32_e32 v64, 0xbfb8aa3b, v64
	v_exp_f32_e32 v64, v64
	v_cvt_pk_bf16_f32 v126, v118, v119
	v_add_f32_e32 v64, 1.0, v64
	v_rcp_f32_e32 v121, v64
	v_mul_f32_e32 v64, 0x3d372713, v40
	v_mul_f32_e32 v64, v40, v64
	v_fma_f32 v64, v40, v64, v40
	v_mul_f32_e32 v64, 0x3fcc422a, v64
	v_mul_f32_e32 v64, 0xbfb8aa3b, v64
	v_exp_f32_e32 v64, v64
	v_pk_mul_f32 v[120:121], v[46:47], v[120:121]
	v_add_f32_e32 v64, 1.0, v64
	v_rcp_f32_e32 v122, v64
	v_mul_f32_e32 v64, 0x3d372713, v41
	v_mul_f32_e32 v64, v41, v64
	v_fma_f32 v64, v41, v64, v41
	v_mul_f32_e32 v64, 0x3fcc422a, v64
	v_mul_f32_e32 v64, 0xbfb8aa3b, v64
	v_exp_f32_e32 v64, v64
	v_cvt_pk_bf16_f32 v127, v120, v121
	v_add_f32_e32 v64, 1.0, v64
	v_rcp_f32_e32 v123, v64
	v_mul_f32_e32 v64, 0x3d372713, v42
	v_mul_f32_e32 v64, v42, v64
	v_fma_f32 v64, v42, v64, v42
	v_mul_f32_e32 v64, 0x3fcc422a, v64
	v_mul_f32_e32 v64, 0xbfb8aa3b, v64
	v_exp_f32_e32 v64, v64
	v_pk_mul_f32 v[122:123], v[40:41], v[122:123]
	v_add_f32_e32 v64, 1.0, v64
	v_rcp_f32_e32 v124, v64
	v_mul_f32_e32 v64, 0x3d372713, v43
	v_mul_f32_e32 v64, v43, v64
	v_fma_f32 v64, v43, v64, v43
	v_mul_f32_e32 v64, 0x3fcc422a, v64
	v_mul_f32_e32 v64, 0xbfb8aa3b, v64
	v_exp_f32_e32 v64, v64
	v_cvt_pk_bf16_f32 v128, v122, v123
	v_add_f32_e32 v64, 1.0, v64
	v_rcp_f32_e32 v125, v64
	v_mul_f32_e32 v64, 0x3d372713, v110
	v_mul_f32_e32 v64, v110, v64
	v_fma_f32 v64, v110, v64, v110
	v_mul_f32_e32 v64, 0x3fcc422a, v64
	v_mul_f32_e32 v64, 0xbfb8aa3b, v64
	v_exp_f32_e32 v64, v64
	v_pk_mul_f32 v[124:125], v[42:43], v[124:125]
	v_add_f32_e32 v64, 1.0, v64
	v_cvt_pk_bf16_f32 v129, v124, v125
	v_mov_b32_e32 v240, v126
	v_mov_b32_e32 v241, v127
	v_mov_b32_e32 v242, v128
	v_mov_b32_e32 v243, v129
	s_nop 1
	v_rcp_f32_e32 v126, v64
	v_mul_f32_e32 v64, 0x3d372713, v111
	v_mul_f32_e32 v64, v111, v64
	v_fma_f32 v64, v111, v64, v111
	v_mul_f32_e32 v64, 0x3fcc422a, v64
	v_mul_f32_e32 v64, 0xbfb8aa3b, v64
	v_exp_f32_e32 v64, v64
	s_nop 0
	v_add_f32_e32 v64, 1.0, v64
	v_rcp_f32_e32 v127, v64
	v_mul_f32_e32 v64, 0x3d372713, v112
	v_mul_f32_e32 v64, v112, v64
	v_fma_f32 v64, v112, v64, v112
	v_mul_f32_e32 v64, 0x3fcc422a, v64
	v_mul_f32_e32 v64, 0xbfb8aa3b, v64
	v_exp_f32_e32 v64, v64
	v_pk_mul_f32 v[110:111], v[110:111], v[126:127]
	v_add_f32_e32 v64, 1.0, v64
	v_rcp_f32_e32 v126, v64
	v_mul_f32_e32 v64, 0x3d372713, v113
	v_mul_f32_e32 v64, v113, v64
	v_fma_f32 v64, v113, v64, v113
	v_mul_f32_e32 v64, 0x3fcc422a, v64
	v_mul_f32_e32 v64, 0xbfb8aa3b, v64
	v_exp_f32_e32 v64, v64
	s_nop 0
	v_add_f32_e32 v64, 1.0, v64
	v_rcp_f32_e32 v127, v64
	v_mul_f32_e32 v64, 0x3d372713, v106
	v_mul_f32_e32 v64, v106, v64
	v_fma_f32 v64, v106, v64, v106
	v_mul_f32_e32 v64, 0x3fcc422a, v64
	v_mul_f32_e32 v64, 0xbfb8aa3b, v64
	v_exp_f32_e32 v64, v64
	v_pk_mul_f32 v[112:113], v[112:113], v[126:127]
	v_add_f32_e32 v64, 1.0, v64
	v_rcp_f32_e32 v126, v64
	v_mul_f32_e32 v64, 0x3d372713, v107
	v_mul_f32_e32 v64, v107, v64
	v_fma_f32 v64, v107, v64, v107
	v_mul_f32_e32 v64, 0x3fcc422a, v64
	v_mul_f32_e32 v64, 0xbfb8aa3b, v64
	v_exp_f32_e32 v64, v64
	s_nop 0
	v_add_f32_e32 v64, 1.0, v64
	v_rcp_f32_e32 v127, v64
	v_mul_f32_e32 v64, 0x3d372713, v108
	v_mul_f32_e32 v64, v108, v64
	v_fma_f32 v64, v108, v64, v108
	v_mul_f32_e32 v64, 0x3fcc422a, v64
	v_mul_f32_e32 v64, 0xbfb8aa3b, v64
	v_exp_f32_e32 v64, v64
	v_pk_mul_f32 v[106:107], v[106:107], v[126:127]
	v_add_f32_e32 v64, 1.0, v64
	v_rcp_f32_e32 v126, v64
	v_mul_f32_e32 v64, 0x3d372713, v109
	v_mul_f32_e32 v64, v109, v64
	v_fma_f32 v64, v109, v64, v109
	v_mul_f32_e32 v64, 0x3fcc422a, v64
	v_mul_f32_e32 v64, 0xbfb8aa3b, v64
	v_exp_f32_e32 v64, v64
	v_cvt_pk_bf16_f32 v128, v106, v107
	v_add_f32_e32 v64, 1.0, v64
	v_rcp_f32_e32 v127, v64
	s_nop 0
	v_pk_mul_f32 v[108:109], v[108:109], v[126:127]
	v_cvt_pk_bf16_f32 v126, v110, v111
	v_cvt_pk_bf16_f32 v127, v112, v113
	v_cvt_pk_bf16_f32 v129, v108, v109
	s_nop 1
	v_mov_b32_dpp v244, v126 quad_perm:[1,0,3,2] row_mask:0xf bank_mask:0xf
	v_mov_b32_dpp v245, v240 quad_perm:[1,0,3,2] row_mask:0xf bank_mask:0xf
	v_cndmask_b32_e64 v240, v240, v244, s[98:99]
	v_cndmask_b32_e64 v126, v245, v126, s[98:99]
	v_mov_b32_dpp v244, v127 quad_perm:[1,0,3,2] row_mask:0xf bank_mask:0xf
	v_mov_b32_dpp v245, v241 quad_perm:[1,0,3,2] row_mask:0xf bank_mask:0xf
	v_cndmask_b32_e64 v241, v241, v244, s[98:99]
	v_cndmask_b32_e64 v127, v245, v127, s[98:99]
	v_mov_b32_dpp v244, v128 quad_perm:[1,0,3,2] row_mask:0xf bank_mask:0xf
	v_mov_b32_dpp v245, v242 quad_perm:[1,0,3,2] row_mask:0xf bank_mask:0xf
	v_cndmask_b32_e64 v242, v242, v244, s[98:99]
	v_cndmask_b32_e64 v128, v245, v128, s[98:99]
	v_mov_b32_dpp v244, v129 quad_perm:[1,0,3,2] row_mask:0xf bank_mask:0xf
	v_mov_b32_dpp v245, v243 quad_perm:[1,0,3,2] row_mask:0xf bank_mask:0xf
	v_cndmask_b32_e64 v243, v243, v244, s[98:99]
	v_cndmask_b32_e64 v129, v245, v129, s[98:99]
	v_lshl_add_u64 v[246:247], v[116:117], 0, s[100:101]
	global_store_dwordx4 v[116:117], v[240:243], off nt
	global_store_dwordx4 v[246:247], v[126:129], off nt
	s_cbranch_vccnz .LBB0_358
	s_nop 0
	v_mov_b32_e32 v126, v65
	v_mov_b32_e32 v127, v119
	v_pk_mul_f32 v[116:117], v[118:119], v[118:119]
	v_pk_add_f32 v[126:127], v[118:119], v[126:127]
	v_pk_mul_f32 v[128:129], v[120:121], v[120:121]
	v_mov_b32_e32 v127, v117
	v_pk_mov_b32 v[116:117], v[118:119], v[116:117] op_sel:[1,0]
	v_mov_b32_e32 v118, v120
	v_pk_add_f32 v[116:117], v[116:117], v[126:127]
	v_mov_b32_e32 v119, v128
	v_pk_mul_f32 v[154:155], v[122:123], v[122:123]
	v_pk_add_f32 v[116:117], v[118:119], v[116:117]
	v_mov_b32_e32 v128, v121
	v_pk_add_f32 v[116:117], v[128:129], v[116:117]
	v_mov_b32_e32 v118, v122
	v_mov_b32_e32 v119, v154
	v_pk_mul_f32 v[156:157], v[124:125], v[124:125]
	v_pk_add_f32 v[116:117], v[118:119], v[116:117]
	v_mov_b32_e32 v154, v123
	v_pk_add_f32 v[116:117], v[154:155], v[116:117]
	v_mov_b32_e32 v118, v124
	v_mov_b32_e32 v119, v156
	v_pk_mul_f32 v[158:159], v[110:111], v[110:111]
	v_pk_add_f32 v[116:117], v[118:119], v[116:117]
	v_mov_b32_e32 v156, v125
	v_pk_add_f32 v[116:117], v[156:157], v[116:117]
	v_mov_b32_e32 v118, v110
	v_mov_b32_e32 v119, v158
	v_pk_mul_f32 v[160:161], v[112:113], v[112:113]
	v_pk_add_f32 v[116:117], v[116:117], v[118:119]
	v_mov_b32_e32 v158, v111
	v_pk_add_f32 v[110:111], v[158:159], v[116:117]
	v_mov_b32_e32 v116, v112
	v_mov_b32_e32 v117, v160
	v_pk_mul_f32 v[162:163], v[106:107], v[106:107]
	v_pk_add_f32 v[110:111], v[116:117], v[110:111]
	v_mov_b32_e32 v160, v113
	v_pk_add_f32 v[110:111], v[160:161], v[110:111]
	v_mov_b32_e32 v112, v106
	v_mov_b32_e32 v113, v162
	v_pk_mul_f32 v[170:171], v[108:109], v[108:109]
	v_pk_add_f32 v[110:111], v[112:113], v[110:111]
	v_mov_b32_e32 v162, v107
	v_pk_add_f32 v[106:107], v[162:163], v[110:111]
	v_mov_b32_e32 v110, v108
	v_mov_b32_e32 v111, v170
	v_pk_add_f32 v[106:107], v[110:111], v[106:107]
	v_mov_b32_e32 v170, v109
	v_pk_add_f32 v[106:107], v[170:171], v[106:107]
	ds_bpermute_b32 v108, v166, v106
	ds_bpermute_b32 v109, v166, v107
	s_waitcnt lgkmcnt(0)
	v_pk_add_f32 v[106:107], v[106:107], v[108:109]
	ds_bpermute_b32 v108, v167, v106
	ds_bpermute_b32 v109, v167, v107
	s_and_saveexec_b64 s[16:17], s[76:77]
	s_cbranch_execz .LBB0_357
	v_ashrrev_i32_e32 v115, 31, v114
	s_lshl_b32 s0, s52, 2
	s_waitcnt lgkmcnt(0)
	v_pk_add_f32 v[106:107], v[106:107], v[108:109]
	v_lshlrev_b64 v[108:109], 5, v[114:115]
	v_and_b32_e32 v248, 1, v190
	v_lshl_or_b32 v108, v248, 5, v108
	s_sub_i32 s0, s0, 32
	v_lshl_add_u64 v[108:109], v[108:109], 0, s[0:1]
	v_or_b32_e32 v108, s63, v108
	v_lshl_add_u64 v[108:109], v[108:109], 3, s[72:73]
	global_store_dwordx2 v[108:109], v[106:107], off

.LBB0_358:
	v_mul_f32_e32 v64, 0x3d372713, v36
	v_mul_f32_e32 v64, v36, v64
	v_fma_f32 v64, v36, v64, v36
	v_mul_f32_e32 v64, 0x3fcc422a, v64
	v_mul_f32_e32 v64, 0xbfb8aa3b, v64
	v_exp_f32_e32 v64, v64
	v_or_b32_e32 v106, 48, v146
	s_waitcnt lgkmcnt(0)
	v_mov_b64_e32 v[108:109], s[56:57]
	v_mad_i64_i32 v[108:109], s[2:3], v106, s69, v[108:109]
	v_add_f32_e32 v64, 1.0, v64
	v_rcp_f32_e32 v110, v64
	v_mul_f32_e32 v64, 0x3d372713, v37
	v_mul_f32_e32 v64, v37, v64
	v_fma_f32 v64, v37, v64, v37
	v_mul_f32_e32 v64, 0x3fcc422a, v64
	v_mul_f32_e32 v64, 0xbfb8aa3b, v64
	v_exp_f32_e32 v64, v64
	v_lshl_add_u64 v[108:109], v[144:145], 1, v[108:109]
	s_and_b64 vcc, exec, s[66:67]
	v_add_f32_e32 v64, 1.0, v64
	v_rcp_f32_e32 v111, v64
	v_mul_f32_e32 v64, 0x3d372713, v38
	v_mul_f32_e32 v64, v38, v64
	v_fma_f32 v64, v38, v64, v38
	v_mul_f32_e32 v64, 0x3fcc422a, v64
	v_mul_f32_e32 v64, 0xbfb8aa3b, v64
	v_exp_f32_e32 v64, v64
	v_pk_mul_f32 v[110:111], v[36:37], v[110:111]
	v_add_f32_e32 v64, 1.0, v64
	v_rcp_f32_e32 v112, v64
	v_mul_f32_e32 v64, 0x3d372713, v39
	v_mul_f32_e32 v64, v39, v64
	v_fma_f32 v64, v39, v64, v39
	v_mul_f32_e32 v64, 0x3fcc422a, v64
	v_mul_f32_e32 v64, 0xbfb8aa3b, v64
	v_exp_f32_e32 v64, v64
	v_cvt_pk_bf16_f32 v118, v110, v111
	v_add_f32_e32 v64, 1.0, v64
	v_rcp_f32_e32 v113, v64
	v_mul_f32_e32 v64, 0x3d372713, v32
	v_mul_f32_e32 v64, v32, v64
	v_fma_f32 v64, v32, v64, v32
	v_mul_f32_e32 v64, 0x3fcc422a, v64
	v_mul_f32_e32 v64, 0xbfb8aa3b, v64
	v_exp_f32_e32 v64, v64
	v_pk_mul_f32 v[112:113], v[38:39], v[112:113]
	v_add_f32_e32 v64, 1.0, v64
	v_rcp_f32_e32 v114, v64
	v_mul_f32_e32 v64, 0x3d372713, v33
	v_mul_f32_e32 v64, v33, v64
	v_fma_f32 v64, v33, v64, v33
	v_mul_f32_e32 v64, 0x3fcc422a, v64
	v_mul_f32_e32 v64, 0xbfb8aa3b, v64
	v_exp_f32_e32 v64, v64
	v_cvt_pk_bf16_f32 v119, v112, v113
	v_add_f32_e32 v64, 1.0, v64
	v_rcp_f32_e32 v115, v64
	v_mul_f32_e32 v64, 0x3d372713, v34
	v_mul_f32_e32 v64, v34, v64
	v_fma_f32 v64, v34, v64, v34
	v_mul_f32_e32 v64, 0x3fcc422a, v64
	v_mul_f32_e32 v64, 0xbfb8aa3b, v64
	v_exp_f32_e32 v64, v64
	v_pk_mul_f32 v[114:115], v[32:33], v[114:115]
	v_add_f32_e32 v64, 1.0, v64
	v_rcp_f32_e32 v116, v64
	v_mul_f32_e32 v64, 0x3d372713, v35
	v_mul_f32_e32 v64, v35, v64
	v_fma_f32 v64, v35, v64, v35
	v_mul_f32_e32 v64, 0x3fcc422a, v64
	v_mul_f32_e32 v64, 0xbfb8aa3b, v64
	v_exp_f32_e32 v64, v64
	v_cvt_pk_bf16_f32 v120, v114, v115
	v_add_f32_e32 v64, 1.0, v64
	v_rcp_f32_e32 v117, v64
	v_mul_f32_e32 v64, 0x3d372713, v102
	v_mul_f32_e32 v64, v102, v64
	v_fma_f32 v64, v102, v64, v102
	v_mul_f32_e32 v64, 0x3fcc422a, v64
	v_mul_f32_e32 v64, 0xbfb8aa3b, v64
	v_exp_f32_e32 v64, v64
	v_pk_mul_f32 v[116:117], v[34:35], v[116:117]
	v_add_f32_e32 v64, 1.0, v64
	v_cvt_pk_bf16_f32 v121, v116, v117
	v_mov_b32_e32 v240, v118
	v_mov_b32_e32 v241, v119
	v_mov_b32_e32 v242, v120
	v_mov_b32_e32 v243, v121
	s_nop 1
	v_rcp_f32_e32 v118, v64
	v_mul_f32_e32 v64, 0x3d372713, v103
	v_mul_f32_e32 v64, v103, v64
	v_fma_f32 v64, v103, v64, v103
	v_mul_f32_e32 v64, 0x3fcc422a, v64
	v_mul_f32_e32 v64, 0xbfb8aa3b, v64
	v_exp_f32_e32 v64, v64
	s_nop 0
	v_add_f32_e32 v64, 1.0, v64
	v_rcp_f32_e32 v119, v64
	v_mul_f32_e32 v64, 0x3d372713, v104
	v_mul_f32_e32 v64, v104, v64
	v_fma_f32 v64, v104, v64, v104
	v_mul_f32_e32 v64, 0x3fcc422a, v64
	v_mul_f32_e32 v64, 0xbfb8aa3b, v64
	v_exp_f32_e32 v64, v64
	v_pk_mul_f32 v[102:103], v[102:103], v[118:119]
	v_add_f32_e32 v64, 1.0, v64
	v_rcp_f32_e32 v118, v64
	v_mul_f32_e32 v64, 0x3d372713, v105
	v_mul_f32_e32 v64, v105, v64
	v_fma_f32 v64, v105, v64, v105
	v_mul_f32_e32 v64, 0x3fcc422a, v64
	v_mul_f32_e32 v64, 0xbfb8aa3b, v64
	v_exp_f32_e32 v64, v64
	s_nop 0
	v_add_f32_e32 v64, 1.0, v64
	v_rcp_f32_e32 v119, v64
	v_mul_f32_e32 v64, 0x3d372713, v98
	v_mul_f32_e32 v64, v98, v64
	v_fma_f32 v64, v98, v64, v98
	v_mul_f32_e32 v64, 0x3fcc422a, v64
	v_mul_f32_e32 v64, 0xbfb8aa3b, v64
	v_exp_f32_e32 v64, v64
	v_pk_mul_f32 v[104:105], v[104:105], v[118:119]
	v_add_f32_e32 v64, 1.0, v64
	v_rcp_f32_e32 v118, v64
	v_mul_f32_e32 v64, 0x3d372713, v99
	v_mul_f32_e32 v64, v99, v64
	v_fma_f32 v64, v99, v64, v99
	v_mul_f32_e32 v64, 0x3fcc422a, v64
	v_mul_f32_e32 v64, 0xbfb8aa3b, v64
	v_exp_f32_e32 v64, v64
	s_nop 0
	v_add_f32_e32 v64, 1.0, v64
	v_rcp_f32_e32 v119, v64
	v_mul_f32_e32 v64, 0x3d372713, v100
	v_mul_f32_e32 v64, v100, v64
	v_fma_f32 v64, v100, v64, v100
	v_mul_f32_e32 v64, 0x3fcc422a, v64
	v_mul_f32_e32 v64, 0xbfb8aa3b, v64
	v_exp_f32_e32 v64, v64
	v_pk_mul_f32 v[98:99], v[98:99], v[118:119]
	v_add_f32_e32 v64, 1.0, v64
	v_rcp_f32_e32 v118, v64
	v_mul_f32_e32 v64, 0x3d372713, v101
	v_mul_f32_e32 v64, v101, v64
	v_fma_f32 v64, v101, v64, v101
	v_mul_f32_e32 v64, 0x3fcc422a, v64
	v_mul_f32_e32 v64, 0xbfb8aa3b, v64
	v_exp_f32_e32 v64, v64
	v_cvt_pk_bf16_f32 v120, v98, v99
	v_add_f32_e32 v64, 1.0, v64
	v_rcp_f32_e32 v119, v64
	s_nop 0
	v_pk_mul_f32 v[100:101], v[100:101], v[118:119]
	v_cvt_pk_bf16_f32 v118, v102, v103
	v_cvt_pk_bf16_f32 v119, v104, v105
	v_cvt_pk_bf16_f32 v121, v100, v101
	s_nop 1
	v_mov_b32_dpp v244, v118 quad_perm:[1,0,3,2] row_mask:0xf bank_mask:0xf
	v_mov_b32_dpp v245, v240 quad_perm:[1,0,3,2] row_mask:0xf bank_mask:0xf
	v_cndmask_b32_e64 v240, v240, v244, s[98:99]
	v_cndmask_b32_e64 v118, v245, v118, s[98:99]
	v_mov_b32_dpp v244, v119 quad_perm:[1,0,3,2] row_mask:0xf bank_mask:0xf
	v_mov_b32_dpp v245, v241 quad_perm:[1,0,3,2] row_mask:0xf bank_mask:0xf
	v_cndmask_b32_e64 v241, v241, v244, s[98:99]
	v_cndmask_b32_e64 v119, v245, v119, s[98:99]
	v_mov_b32_dpp v244, v120 quad_perm:[1,0,3,2] row_mask:0xf bank_mask:0xf
	v_mov_b32_dpp v245, v242 quad_perm:[1,0,3,2] row_mask:0xf bank_mask:0xf
	v_cndmask_b32_e64 v242, v242, v244, s[98:99]
	v_cndmask_b32_e64 v120, v245, v120, s[98:99]
	v_mov_b32_dpp v244, v121 quad_perm:[1,0,3,2] row_mask:0xf bank_mask:0xf
	v_mov_b32_dpp v245, v243 quad_perm:[1,0,3,2] row_mask:0xf bank_mask:0xf
	v_cndmask_b32_e64 v243, v243, v244, s[98:99]
	v_cndmask_b32_e64 v121, v245, v121, s[98:99]
	v_lshl_add_u64 v[246:247], v[108:109], 0, s[100:101]
	global_store_dwordx4 v[108:109], v[240:243], off nt
	global_store_dwordx4 v[246:247], v[118:121], off nt
	s_cbranch_vccnz .LBB0_362
	s_nop 0
	v_mov_b32_e32 v118, v65
	v_mov_b32_e32 v119, v111
	v_pk_mul_f32 v[108:109], v[110:111], v[110:111]
	v_pk_add_f32 v[118:119], v[110:111], v[118:119]
	v_pk_mul_f32 v[120:121], v[112:113], v[112:113]
	v_mov_b32_e32 v119, v109
	v_pk_mov_b32 v[108:109], v[110:111], v[108:109] op_sel:[1,0]
	v_mov_b32_e32 v110, v112
	v_pk_add_f32 v[108:109], v[108:109], v[118:119]
	v_mov_b32_e32 v111, v120
	v_pk_mul_f32 v[122:123], v[114:115], v[114:115]
	v_pk_add_f32 v[108:109], v[110:111], v[108:109]
	v_mov_b32_e32 v120, v113
	v_pk_add_f32 v[108:109], v[120:121], v[108:109]
	v_mov_b32_e32 v110, v114
	v_mov_b32_e32 v111, v122
	v_pk_mul_f32 v[124:125], v[116:117], v[116:117]
	v_pk_add_f32 v[108:109], v[110:111], v[108:109]
	v_mov_b32_e32 v122, v115
	v_pk_add_f32 v[108:109], v[122:123], v[108:109]
	v_mov_b32_e32 v110, v116
	v_mov_b32_e32 v111, v124
	v_pk_mul_f32 v[126:127], v[102:103], v[102:103]
	v_pk_add_f32 v[108:109], v[110:111], v[108:109]
	v_mov_b32_e32 v124, v117
	v_pk_add_f32 v[108:109], v[124:125], v[108:109]
	v_mov_b32_e32 v110, v102
	v_mov_b32_e32 v111, v126
	v_pk_mul_f32 v[128:129], v[104:105], v[104:105]
	v_pk_add_f32 v[108:109], v[108:109], v[110:111]
	v_mov_b32_e32 v126, v103
	v_pk_add_f32 v[102:103], v[126:127], v[108:109]
	v_mov_b32_e32 v108, v104
	v_mov_b32_e32 v109, v128
	v_pk_mul_f32 v[154:155], v[98:99], v[98:99]
	v_pk_add_f32 v[102:103], v[108:109], v[102:103]
	v_mov_b32_e32 v128, v105
	v_pk_add_f32 v[102:103], v[128:129], v[102:103]
	v_mov_b32_e32 v104, v98
	v_mov_b32_e32 v105, v154
	v_pk_mul_f32 v[156:157], v[100:101], v[100:101]
	v_pk_add_f32 v[102:103], v[104:105], v[102:103]
	v_mov_b32_e32 v154, v99
	v_pk_add_f32 v[98:99], v[154:155], v[102:103]
	v_mov_b32_e32 v102, v100
	v_mov_b32_e32 v103, v156
	v_pk_add_f32 v[98:99], v[102:103], v[98:99]
	v_mov_b32_e32 v156, v101
	v_pk_add_f32 v[98:99], v[156:157], v[98:99]
	ds_bpermute_b32 v100, v166, v98
	ds_bpermute_b32 v101, v166, v99
	s_waitcnt lgkmcnt(0)
	v_pk_add_f32 v[98:99], v[98:99], v[100:101]
	ds_bpermute_b32 v100, v167, v98
	ds_bpermute_b32 v101, v167, v99
	s_and_saveexec_b64 s[16:17], s[76:77]
	s_cbranch_execz .LBB0_361
	v_ashrrev_i32_e32 v107, 31, v106
	s_lshl_b32 s0, s52, 2
	s_waitcnt lgkmcnt(0)
	v_pk_add_f32 v[98:99], v[98:99], v[100:101]
	v_lshlrev_b64 v[100:101], 5, v[106:107]
	v_and_b32_e32 v248, 1, v190
	v_lshl_or_b32 v100, v248, 5, v100
	s_sub_i32 s0, s0, 32
	v_lshl_add_u64 v[100:101], v[100:101], 0, s[0:1]
	v_or_b32_e32 v100, s63, v100
	v_lshl_add_u64 v[100:101], v[100:101], 3, s[72:73]
	global_store_dwordx2 v[100:101], v[98:99], off

.LBB0_362:
	v_mul_f32_e32 v64, 0x3d372713, v28
	v_mul_f32_e32 v64, v28, v64
	v_fma_f32 v64, v28, v64, v28
	v_mul_f32_e32 v64, 0x3fcc422a, v64
	v_mul_f32_e32 v64, 0xbfb8aa3b, v64
	v_exp_f32_e32 v64, v64
	v_add_u32_e32 v98, 0x80, v146
	s_waitcnt lgkmcnt(0)
	v_mov_b64_e32 v[100:101], s[56:57]
	v_mad_i64_i32 v[100:101], s[2:3], v98, s69, v[100:101]
	v_add_f32_e32 v64, 1.0, v64
	v_rcp_f32_e32 v102, v64
	v_mul_f32_e32 v64, 0x3d372713, v29
	v_mul_f32_e32 v64, v29, v64
	v_fma_f32 v64, v29, v64, v29
	v_mul_f32_e32 v64, 0x3fcc422a, v64
	v_mul_f32_e32 v64, 0xbfb8aa3b, v64
	v_exp_f32_e32 v64, v64
	v_lshl_add_u64 v[100:101], v[144:145], 1, v[100:101]
	s_and_b64 vcc, exec, s[66:67]
	v_add_f32_e32 v64, 1.0, v64
	v_rcp_f32_e32 v103, v64
	v_mul_f32_e32 v64, 0x3d372713, v30
	v_mul_f32_e32 v64, v30, v64
	v_fma_f32 v64, v30, v64, v30
	v_mul_f32_e32 v64, 0x3fcc422a, v64
	v_mul_f32_e32 v64, 0xbfb8aa3b, v64
	v_exp_f32_e32 v64, v64
	v_pk_mul_f32 v[102:103], v[28:29], v[102:103]
	v_add_f32_e32 v64, 1.0, v64
	v_rcp_f32_e32 v104, v64
	v_mul_f32_e32 v64, 0x3d372713, v31
	v_mul_f32_e32 v64, v31, v64
	v_fma_f32 v64, v31, v64, v31
	v_mul_f32_e32 v64, 0x3fcc422a, v64
	v_mul_f32_e32 v64, 0xbfb8aa3b, v64
	v_exp_f32_e32 v64, v64
	v_cvt_pk_bf16_f32 v110, v102, v103
	v_add_f32_e32 v64, 1.0, v64
	v_rcp_f32_e32 v105, v64
	v_mul_f32_e32 v64, 0x3d372713, v24
	v_mul_f32_e32 v64, v24, v64
	v_fma_f32 v64, v24, v64, v24
	v_mul_f32_e32 v64, 0x3fcc422a, v64
	v_mul_f32_e32 v64, 0xbfb8aa3b, v64
	v_exp_f32_e32 v64, v64
	v_pk_mul_f32 v[104:105], v[30:31], v[104:105]
	v_add_f32_e32 v64, 1.0, v64
	v_rcp_f32_e32 v106, v64
	v_mul_f32_e32 v64, 0x3d372713, v25
	v_mul_f32_e32 v64, v25, v64
	v_fma_f32 v64, v25, v64, v25
	v_mul_f32_e32 v64, 0x3fcc422a, v64
	v_mul_f32_e32 v64, 0xbfb8aa3b, v64
	v_exp_f32_e32 v64, v64
	v_cvt_pk_bf16_f32 v111, v104, v105
	v_add_f32_e32 v64, 1.0, v64
	v_rcp_f32_e32 v107, v64
	v_mul_f32_e32 v64, 0x3d372713, v26
	v_mul_f32_e32 v64, v26, v64
	v_fma_f32 v64, v26, v64, v26
	v_mul_f32_e32 v64, 0x3fcc422a, v64
	v_mul_f32_e32 v64, 0xbfb8aa3b, v64
	v_exp_f32_e32 v64, v64
	v_pk_mul_f32 v[106:107], v[24:25], v[106:107]
	v_add_f32_e32 v64, 1.0, v64
	v_rcp_f32_e32 v108, v64
	v_mul_f32_e32 v64, 0x3d372713, v27
	v_mul_f32_e32 v64, v27, v64
	v_fma_f32 v64, v27, v64, v27
	v_mul_f32_e32 v64, 0x3fcc422a, v64
	v_mul_f32_e32 v64, 0xbfb8aa3b, v64
	v_exp_f32_e32 v64, v64
	v_cvt_pk_bf16_f32 v112, v106, v107
	v_add_f32_e32 v64, 1.0, v64
	v_rcp_f32_e32 v109, v64
	v_mul_f32_e32 v64, 0x3d372713, v94
	v_mul_f32_e32 v64, v94, v64
	v_fma_f32 v64, v94, v64, v94
	v_mul_f32_e32 v64, 0x3fcc422a, v64
	v_mul_f32_e32 v64, 0xbfb8aa3b, v64
	v_exp_f32_e32 v64, v64
	v_pk_mul_f32 v[108:109], v[26:27], v[108:109]
	v_add_f32_e32 v64, 1.0, v64
	v_cvt_pk_bf16_f32 v113, v108, v109
	v_mov_b32_e32 v240, v110
	v_mov_b32_e32 v241, v111
	v_mov_b32_e32 v242, v112
	v_mov_b32_e32 v243, v113
	s_nop 1
	v_rcp_f32_e32 v110, v64
	v_mul_f32_e32 v64, 0x3d372713, v95
	v_mul_f32_e32 v64, v95, v64
	v_fma_f32 v64, v95, v64, v95
	v_mul_f32_e32 v64, 0x3fcc422a, v64
	v_mul_f32_e32 v64, 0xbfb8aa3b, v64
	v_exp_f32_e32 v64, v64
	s_nop 0
	v_add_f32_e32 v64, 1.0, v64
	v_rcp_f32_e32 v111, v64
	v_mul_f32_e32 v64, 0x3d372713, v96
	v_mul_f32_e32 v64, v96, v64
	v_fma_f32 v64, v96, v64, v96
	v_mul_f32_e32 v64, 0x3fcc422a, v64
	v_mul_f32_e32 v64, 0xbfb8aa3b, v64
	v_exp_f32_e32 v64, v64
	v_pk_mul_f32 v[94:95], v[94:95], v[110:111]
	v_add_f32_e32 v64, 1.0, v64
	v_rcp_f32_e32 v110, v64
	v_mul_f32_e32 v64, 0x3d372713, v97
	v_mul_f32_e32 v64, v97, v64
	v_fma_f32 v64, v97, v64, v97
	v_mul_f32_e32 v64, 0x3fcc422a, v64
	v_mul_f32_e32 v64, 0xbfb8aa3b, v64
	v_exp_f32_e32 v64, v64
	s_nop 0
	v_add_f32_e32 v64, 1.0, v64
	v_rcp_f32_e32 v111, v64
	v_mul_f32_e32 v64, 0x3d372713, v90
	v_mul_f32_e32 v64, v90, v64
	v_fma_f32 v64, v90, v64, v90
	v_mul_f32_e32 v64, 0x3fcc422a, v64
	v_mul_f32_e32 v64, 0xbfb8aa3b, v64
	v_exp_f32_e32 v64, v64
	v_pk_mul_f32 v[96:97], v[96:97], v[110:111]
	v_add_f32_e32 v64, 1.0, v64
	v_rcp_f32_e32 v110, v64
	v_mul_f32_e32 v64, 0x3d372713, v91
	v_mul_f32_e32 v64, v91, v64
	v_fma_f32 v64, v91, v64, v91
	v_mul_f32_e32 v64, 0x3fcc422a, v64
	v_mul_f32_e32 v64, 0xbfb8aa3b, v64
	v_exp_f32_e32 v64, v64
	s_nop 0
	v_add_f32_e32 v64, 1.0, v64
	v_rcp_f32_e32 v111, v64
	v_mul_f32_e32 v64, 0x3d372713, v92
	v_mul_f32_e32 v64, v92, v64
	v_fma_f32 v64, v92, v64, v92
	v_mul_f32_e32 v64, 0x3fcc422a, v64
	v_mul_f32_e32 v64, 0xbfb8aa3b, v64
	v_exp_f32_e32 v64, v64
	v_pk_mul_f32 v[90:91], v[90:91], v[110:111]
	v_add_f32_e32 v64, 1.0, v64
	v_rcp_f32_e32 v110, v64
	v_mul_f32_e32 v64, 0x3d372713, v93
	v_mul_f32_e32 v64, v93, v64
	v_fma_f32 v64, v93, v64, v93
	v_mul_f32_e32 v64, 0x3fcc422a, v64
	v_mul_f32_e32 v64, 0xbfb8aa3b, v64
	v_exp_f32_e32 v64, v64
	v_cvt_pk_bf16_f32 v112, v90, v91
	v_add_f32_e32 v64, 1.0, v64
	v_rcp_f32_e32 v111, v64
	s_nop 0
	v_pk_mul_f32 v[92:93], v[92:93], v[110:111]
	v_cvt_pk_bf16_f32 v110, v94, v95
	v_cvt_pk_bf16_f32 v111, v96, v97
	v_cvt_pk_bf16_f32 v113, v92, v93
	s_nop 1
	v_mov_b32_dpp v244, v110 quad_perm:[1,0,3,2] row_mask:0xf bank_mask:0xf
	v_mov_b32_dpp v245, v240 quad_perm:[1,0,3,2] row_mask:0xf bank_mask:0xf
	v_cndmask_b32_e64 v240, v240, v244, s[98:99]
	v_cndmask_b32_e64 v110, v245, v110, s[98:99]
	v_mov_b32_dpp v244, v111 quad_perm:[1,0,3,2] row_mask:0xf bank_mask:0xf
	v_mov_b32_dpp v245, v241 quad_perm:[1,0,3,2] row_mask:0xf bank_mask:0xf
	v_cndmask_b32_e64 v241, v241, v244, s[98:99]
	v_cndmask_b32_e64 v111, v245, v111, s[98:99]
	v_mov_b32_dpp v244, v112 quad_perm:[1,0,3,2] row_mask:0xf bank_mask:0xf
	v_mov_b32_dpp v245, v242 quad_perm:[1,0,3,2] row_mask:0xf bank_mask:0xf
	v_cndmask_b32_e64 v242, v242, v244, s[98:99]
	v_cndmask_b32_e64 v112, v245, v112, s[98:99]
	v_mov_b32_dpp v244, v113 quad_perm:[1,0,3,2] row_mask:0xf bank_mask:0xf
	v_mov_b32_dpp v245, v243 quad_perm:[1,0,3,2] row_mask:0xf bank_mask:0xf
	v_cndmask_b32_e64 v243, v243, v244, s[98:99]
	v_cndmask_b32_e64 v113, v245, v113, s[98:99]
	v_lshl_add_u64 v[246:247], v[100:101], 0, s[100:101]
	global_store_dwordx4 v[100:101], v[240:243], off nt
	global_store_dwordx4 v[246:247], v[110:113], off nt
	s_cbranch_vccnz .LBB0_366
	s_nop 0
	v_mov_b32_e32 v110, v65
	v_mov_b32_e32 v111, v103
	v_pk_mul_f32 v[100:101], v[102:103], v[102:103]
	v_pk_add_f32 v[110:111], v[102:103], v[110:111]
	v_pk_mul_f32 v[112:113], v[104:105], v[104:105]
	v_mov_b32_e32 v111, v101
	v_pk_mov_b32 v[100:101], v[102:103], v[100:101] op_sel:[1,0]
	v_mov_b32_e32 v102, v104
	v_pk_add_f32 v[100:101], v[100:101], v[110:111]
	v_mov_b32_e32 v103, v112
	v_pk_mul_f32 v[114:115], v[106:107], v[106:107]
	v_pk_add_f32 v[100:101], v[102:103], v[100:101]
	v_mov_b32_e32 v112, v105
	v_pk_add_f32 v[100:101], v[112:113], v[100:101]
	v_mov_b32_e32 v102, v106
	v_mov_b32_e32 v103, v114
	v_pk_mul_f32 v[116:117], v[108:109], v[108:109]
	v_pk_add_f32 v[100:101], v[102:103], v[100:101]
	v_mov_b32_e32 v114, v107
	v_pk_add_f32 v[100:101], v[114:115], v[100:101]
	v_mov_b32_e32 v102, v108
	v_mov_b32_e32 v103, v116
	v_pk_mul_f32 v[118:119], v[94:95], v[94:95]
	v_pk_add_f32 v[100:101], v[102:103], v[100:101]
	v_mov_b32_e32 v116, v109
	v_pk_add_f32 v[100:101], v[116:117], v[100:101]
	v_mov_b32_e32 v102, v94
	v_mov_b32_e32 v103, v118
	v_pk_mul_f32 v[120:121], v[96:97], v[96:97]
	v_pk_add_f32 v[100:101], v[100:101], v[102:103]
	v_mov_b32_e32 v118, v95
	v_pk_add_f32 v[94:95], v[118:119], v[100:101]
	v_mov_b32_e32 v100, v96
	v_mov_b32_e32 v101, v120
	v_pk_mul_f32 v[122:123], v[90:91], v[90:91]
	v_pk_add_f32 v[94:95], v[100:101], v[94:95]
	v_mov_b32_e32 v120, v97
	v_pk_add_f32 v[94:95], v[120:121], v[94:95]
	v_mov_b32_e32 v96, v90
	v_mov_b32_e32 v97, v122
	v_pk_mul_f32 v[124:125], v[92:93], v[92:93]
	v_pk_add_f32 v[94:95], v[96:97], v[94:95]
	v_mov_b32_e32 v122, v91
	v_pk_add_f32 v[90:91], v[122:123], v[94:95]
	v_mov_b32_e32 v94, v92
	v_mov_b32_e32 v95, v124
	v_pk_add_f32 v[90:91], v[94:95], v[90:91]
	v_mov_b32_e32 v124, v93
	v_pk_add_f32 v[90:91], v[124:125], v[90:91]
	ds_bpermute_b32 v92, v166, v90
	ds_bpermute_b32 v93, v166, v91
	s_waitcnt lgkmcnt(0)
	v_pk_add_f32 v[90:91], v[90:91], v[92:93]
	ds_bpermute_b32 v92, v167, v90
	ds_bpermute_b32 v93, v167, v91
	s_and_saveexec_b64 s[16:17], s[76:77]
	s_cbranch_execz .LBB0_365
	v_ashrrev_i32_e32 v99, 31, v98
	s_lshl_b32 s0, s52, 2
	s_waitcnt lgkmcnt(0)
	v_pk_add_f32 v[90:91], v[90:91], v[92:93]
	v_lshlrev_b64 v[92:93], 5, v[98:99]
	v_and_b32_e32 v248, 1, v190
	v_lshl_or_b32 v92, v248, 5, v92
	s_sub_i32 s0, s0, 32
	v_lshl_add_u64 v[92:93], v[92:93], 0, s[0:1]
	v_or_b32_e32 v92, s63, v92
	v_lshl_add_u64 v[92:93], v[92:93], 3, s[72:73]
	global_store_dwordx2 v[92:93], v[90:91], off

.LBB0_366:
	v_mul_f32_e32 v64, 0x3d372713, v20
	v_mul_f32_e32 v64, v20, v64
	v_fma_f32 v64, v20, v64, v20
	v_mul_f32_e32 v64, 0x3fcc422a, v64
	v_mul_f32_e32 v64, 0xbfb8aa3b, v64
	v_exp_f32_e32 v64, v64
	v_add_u32_e32 v90, 0x90, v146
	s_waitcnt lgkmcnt(0)
	v_mov_b64_e32 v[92:93], s[56:57]
	v_mad_i64_i32 v[92:93], s[2:3], v90, s69, v[92:93]
	v_add_f32_e32 v64, 1.0, v64
	v_rcp_f32_e32 v94, v64
	v_mul_f32_e32 v64, 0x3d372713, v21
	v_mul_f32_e32 v64, v21, v64
	v_fma_f32 v64, v21, v64, v21
	v_mul_f32_e32 v64, 0x3fcc422a, v64
	v_mul_f32_e32 v64, 0xbfb8aa3b, v64
	v_exp_f32_e32 v64, v64
	v_lshl_add_u64 v[92:93], v[144:145], 1, v[92:93]
	s_and_b64 vcc, exec, s[66:67]
	v_add_f32_e32 v64, 1.0, v64
	v_rcp_f32_e32 v95, v64
	v_mul_f32_e32 v64, 0x3d372713, v22
	v_mul_f32_e32 v64, v22, v64
	v_fma_f32 v64, v22, v64, v22
	v_mul_f32_e32 v64, 0x3fcc422a, v64
	v_mul_f32_e32 v64, 0xbfb8aa3b, v64
	v_exp_f32_e32 v64, v64
	v_pk_mul_f32 v[94:95], v[20:21], v[94:95]
	v_add_f32_e32 v64, 1.0, v64
	v_rcp_f32_e32 v96, v64
	v_mul_f32_e32 v64, 0x3d372713, v23
	v_mul_f32_e32 v64, v23, v64
	v_fma_f32 v64, v23, v64, v23
	v_mul_f32_e32 v64, 0x3fcc422a, v64
	v_mul_f32_e32 v64, 0xbfb8aa3b, v64
	v_exp_f32_e32 v64, v64
	v_cvt_pk_bf16_f32 v102, v94, v95
	v_add_f32_e32 v64, 1.0, v64
	v_rcp_f32_e32 v97, v64
	v_mul_f32_e32 v64, 0x3d372713, v16
	v_mul_f32_e32 v64, v16, v64
	v_fma_f32 v64, v16, v64, v16
	v_mul_f32_e32 v64, 0x3fcc422a, v64
	v_mul_f32_e32 v64, 0xbfb8aa3b, v64
	v_exp_f32_e32 v64, v64
	v_pk_mul_f32 v[96:97], v[22:23], v[96:97]
	v_add_f32_e32 v64, 1.0, v64
	v_rcp_f32_e32 v98, v64
	v_mul_f32_e32 v64, 0x3d372713, v17
	v_mul_f32_e32 v64, v17, v64
	v_fma_f32 v64, v17, v64, v17
	v_mul_f32_e32 v64, 0x3fcc422a, v64
	v_mul_f32_e32 v64, 0xbfb8aa3b, v64
	v_exp_f32_e32 v64, v64
	v_cvt_pk_bf16_f32 v103, v96, v97
	v_add_f32_e32 v64, 1.0, v64
	v_rcp_f32_e32 v99, v64
	v_mul_f32_e32 v64, 0x3d372713, v18
	v_mul_f32_e32 v64, v18, v64
	v_fma_f32 v64, v18, v64, v18
	v_mul_f32_e32 v64, 0x3fcc422a, v64
	v_mul_f32_e32 v64, 0xbfb8aa3b, v64
	v_exp_f32_e32 v64, v64
	v_pk_mul_f32 v[98:99], v[16:17], v[98:99]
	v_add_f32_e32 v64, 1.0, v64
	v_rcp_f32_e32 v100, v64
	v_mul_f32_e32 v64, 0x3d372713, v19
	v_mul_f32_e32 v64, v19, v64
	v_fma_f32 v64, v19, v64, v19
	v_mul_f32_e32 v64, 0x3fcc422a, v64
	v_mul_f32_e32 v64, 0xbfb8aa3b, v64
	v_exp_f32_e32 v64, v64
	v_cvt_pk_bf16_f32 v104, v98, v99
	v_add_f32_e32 v64, 1.0, v64
	v_rcp_f32_e32 v101, v64
	v_mul_f32_e32 v64, 0x3d372713, v86
	v_mul_f32_e32 v64, v86, v64
	v_fma_f32 v64, v86, v64, v86
	v_mul_f32_e32 v64, 0x3fcc422a, v64
	v_mul_f32_e32 v64, 0xbfb8aa3b, v64
	v_exp_f32_e32 v64, v64
	v_pk_mul_f32 v[100:101], v[18:19], v[100:101]
	v_add_f32_e32 v64, 1.0, v64
	v_cvt_pk_bf16_f32 v105, v100, v101
	v_mov_b32_e32 v240, v102
	v_mov_b32_e32 v241, v103
	v_mov_b32_e32 v242, v104
	v_mov_b32_e32 v243, v105
	s_nop 1
	v_rcp_f32_e32 v102, v64
	v_mul_f32_e32 v64, 0x3d372713, v87
	v_mul_f32_e32 v64, v87, v64
	v_fma_f32 v64, v87, v64, v87
	v_mul_f32_e32 v64, 0x3fcc422a, v64
	v_mul_f32_e32 v64, 0xbfb8aa3b, v64
	v_exp_f32_e32 v64, v64
	s_nop 0
	v_add_f32_e32 v64, 1.0, v64
	v_rcp_f32_e32 v103, v64
	v_mul_f32_e32 v64, 0x3d372713, v88
	v_mul_f32_e32 v64, v88, v64
	v_fma_f32 v64, v88, v64, v88
	v_mul_f32_e32 v64, 0x3fcc422a, v64
	v_mul_f32_e32 v64, 0xbfb8aa3b, v64
	v_exp_f32_e32 v64, v64
	v_pk_mul_f32 v[86:87], v[86:87], v[102:103]
	v_add_f32_e32 v64, 1.0, v64
	v_rcp_f32_e32 v102, v64
	v_mul_f32_e32 v64, 0x3d372713, v89
	v_mul_f32_e32 v64, v89, v64
	v_fma_f32 v64, v89, v64, v89
	v_mul_f32_e32 v64, 0x3fcc422a, v64
	v_mul_f32_e32 v64, 0xbfb8aa3b, v64
	v_exp_f32_e32 v64, v64
	s_nop 0
	v_add_f32_e32 v64, 1.0, v64
	v_rcp_f32_e32 v103, v64
	v_mul_f32_e32 v64, 0x3d372713, v82
	v_mul_f32_e32 v64, v82, v64
	v_fma_f32 v64, v82, v64, v82
	v_mul_f32_e32 v64, 0x3fcc422a, v64
	v_mul_f32_e32 v64, 0xbfb8aa3b, v64
	v_exp_f32_e32 v64, v64
	v_pk_mul_f32 v[88:89], v[88:89], v[102:103]
	v_add_f32_e32 v64, 1.0, v64
	v_rcp_f32_e32 v102, v64
	v_mul_f32_e32 v64, 0x3d372713, v83
	v_mul_f32_e32 v64, v83, v64
	v_fma_f32 v64, v83, v64, v83
	v_mul_f32_e32 v64, 0x3fcc422a, v64
	v_mul_f32_e32 v64, 0xbfb8aa3b, v64
	v_exp_f32_e32 v64, v64
	s_nop 0
	v_add_f32_e32 v64, 1.0, v64
	v_rcp_f32_e32 v103, v64
	v_mul_f32_e32 v64, 0x3d372713, v84
	v_mul_f32_e32 v64, v84, v64
	v_fma_f32 v64, v84, v64, v84
	v_mul_f32_e32 v64, 0x3fcc422a, v64
	v_mul_f32_e32 v64, 0xbfb8aa3b, v64
	v_exp_f32_e32 v64, v64
	v_pk_mul_f32 v[82:83], v[82:83], v[102:103]
	v_add_f32_e32 v64, 1.0, v64
	v_rcp_f32_e32 v102, v64
	v_mul_f32_e32 v64, 0x3d372713, v85
	v_mul_f32_e32 v64, v85, v64
	v_fma_f32 v64, v85, v64, v85
	v_mul_f32_e32 v64, 0x3fcc422a, v64
	v_mul_f32_e32 v64, 0xbfb8aa3b, v64
	v_exp_f32_e32 v64, v64
	v_cvt_pk_bf16_f32 v104, v82, v83
	v_add_f32_e32 v64, 1.0, v64
	v_rcp_f32_e32 v103, v64
	s_nop 0
	v_pk_mul_f32 v[84:85], v[84:85], v[102:103]
	v_cvt_pk_bf16_f32 v102, v86, v87
	v_cvt_pk_bf16_f32 v103, v88, v89
	v_cvt_pk_bf16_f32 v105, v84, v85
	s_nop 1
	v_mov_b32_dpp v244, v102 quad_perm:[1,0,3,2] row_mask:0xf bank_mask:0xf
	v_mov_b32_dpp v245, v240 quad_perm:[1,0,3,2] row_mask:0xf bank_mask:0xf
	v_cndmask_b32_e64 v240, v240, v244, s[98:99]
	v_cndmask_b32_e64 v102, v245, v102, s[98:99]
	v_mov_b32_dpp v244, v103 quad_perm:[1,0,3,2] row_mask:0xf bank_mask:0xf
	v_mov_b32_dpp v245, v241 quad_perm:[1,0,3,2] row_mask:0xf bank_mask:0xf
	v_cndmask_b32_e64 v241, v241, v244, s[98:99]
	v_cndmask_b32_e64 v103, v245, v103, s[98:99]
	v_mov_b32_dpp v244, v104 quad_perm:[1,0,3,2] row_mask:0xf bank_mask:0xf
	v_mov_b32_dpp v245, v242 quad_perm:[1,0,3,2] row_mask:0xf bank_mask:0xf
	v_cndmask_b32_e64 v242, v242, v244, s[98:99]
	v_cndmask_b32_e64 v104, v245, v104, s[98:99]
	v_mov_b32_dpp v244, v105 quad_perm:[1,0,3,2] row_mask:0xf bank_mask:0xf
	v_mov_b32_dpp v245, v243 quad_perm:[1,0,3,2] row_mask:0xf bank_mask:0xf
	v_cndmask_b32_e64 v243, v243, v244, s[98:99]
	v_cndmask_b32_e64 v105, v245, v105, s[98:99]
	v_lshl_add_u64 v[246:247], v[92:93], 0, s[100:101]
	global_store_dwordx4 v[92:93], v[240:243], off nt
	global_store_dwordx4 v[246:247], v[102:105], off nt
	s_cbranch_vccnz .LBB0_370
	s_nop 0
	v_mov_b32_e32 v102, v65
	v_mov_b32_e32 v103, v95
	v_pk_mul_f32 v[92:93], v[94:95], v[94:95]
	v_pk_add_f32 v[102:103], v[94:95], v[102:103]
	v_pk_mul_f32 v[104:105], v[96:97], v[96:97]
	v_mov_b32_e32 v103, v93
	v_pk_mov_b32 v[92:93], v[94:95], v[92:93] op_sel:[1,0]
	v_mov_b32_e32 v94, v96
	v_pk_add_f32 v[92:93], v[92:93], v[102:103]
	v_mov_b32_e32 v95, v104
	v_pk_mul_f32 v[106:107], v[98:99], v[98:99]
	v_pk_add_f32 v[92:93], v[94:95], v[92:93]
	v_mov_b32_e32 v104, v97
	v_pk_add_f32 v[92:93], v[104:105], v[92:93]
	v_mov_b32_e32 v94, v98
	v_mov_b32_e32 v95, v106
	v_pk_mul_f32 v[108:109], v[100:101], v[100:101]
	v_pk_add_f32 v[92:93], v[94:95], v[92:93]
	v_mov_b32_e32 v106, v99
	v_pk_add_f32 v[92:93], v[106:107], v[92:93]
	v_mov_b32_e32 v94, v100
	v_mov_b32_e32 v95, v108
	v_pk_mul_f32 v[110:111], v[86:87], v[86:87]
	v_pk_add_f32 v[92:93], v[94:95], v[92:93]
	v_mov_b32_e32 v108, v101
	v_pk_add_f32 v[92:93], v[108:109], v[92:93]
	v_mov_b32_e32 v94, v86
	v_mov_b32_e32 v95, v110
	v_pk_mul_f32 v[112:113], v[88:89], v[88:89]
	v_pk_add_f32 v[92:93], v[92:93], v[94:95]
	v_mov_b32_e32 v110, v87
	v_pk_add_f32 v[86:87], v[110:111], v[92:93]
	v_mov_b32_e32 v92, v88
	v_mov_b32_e32 v93, v112
	v_pk_mul_f32 v[114:115], v[82:83], v[82:83]
	v_pk_add_f32 v[86:87], v[92:93], v[86:87]
	v_mov_b32_e32 v112, v89
	v_pk_add_f32 v[86:87], v[112:113], v[86:87]
	v_mov_b32_e32 v88, v82
	v_mov_b32_e32 v89, v114
	v_pk_mul_f32 v[116:117], v[84:85], v[84:85]
	v_pk_add_f32 v[86:87], v[88:89], v[86:87]
	v_mov_b32_e32 v114, v83
	v_pk_add_f32 v[82:83], v[114:115], v[86:87]
	v_mov_b32_e32 v86, v84
	v_mov_b32_e32 v87, v116
	v_pk_add_f32 v[82:83], v[86:87], v[82:83]
	v_mov_b32_e32 v116, v85
	v_pk_add_f32 v[82:83], v[116:117], v[82:83]
	ds_bpermute_b32 v84, v166, v82
	ds_bpermute_b32 v85, v166, v83
	s_waitcnt lgkmcnt(0)
	v_pk_add_f32 v[82:83], v[82:83], v[84:85]
	ds_bpermute_b32 v84, v167, v82
	ds_bpermute_b32 v85, v167, v83
	s_and_saveexec_b64 s[16:17], s[76:77]
	s_cbranch_execz .LBB0_369
	v_ashrrev_i32_e32 v91, 31, v90
	s_lshl_b32 s0, s52, 2
	s_waitcnt lgkmcnt(0)
	v_pk_add_f32 v[82:83], v[82:83], v[84:85]
	v_lshlrev_b64 v[84:85], 5, v[90:91]
	v_and_b32_e32 v248, 1, v190
	v_lshl_or_b32 v84, v248, 5, v84
	s_sub_i32 s0, s0, 32
	v_lshl_add_u64 v[84:85], v[84:85], 0, s[0:1]
	v_or_b32_e32 v84, s63, v84
	v_lshl_add_u64 v[84:85], v[84:85], 3, s[72:73]
	global_store_dwordx2 v[84:85], v[82:83], off

.LBB0_370:
	v_mul_f32_e32 v64, 0x3d372713, v12
	v_mul_f32_e32 v64, v12, v64
	v_fma_f32 v64, v12, v64, v12
	v_mul_f32_e32 v64, 0x3fcc422a, v64
	v_mul_f32_e32 v64, 0xbfb8aa3b, v64
	v_exp_f32_e32 v64, v64
	v_add_u32_e32 v82, 0xa0, v146
	s_waitcnt lgkmcnt(0)
	v_mov_b64_e32 v[84:85], s[56:57]
	v_mad_i64_i32 v[84:85], s[2:3], v82, s69, v[84:85]
	v_add_f32_e32 v64, 1.0, v64
	v_rcp_f32_e32 v86, v64
	v_mul_f32_e32 v64, 0x3d372713, v13
	v_mul_f32_e32 v64, v13, v64
	v_fma_f32 v64, v13, v64, v13
	v_mul_f32_e32 v64, 0x3fcc422a, v64
	v_mul_f32_e32 v64, 0xbfb8aa3b, v64
	v_exp_f32_e32 v64, v64
	v_lshl_add_u64 v[84:85], v[144:145], 1, v[84:85]
	s_and_b64 vcc, exec, s[66:67]
	v_add_f32_e32 v64, 1.0, v64
	v_rcp_f32_e32 v87, v64
	v_mul_f32_e32 v64, 0x3d372713, v14
	v_mul_f32_e32 v64, v14, v64
	v_fma_f32 v64, v14, v64, v14
	v_mul_f32_e32 v64, 0x3fcc422a, v64
	v_mul_f32_e32 v64, 0xbfb8aa3b, v64
	v_exp_f32_e32 v64, v64
	v_pk_mul_f32 v[86:87], v[12:13], v[86:87]
	v_add_f32_e32 v64, 1.0, v64
	v_rcp_f32_e32 v88, v64
	v_mul_f32_e32 v64, 0x3d372713, v15
	v_mul_f32_e32 v64, v15, v64
	v_fma_f32 v64, v15, v64, v15
	v_mul_f32_e32 v64, 0x3fcc422a, v64
	v_mul_f32_e32 v64, 0xbfb8aa3b, v64
	v_exp_f32_e32 v64, v64
	v_cvt_pk_bf16_f32 v94, v86, v87
	v_add_f32_e32 v64, 1.0, v64
	v_rcp_f32_e32 v89, v64
	v_mul_f32_e32 v64, 0x3d372713, v8
	v_mul_f32_e32 v64, v8, v64
	v_fma_f32 v64, v8, v64, v8
	v_mul_f32_e32 v64, 0x3fcc422a, v64
	v_mul_f32_e32 v64, 0xbfb8aa3b, v64
	v_exp_f32_e32 v64, v64
	v_pk_mul_f32 v[88:89], v[14:15], v[88:89]
	v_add_f32_e32 v64, 1.0, v64
	v_rcp_f32_e32 v90, v64
	v_mul_f32_e32 v64, 0x3d372713, v9
	v_mul_f32_e32 v64, v9, v64
	v_fma_f32 v64, v9, v64, v9
	v_mul_f32_e32 v64, 0x3fcc422a, v64
	v_mul_f32_e32 v64, 0xbfb8aa3b, v64
	v_exp_f32_e32 v64, v64
	v_cvt_pk_bf16_f32 v95, v88, v89
	v_add_f32_e32 v64, 1.0, v64
	v_rcp_f32_e32 v91, v64
	v_mul_f32_e32 v64, 0x3d372713, v10
	v_mul_f32_e32 v64, v10, v64
	v_fma_f32 v64, v10, v64, v10
	v_mul_f32_e32 v64, 0x3fcc422a, v64
	v_mul_f32_e32 v64, 0xbfb8aa3b, v64
	v_exp_f32_e32 v64, v64
	v_pk_mul_f32 v[90:91], v[8:9], v[90:91]
	v_add_f32_e32 v64, 1.0, v64
	v_rcp_f32_e32 v92, v64
	v_mul_f32_e32 v64, 0x3d372713, v11
	v_mul_f32_e32 v64, v11, v64
	v_fma_f32 v64, v11, v64, v11
	v_mul_f32_e32 v64, 0x3fcc422a, v64
	v_mul_f32_e32 v64, 0xbfb8aa3b, v64
	v_exp_f32_e32 v64, v64
	v_cvt_pk_bf16_f32 v96, v90, v91
	v_add_f32_e32 v64, 1.0, v64
	v_rcp_f32_e32 v93, v64
	v_mul_f32_e32 v64, 0x3d372713, v78
	v_mul_f32_e32 v64, v78, v64
	v_fma_f32 v64, v78, v64, v78
	v_mul_f32_e32 v64, 0x3fcc422a, v64
	v_mul_f32_e32 v64, 0xbfb8aa3b, v64
	v_exp_f32_e32 v64, v64
	v_pk_mul_f32 v[92:93], v[10:11], v[92:93]
	v_add_f32_e32 v64, 1.0, v64
	v_cvt_pk_bf16_f32 v97, v92, v93
	v_mov_b32_e32 v240, v94
	v_mov_b32_e32 v241, v95
	v_mov_b32_e32 v242, v96
	v_mov_b32_e32 v243, v97
	s_nop 1
	v_rcp_f32_e32 v94, v64
	v_mul_f32_e32 v64, 0x3d372713, v79
	v_mul_f32_e32 v64, v79, v64
	v_fma_f32 v64, v79, v64, v79
	v_mul_f32_e32 v64, 0x3fcc422a, v64
	v_mul_f32_e32 v64, 0xbfb8aa3b, v64
	v_exp_f32_e32 v64, v64
	s_nop 0
	v_add_f32_e32 v64, 1.0, v64
	v_rcp_f32_e32 v95, v64
	v_mul_f32_e32 v64, 0x3d372713, v80
	v_mul_f32_e32 v64, v80, v64
	v_fma_f32 v64, v80, v64, v80
	v_mul_f32_e32 v64, 0x3fcc422a, v64
	v_mul_f32_e32 v64, 0xbfb8aa3b, v64
	v_exp_f32_e32 v64, v64
	v_pk_mul_f32 v[78:79], v[78:79], v[94:95]
	v_add_f32_e32 v64, 1.0, v64
	v_rcp_f32_e32 v94, v64
	v_mul_f32_e32 v64, 0x3d372713, v81
	v_mul_f32_e32 v64, v81, v64
	v_fma_f32 v64, v81, v64, v81
	v_mul_f32_e32 v64, 0x3fcc422a, v64
	v_mul_f32_e32 v64, 0xbfb8aa3b, v64
	v_exp_f32_e32 v64, v64
	s_nop 0
	v_add_f32_e32 v64, 1.0, v64
	v_rcp_f32_e32 v95, v64
	v_mul_f32_e32 v64, 0x3d372713, v74
	v_mul_f32_e32 v64, v74, v64
	v_fma_f32 v64, v74, v64, v74
	v_mul_f32_e32 v64, 0x3fcc422a, v64
	v_mul_f32_e32 v64, 0xbfb8aa3b, v64
	v_exp_f32_e32 v64, v64
	v_pk_mul_f32 v[80:81], v[80:81], v[94:95]
	v_add_f32_e32 v64, 1.0, v64
	v_rcp_f32_e32 v94, v64
	v_mul_f32_e32 v64, 0x3d372713, v75
	v_mul_f32_e32 v64, v75, v64
	v_fma_f32 v64, v75, v64, v75
	v_mul_f32_e32 v64, 0x3fcc422a, v64
	v_mul_f32_e32 v64, 0xbfb8aa3b, v64
	v_exp_f32_e32 v64, v64
	s_nop 0
	v_add_f32_e32 v64, 1.0, v64
	v_rcp_f32_e32 v95, v64
	v_mul_f32_e32 v64, 0x3d372713, v76
	v_mul_f32_e32 v64, v76, v64
	v_fma_f32 v64, v76, v64, v76
	v_mul_f32_e32 v64, 0x3fcc422a, v64
	v_mul_f32_e32 v64, 0xbfb8aa3b, v64
	v_exp_f32_e32 v64, v64
	v_pk_mul_f32 v[74:75], v[74:75], v[94:95]
	v_add_f32_e32 v64, 1.0, v64
	v_rcp_f32_e32 v94, v64
	v_mul_f32_e32 v64, 0x3d372713, v77
	v_mul_f32_e32 v64, v77, v64
	v_fma_f32 v64, v77, v64, v77
	v_mul_f32_e32 v64, 0x3fcc422a, v64
	v_mul_f32_e32 v64, 0xbfb8aa3b, v64
	v_exp_f32_e32 v64, v64
	v_cvt_pk_bf16_f32 v96, v74, v75
	v_add_f32_e32 v64, 1.0, v64
	v_rcp_f32_e32 v95, v64
	s_nop 0
	v_pk_mul_f32 v[76:77], v[76:77], v[94:95]
	v_cvt_pk_bf16_f32 v94, v78, v79
	v_cvt_pk_bf16_f32 v95, v80, v81
	v_cvt_pk_bf16_f32 v97, v76, v77
	s_nop 1
	v_mov_b32_dpp v244, v94 quad_perm:[1,0,3,2] row_mask:0xf bank_mask:0xf
	v_mov_b32_dpp v245, v240 quad_perm:[1,0,3,2] row_mask:0xf bank_mask:0xf
	v_cndmask_b32_e64 v240, v240, v244, s[98:99]
	v_cndmask_b32_e64 v94, v245, v94, s[98:99]
	v_mov_b32_dpp v244, v95 quad_perm:[1,0,3,2] row_mask:0xf bank_mask:0xf
	v_mov_b32_dpp v245, v241 quad_perm:[1,0,3,2] row_mask:0xf bank_mask:0xf
	v_cndmask_b32_e64 v241, v241, v244, s[98:99]
	v_cndmask_b32_e64 v95, v245, v95, s[98:99]
	v_mov_b32_dpp v244, v96 quad_perm:[1,0,3,2] row_mask:0xf bank_mask:0xf
	v_mov_b32_dpp v245, v242 quad_perm:[1,0,3,2] row_mask:0xf bank_mask:0xf
	v_cndmask_b32_e64 v242, v242, v244, s[98:99]
	v_cndmask_b32_e64 v96, v245, v96, s[98:99]
	v_mov_b32_dpp v244, v97 quad_perm:[1,0,3,2] row_mask:0xf bank_mask:0xf
	v_mov_b32_dpp v245, v243 quad_perm:[1,0,3,2] row_mask:0xf bank_mask:0xf
	v_cndmask_b32_e64 v243, v243, v244, s[98:99]
	v_cndmask_b32_e64 v97, v245, v97, s[98:99]
	v_lshl_add_u64 v[246:247], v[84:85], 0, s[100:101]
	global_store_dwordx4 v[84:85], v[240:243], off nt
	global_store_dwordx4 v[246:247], v[94:97], off nt
	s_cbranch_vccnz .LBB0_374
	s_nop 0
	v_mov_b32_e32 v94, v65
	v_mov_b32_e32 v95, v87
	v_pk_mul_f32 v[84:85], v[86:87], v[86:87]
	v_pk_add_f32 v[94:95], v[86:87], v[94:95]
	v_pk_mul_f32 v[96:97], v[88:89], v[88:89]
	v_mov_b32_e32 v95, v85
	v_pk_mov_b32 v[84:85], v[86:87], v[84:85] op_sel:[1,0]
	v_mov_b32_e32 v86, v88
	v_pk_add_f32 v[84:85], v[84:85], v[94:95]
	v_mov_b32_e32 v87, v96
	v_pk_mul_f32 v[98:99], v[90:91], v[90:91]
	v_pk_add_f32 v[84:85], v[86:87], v[84:85]
	v_mov_b32_e32 v96, v89
	v_pk_add_f32 v[84:85], v[96:97], v[84:85]
	v_mov_b32_e32 v86, v90
	v_mov_b32_e32 v87, v98
	v_pk_mul_f32 v[100:101], v[92:93], v[92:93]
	v_pk_add_f32 v[84:85], v[86:87], v[84:85]
	v_mov_b32_e32 v98, v91
	v_pk_add_f32 v[84:85], v[98:99], v[84:85]
	v_mov_b32_e32 v86, v92
	v_mov_b32_e32 v87, v100
	v_pk_mul_f32 v[102:103], v[78:79], v[78:79]
	v_pk_add_f32 v[84:85], v[86:87], v[84:85]
	v_mov_b32_e32 v100, v93
	v_pk_add_f32 v[84:85], v[100:101], v[84:85]
	v_mov_b32_e32 v86, v78
	v_mov_b32_e32 v87, v102
	v_pk_mul_f32 v[104:105], v[80:81], v[80:81]
	v_pk_add_f32 v[84:85], v[84:85], v[86:87]
	v_mov_b32_e32 v102, v79
	v_pk_add_f32 v[78:79], v[102:103], v[84:85]
	v_mov_b32_e32 v84, v80
	v_mov_b32_e32 v85, v104
	v_pk_mul_f32 v[106:107], v[74:75], v[74:75]
	v_pk_add_f32 v[78:79], v[84:85], v[78:79]
	v_mov_b32_e32 v104, v81
	v_pk_add_f32 v[78:79], v[104:105], v[78:79]
	v_mov_b32_e32 v80, v74
	v_mov_b32_e32 v81, v106
	v_pk_mul_f32 v[108:109], v[76:77], v[76:77]
	v_pk_add_f32 v[78:79], v[80:81], v[78:79]
	v_mov_b32_e32 v106, v75
	v_pk_add_f32 v[74:75], v[106:107], v[78:79]
	v_mov_b32_e32 v78, v76
	v_mov_b32_e32 v79, v108
	v_pk_add_f32 v[74:75], v[78:79], v[74:75]
	v_mov_b32_e32 v108, v77
	v_pk_add_f32 v[74:75], v[108:109], v[74:75]
	ds_bpermute_b32 v76, v166, v74
	ds_bpermute_b32 v77, v166, v75
	s_waitcnt lgkmcnt(0)
	v_pk_add_f32 v[74:75], v[74:75], v[76:77]
	ds_bpermute_b32 v76, v167, v74
	ds_bpermute_b32 v77, v167, v75
	s_and_saveexec_b64 s[16:17], s[76:77]
	s_cbranch_execz .LBB0_373
	v_ashrrev_i32_e32 v83, 31, v82
	s_lshl_b32 s0, s52, 2
	s_waitcnt lgkmcnt(0)
	v_pk_add_f32 v[74:75], v[74:75], v[76:77]
	v_lshlrev_b64 v[76:77], 5, v[82:83]
	v_and_b32_e32 v248, 1, v190
	v_lshl_or_b32 v76, v248, 5, v76
	s_sub_i32 s0, s0, 32
	v_lshl_add_u64 v[76:77], v[76:77], 0, s[0:1]
	v_or_b32_e32 v76, s63, v76
	v_lshl_add_u64 v[76:77], v[76:77], 3, s[72:73]
	global_store_dwordx2 v[76:77], v[74:75], off

.LBB0_374:
	v_mul_f32_e32 v64, 0x3d372713, v4
	v_mul_f32_e32 v64, v4, v64
	v_fma_f32 v64, v4, v64, v4
	v_mul_f32_e32 v64, 0x3fcc422a, v64
	v_mul_f32_e32 v64, 0xbfb8aa3b, v64
	v_exp_f32_e32 v64, v64
	v_add_u32_e32 v74, 0xb0, v146
	s_waitcnt lgkmcnt(0)
	v_mov_b64_e32 v[76:77], s[56:57]
	v_mad_i64_i32 v[76:77], s[2:3], v74, s69, v[76:77]
	v_add_f32_e32 v64, 1.0, v64
	v_rcp_f32_e32 v78, v64
	v_mul_f32_e32 v64, 0x3d372713, v5
	v_mul_f32_e32 v64, v5, v64
	v_fma_f32 v64, v5, v64, v5
	v_mul_f32_e32 v64, 0x3fcc422a, v64
	v_mul_f32_e32 v64, 0xbfb8aa3b, v64
	v_exp_f32_e32 v64, v64
	v_lshl_add_u64 v[76:77], v[144:145], 1, v[76:77]
	s_and_b64 vcc, exec, s[66:67]
	v_add_f32_e32 v64, 1.0, v64
	v_rcp_f32_e32 v79, v64
	v_mul_f32_e32 v64, 0x3d372713, v6
	v_mul_f32_e32 v64, v6, v64
	v_fma_f32 v64, v6, v64, v6
	v_mul_f32_e32 v64, 0x3fcc422a, v64
	v_mul_f32_e32 v64, 0xbfb8aa3b, v64
	v_exp_f32_e32 v64, v64
	v_pk_mul_f32 v[78:79], v[4:5], v[78:79]
	v_add_f32_e32 v64, 1.0, v64
	v_rcp_f32_e32 v80, v64
	v_mul_f32_e32 v64, 0x3d372713, v7
	v_mul_f32_e32 v64, v7, v64
	v_fma_f32 v64, v7, v64, v7
	v_mul_f32_e32 v64, 0x3fcc422a, v64
	v_mul_f32_e32 v64, 0xbfb8aa3b, v64
	v_exp_f32_e32 v64, v64
	v_cvt_pk_bf16_f32 v86, v78, v79
	v_add_f32_e32 v64, 1.0, v64
	v_rcp_f32_e32 v81, v64
	v_mul_f32_e32 v64, 0x3d372713, v0
	v_mul_f32_e32 v64, v0, v64
	v_fma_f32 v64, v0, v64, v0
	v_mul_f32_e32 v64, 0x3fcc422a, v64
	v_mul_f32_e32 v64, 0xbfb8aa3b, v64
	v_exp_f32_e32 v64, v64
	v_pk_mul_f32 v[80:81], v[6:7], v[80:81]
	v_add_f32_e32 v64, 1.0, v64
	v_rcp_f32_e32 v82, v64
	v_mul_f32_e32 v64, 0x3d372713, v1
	v_mul_f32_e32 v64, v1, v64
	v_fma_f32 v64, v1, v64, v1
	v_mul_f32_e32 v64, 0x3fcc422a, v64
	v_mul_f32_e32 v64, 0xbfb8aa3b, v64
	v_exp_f32_e32 v64, v64
	v_cvt_pk_bf16_f32 v87, v80, v81
	v_add_f32_e32 v64, 1.0, v64
	v_rcp_f32_e32 v83, v64
	v_mul_f32_e32 v64, 0x3d372713, v2
	v_mul_f32_e32 v64, v2, v64
	v_fma_f32 v64, v2, v64, v2
	v_mul_f32_e32 v64, 0x3fcc422a, v64
	v_mul_f32_e32 v64, 0xbfb8aa3b, v64
	v_exp_f32_e32 v64, v64
	v_pk_mul_f32 v[82:83], v[0:1], v[82:83]
	v_add_f32_e32 v64, 1.0, v64
	v_rcp_f32_e32 v84, v64
	v_mul_f32_e32 v64, 0x3d372713, v3
	v_mul_f32_e32 v64, v3, v64
	v_fma_f32 v64, v3, v64, v3
	v_mul_f32_e32 v64, 0x3fcc422a, v64
	v_mul_f32_e32 v64, 0xbfb8aa3b, v64
	v_exp_f32_e32 v64, v64
	v_cvt_pk_bf16_f32 v88, v82, v83
	v_add_f32_e32 v64, 1.0, v64
	v_rcp_f32_e32 v85, v64
	v_mul_f32_e32 v64, 0x3d372713, v70
	v_mul_f32_e32 v64, v70, v64
	v_fma_f32 v64, v70, v64, v70
	v_mul_f32_e32 v64, 0x3fcc422a, v64
	v_mul_f32_e32 v64, 0xbfb8aa3b, v64
	v_exp_f32_e32 v64, v64
	v_pk_mul_f32 v[84:85], v[2:3], v[84:85]
	v_add_f32_e32 v64, 1.0, v64
	v_cvt_pk_bf16_f32 v89, v84, v85
	v_mov_b32_e32 v240, v86
	v_mov_b32_e32 v241, v87
	v_mov_b32_e32 v242, v88
	v_mov_b32_e32 v243, v89
	s_nop 1
	v_rcp_f32_e32 v86, v64
	v_mul_f32_e32 v64, 0x3d372713, v71
	v_mul_f32_e32 v64, v71, v64
	v_fma_f32 v64, v71, v64, v71
	v_mul_f32_e32 v64, 0x3fcc422a, v64
	v_mul_f32_e32 v64, 0xbfb8aa3b, v64
	v_exp_f32_e32 v64, v64
	s_nop 0
	v_add_f32_e32 v64, 1.0, v64
	v_rcp_f32_e32 v87, v64
	v_mul_f32_e32 v64, 0x3d372713, v72
	v_mul_f32_e32 v64, v72, v64
	v_fma_f32 v64, v72, v64, v72
	v_mul_f32_e32 v64, 0x3fcc422a, v64
	v_mul_f32_e32 v64, 0xbfb8aa3b, v64
	v_exp_f32_e32 v64, v64
	v_pk_mul_f32 v[70:71], v[70:71], v[86:87]
	v_add_f32_e32 v64, 1.0, v64
	v_rcp_f32_e32 v86, v64
	v_mul_f32_e32 v64, 0x3d372713, v73
	v_mul_f32_e32 v64, v73, v64
	v_fma_f32 v64, v73, v64, v73
	v_mul_f32_e32 v64, 0x3fcc422a, v64
	v_mul_f32_e32 v64, 0xbfb8aa3b, v64
	v_exp_f32_e32 v64, v64
	s_nop 0
	v_add_f32_e32 v64, 1.0, v64
	v_rcp_f32_e32 v87, v64
	v_mul_f32_e32 v64, 0x3d372713, v66
	v_mul_f32_e32 v64, v66, v64
	v_fma_f32 v64, v66, v64, v66
	v_mul_f32_e32 v64, 0x3fcc422a, v64
	v_mul_f32_e32 v64, 0xbfb8aa3b, v64
	v_exp_f32_e32 v64, v64
	v_pk_mul_f32 v[72:73], v[72:73], v[86:87]
	v_add_f32_e32 v64, 1.0, v64
	v_rcp_f32_e32 v86, v64
	v_mul_f32_e32 v64, 0x3d372713, v67
	v_mul_f32_e32 v64, v67, v64
	v_fma_f32 v64, v67, v64, v67
	v_mul_f32_e32 v64, 0x3fcc422a, v64
	v_mul_f32_e32 v64, 0xbfb8aa3b, v64
	v_exp_f32_e32 v64, v64
	s_nop 0
	v_add_f32_e32 v64, 1.0, v64
	v_rcp_f32_e32 v87, v64
	v_mul_f32_e32 v64, 0x3d372713, v68
	v_mul_f32_e32 v64, v68, v64
	v_fma_f32 v64, v68, v64, v68
	v_mul_f32_e32 v64, 0x3fcc422a, v64
	v_mul_f32_e32 v64, 0xbfb8aa3b, v64
	v_exp_f32_e32 v64, v64
	v_pk_mul_f32 v[66:67], v[66:67], v[86:87]
	v_add_f32_e32 v64, 1.0, v64
	v_rcp_f32_e32 v86, v64
	v_mul_f32_e32 v64, 0x3d372713, v69
	v_mul_f32_e32 v64, v69, v64
	v_fma_f32 v64, v69, v64, v69
	v_mul_f32_e32 v64, 0x3fcc422a, v64
	v_mul_f32_e32 v64, 0xbfb8aa3b, v64
	v_exp_f32_e32 v64, v64
	v_cvt_pk_bf16_f32 v88, v66, v67
	v_add_f32_e32 v64, 1.0, v64
	v_rcp_f32_e32 v87, v64
	s_nop 0
	v_pk_mul_f32 v[68:69], v[68:69], v[86:87]
	v_cvt_pk_bf16_f32 v86, v70, v71
	v_cvt_pk_bf16_f32 v87, v72, v73
	v_cvt_pk_bf16_f32 v89, v68, v69
	s_nop 1
	v_mov_b32_dpp v244, v86 quad_perm:[1,0,3,2] row_mask:0xf bank_mask:0xf
	v_mov_b32_dpp v245, v240 quad_perm:[1,0,3,2] row_mask:0xf bank_mask:0xf
	v_cndmask_b32_e64 v240, v240, v244, s[98:99]
	v_cndmask_b32_e64 v86, v245, v86, s[98:99]
	v_mov_b32_dpp v244, v87 quad_perm:[1,0,3,2] row_mask:0xf bank_mask:0xf
	v_mov_b32_dpp v245, v241 quad_perm:[1,0,3,2] row_mask:0xf bank_mask:0xf
	v_cndmask_b32_e64 v241, v241, v244, s[98:99]
	v_cndmask_b32_e64 v87, v245, v87, s[98:99]
	v_mov_b32_dpp v244, v88 quad_perm:[1,0,3,2] row_mask:0xf bank_mask:0xf
	v_mov_b32_dpp v245, v242 quad_perm:[1,0,3,2] row_mask:0xf bank_mask:0xf
	v_cndmask_b32_e64 v242, v242, v244, s[98:99]
	v_cndmask_b32_e64 v88, v245, v88, s[98:99]
	v_mov_b32_dpp v244, v89 quad_perm:[1,0,3,2] row_mask:0xf bank_mask:0xf
	v_mov_b32_dpp v245, v243 quad_perm:[1,0,3,2] row_mask:0xf bank_mask:0xf
	v_cndmask_b32_e64 v243, v243, v244, s[98:99]
	v_cndmask_b32_e64 v89, v245, v89, s[98:99]
	v_lshl_add_u64 v[246:247], v[76:77], 0, s[100:101]
	global_store_dwordx4 v[76:77], v[240:243], off nt
	global_store_dwordx4 v[246:247], v[86:89], off nt
	s_cbranch_vccnz .LBB0_378
	s_nop 0
	v_mov_b32_e32 v86, v65
	v_mov_b32_e32 v87, v79
	v_pk_mul_f32 v[76:77], v[78:79], v[78:79]
	v_pk_add_f32 v[86:87], v[78:79], v[86:87]
	v_pk_mul_f32 v[88:89], v[80:81], v[80:81]
	v_mov_b32_e32 v87, v77
	v_pk_mov_b32 v[76:77], v[78:79], v[76:77] op_sel:[1,0]
	v_mov_b32_e32 v78, v80
	v_pk_add_f32 v[76:77], v[76:77], v[86:87]
	v_mov_b32_e32 v79, v88
	v_pk_mul_f32 v[90:91], v[82:83], v[82:83]
	v_pk_add_f32 v[76:77], v[78:79], v[76:77]
	v_mov_b32_e32 v88, v81
	v_pk_add_f32 v[76:77], v[88:89], v[76:77]
	v_mov_b32_e32 v78, v82
	v_mov_b32_e32 v79, v90
	v_pk_mul_f32 v[92:93], v[84:85], v[84:85]
	v_pk_add_f32 v[76:77], v[78:79], v[76:77]
	v_mov_b32_e32 v90, v83
	v_pk_add_f32 v[76:77], v[90:91], v[76:77]
	v_mov_b32_e32 v78, v84
	v_mov_b32_e32 v79, v92
	v_pk_mul_f32 v[94:95], v[70:71], v[70:71]
	v_pk_add_f32 v[76:77], v[78:79], v[76:77]
	v_mov_b32_e32 v92, v85
	v_pk_add_f32 v[76:77], v[92:93], v[76:77]
	v_mov_b32_e32 v78, v70
	v_mov_b32_e32 v79, v94
	v_pk_mul_f32 v[96:97], v[72:73], v[72:73]
	v_pk_add_f32 v[76:77], v[76:77], v[78:79]
	v_mov_b32_e32 v94, v71
	v_pk_add_f32 v[70:71], v[94:95], v[76:77]
	v_mov_b32_e32 v76, v72
	v_mov_b32_e32 v77, v96
	v_pk_mul_f32 v[98:99], v[66:67], v[66:67]
	v_pk_add_f32 v[70:71], v[76:77], v[70:71]
	v_mov_b32_e32 v96, v73
	v_pk_add_f32 v[70:71], v[96:97], v[70:71]
	v_mov_b32_e32 v72, v66
	v_mov_b32_e32 v73, v98
	v_pk_mul_f32 v[100:101], v[68:69], v[68:69]
	v_pk_add_f32 v[70:71], v[72:73], v[70:71]
	v_mov_b32_e32 v98, v67
	v_pk_add_f32 v[66:67], v[98:99], v[70:71]
	v_mov_b32_e32 v70, v68
	v_mov_b32_e32 v71, v100
	v_pk_add_f32 v[66:67], v[70:71], v[66:67]
	v_mov_b32_e32 v100, v69
	v_pk_add_f32 v[66:67], v[100:101], v[66:67]
	ds_bpermute_b32 v68, v166, v66
	ds_bpermute_b32 v69, v166, v67
	s_waitcnt lgkmcnt(0)
	v_pk_add_f32 v[66:67], v[66:67], v[68:69]
	ds_bpermute_b32 v68, v167, v66
	ds_bpermute_b32 v69, v167, v67
	s_and_saveexec_b64 s[16:17], s[76:77]
	s_cbranch_execz .LBB0_377
	v_ashrrev_i32_e32 v75, 31, v74
	s_lshl_b32 s0, s52, 2
	s_waitcnt lgkmcnt(0)
	v_pk_add_f32 v[66:67], v[66:67], v[68:69]
	v_lshlrev_b64 v[68:69], 5, v[74:75]
	v_and_b32_e32 v248, 1, v190
	v_lshl_or_b32 v68, v248, 5, v68
	s_sub_i32 s0, s0, 32
	v_lshl_add_u64 v[68:69], v[68:69], 0, s[0:1]
	v_or_b32_e32 v68, s63, v68
	v_lshl_add_u64 v[68:69], v[68:69], 3, s[72:73]
	global_store_dwordx2 v[68:69], v[66:67], off
